# fastdiv (IEEE div -> rcp*mul in f32 silu/sigmoid), conv_job loads issued together, flat->global
# speedup vs baseline: 1.0206x; 1.0206x over previous
.LBB0_7:
	v_and_b32_e32 v6, 0x3ff, v3
	v_lshlrev_b32_e32 v6, 2, v6
	s_waitcnt lgkmcnt(0)
	v_lshl_add_u64 v[8:9], s[22:23], 0, v[6:7]
	v_cmp_gt_i32_e32 vcc, s14, v3
	s_nop 1
	v_cndmask_b32_e32 v9, v9, v5, vcc
	v_cndmask_b32_e32 v8, v8, v4, vcc
	global_load_dword v6, v[8:9], off
	v_add_u32_e32 v8, 0x200, v3
	v_cmp_lt_i32_e32 vcc, s15, v3
	v_mov_b32_e32 v3, v8
	s_or_b64 s[6:7], vcc, s[6:7]
	v_lshl_add_u64 v[4:5], v[4:5], 0, s[8:9]
	s_waitcnt vmcnt(0)
	v_mul_f32_e32 v8, 0xbfb8aa3b, v6
	v_exp_f32_e32 v8, v8
	s_nop 0
	v_add_f32_e32 v8, 1.0, v8
	s_nop 0
	v_rcp_f32_e32 v10, v8
	s_nop 0
	s_load_dwordx16 s[16:31], s[0:1], 0x0
	s_nop 6
	v_mul_f32_e32 v6, v6, v10
	ds_write_b32 v1, v6
	v_add_u32_e32 v1, 0x800, v1
	s_andn2_b64 exec, exec, s[6:7]
	s_cbranch_execnz .LBB0_7

.LBB0_31:
	v_lshl_add_u64 v[6:7], s[26:27], 0, v[4:5]
	global_load_dword v8, v[6:7], off
	global_load_dword v9, v[6:7], off offset:2048
	v_add_co_u32_e32 v6, vcc, 0x1000, v6
	v_add_u32_e32 v3, s2, v3
	s_nop 0
	v_addc_co_u32_e32 v7, vcc, 0, v7, vcc
	global_load_dword v12, v[6:7], off
	v_cmp_lt_i32_e32 vcc, s19, v3
	s_or_b64 s[14:15], vcc, s[14:15]
	v_lshl_add_u64 v[6:7], s[90:91], 0, v[4:5]
	v_lshl_add_u64 v[4:5], v[4:5], 0, s[8:9]
	s_waitcnt vmcnt(0)
	v_max3_f32 v13, v8, v9, v12
	v_sub_f32_e32 v8, v8, v13
	v_sub_f32_e32 v9, v9, v13
	v_sub_f32_e32 v12, v12, v13
	v_mul_f32_e32 v13, 0x3fb8aa3b, v8
	v_mul_f32_e32 v14, 0x3fb8aa3b, v9
	v_mul_f32_e32 v15, 0x3fb8aa3b, v12
	v_fma_f32 v16, v8, s16, -v13
	v_rndne_f32_e32 v17, v13
	v_fma_f32 v18, v9, s16, -v14
	v_rndne_f32_e32 v19, v14
	v_fma_f32 v20, v12, s16, -v15
	v_rndne_f32_e32 v21, v15
	v_fmac_f32_e32 v16, 0x32a5705f, v8
	v_sub_f32_e32 v13, v13, v17
	v_fmac_f32_e32 v18, 0x32a5705f, v9
	v_sub_f32_e32 v14, v14, v19
	v_fmac_f32_e32 v20, 0x32a5705f, v12
	v_sub_f32_e32 v15, v15, v21
	v_add_f32_e32 v13, v13, v16
	v_add_f32_e32 v14, v14, v18
	v_cvt_i32_f32_e32 v17, v17
	v_cvt_i32_f32_e32 v19, v19
	v_add_f32_e32 v15, v15, v20
	v_exp_f32_e32 v13, v13
	v_exp_f32_e32 v14, v14
	v_cvt_i32_f32_e32 v21, v21
	v_exp_f32_e32 v15, v15
	v_ldexp_f32 v13, v13, v17
	v_ldexp_f32 v14, v14, v19
	v_cmp_ngt_f32_e32 vcc, s17, v9
	v_cmp_ngt_f32_e64 s[4:5], s17, v8
	v_ldexp_f32 v15, v15, v21
	v_cmp_ngt_f32_e64 s[0:1], s17, v12
	v_cndmask_b32_e64 v13, 0, v13, s[4:5]
	v_cndmask_b32_e32 v14, 0, v14, vcc
	v_cmp_nlt_f32_e32 vcc, s18, v9
	v_cmp_nlt_f32_e64 s[4:5], s18, v8
	v_cndmask_b32_e64 v9, 0, v15, s[0:1]
	v_cmp_nlt_f32_e64 s[0:1], s18, v12
	v_cndmask_b32_e64 v8, v1, v13, s[4:5]
	v_cndmask_b32_e32 v12, v1, v14, vcc
	v_cndmask_b32_e64 v9, v1, v9, s[0:1]
	v_add_f32_e32 v12, v8, v12
	v_add_f32_e32 v9, v9, v12
	s_nop 0
	v_rcp_f32_e32 v17, v9
	v_div_scale_f32 v15, s[0:1], v9, v9, v12
	v_rcp_f32_e32 v18, v15
	s_nop 3
	v_fma_f32 v20, -v15, v18, 1.0
	s_nop 0
	v_div_scale_f32 v16, s[0:1], v12, v9, v12
	v_fmac_f32_e32 v18, v20, v18
	s_nop 0
	v_mul_f32_e32 v20, v16, v18
	s_nop 0
	v_fma_f32 v22, -v15, v20, v16
	s_nop 0
	v_add_co_u32_e32 v6, vcc, 0x548000, v6
	v_fmac_f32_e32 v20, v22, v18
	s_nop 0
	v_addc_co_u32_e32 v7, vcc, 0, v7, vcc
	v_fma_f32 v14, -v15, v20, v16
	v_mul_f32_e32 v8, v8, v17
	s_mov_b64 vcc, s[0:1]
	global_store_dword v[6:7], v8, off
	v_div_fmas_f32 v8, v14, v18, v20
	v_div_fixup_f32 v8, v8, v9, v12
	global_store_dword v[6:7], v8, off offset:2048
	s_andn2_b64 exec, exec, s[14:15]
	s_cbranch_execnz .LBB0_31

.Lconv_store_0:
	ds_read2_b32 v[2:3], v13 offset1:8
	s_mulk_i32 s5, 0xea00
	v_add_u32_e32 v21, s5, v18
	s_movk_i32 s5, 0xffe0
	v_and_or_b32 v24, v21, s5, v12
	s_ashr_i32 s19, s18, 31
	v_ashrrev_i32_e32 v25, 31, v24
	v_lshl_add_u64 v[22:23], s[18:19], 1, v[0:1]
	v_lshlrev_b64 v[24:25], 11, v[24:25]
	s_waitcnt lgkmcnt(0)
	v_cvt_pk_bf16_f32 v2, v2, s0
	v_lshl_add_u64 v[24:25], v[22:23], 0, v[24:25]
	global_store_short v[24:25], v2, off
	v_add_u32_e32 v2, 16, v21
	v_and_or_b32 v2, v2, s5, v14
	v_cvt_pk_bf16_f32 v26, v3, s0
	v_ashrrev_i32_e32 v3, 31, v2
	v_lshlrev_b64 v[2:3], 11, v[2:3]
	ds_read2_b32 v[24:25], v13 offset0:16 offset1:24
	v_lshl_add_u64 v[2:3], v[22:23], 0, v[2:3]
	global_store_short v[2:3], v26, off
	v_add_u32_e32 v2, 32, v21
	v_and_or_b32 v2, v2, s5, v12
	v_ashrrev_i32_e32 v3, 31, v2
	v_lshlrev_b64 v[2:3], 11, v[2:3]
	s_waitcnt lgkmcnt(0)
	v_cvt_pk_bf16_f32 v24, v24, s0
	v_lshl_add_u64 v[2:3], v[22:23], 0, v[2:3]
	global_store_short v[2:3], v24, off
	v_add_u32_e32 v2, 48, v21
	v_and_or_b32 v2, v2, s5, v15
	v_ashrrev_i32_e32 v3, 31, v2
	v_lshlrev_b64 v[2:3], 11, v[2:3]
	v_cvt_pk_bf16_f32 v26, v25, s0
	ds_read2_b32 v[24:25], v13 offset0:32 offset1:40
	v_lshl_add_u64 v[2:3], v[22:23], 0, v[2:3]
	global_store_short v[2:3], v26, off
	v_add_u32_e32 v2, 64, v21
	v_and_or_b32 v2, v2, s5, v12
	v_ashrrev_i32_e32 v3, 31, v2
	v_lshlrev_b64 v[2:3], 11, v[2:3]
	s_waitcnt lgkmcnt(0)
	v_cvt_pk_bf16_f32 v24, v24, s0
	v_lshl_add_u64 v[2:3], v[22:23], 0, v[2:3]
	global_store_short v[2:3], v24, off
	v_add_u32_e32 v2, 0x50, v21
	v_and_or_b32 v2, v2, s5, v16
	v_ashrrev_i32_e32 v3, 31, v2
	v_lshlrev_b64 v[2:3], 11, v[2:3]
	v_cvt_pk_bf16_f32 v26, v25, s0
	ds_read2_b32 v[24:25], v13 offset0:48 offset1:56
	v_lshl_add_u64 v[2:3], v[22:23], 0, v[2:3]
	global_store_short v[2:3], v26, off
	v_add_u32_e32 v2, 0x60, v21
	v_and_or_b32 v2, v2, s5, v12
	v_ashrrev_i32_e32 v3, 31, v2
	v_lshlrev_b64 v[2:3], 11, v[2:3]
	s_waitcnt lgkmcnt(0)
	v_cvt_pk_bf16_f32 v24, v24, s0
	v_lshl_add_u64 v[2:3], v[22:23], 0, v[2:3]
	global_store_short v[2:3], v24, off
	v_add_u32_e32 v2, 0x70, v21
	v_and_or_b32 v2, v2, s5, v17
	v_ashrrev_i32_e32 v3, 31, v2
	v_readlane_b32 s6, v251, 1
	v_lshlrev_b64 v[2:3], 11, v[2:3]
	s_add_i32 s4, s4, s6
	v_readlane_b32 s5, v254, 58
	v_cvt_pk_bf16_f32 v21, v25, s0
	v_lshl_add_u64 v[2:3], v[22:23], 0, v[2:3]
	v_add_u32_e32 v18, s22, v18
	s_cmpk_lt_i32 s4, 0x2c0
	v_add_u32_e32 v19, s5, v19
	global_store_short v[2:3], v21, off
	s_waitcnt lgkmcnt(0)
	s_barrier
	v_readlane_b32 s7, v251, 2
	s_cbranch_scc0 .LBB0_289
.LBB0_281:
	s_mul_hi_i32 s5, s4, 0x2e8ba2e9
	s_lshr_b32 s6, s5, 31
	s_ashr_i32 s5, s5, 3
	s_add_i32 s5, s5, s6
	s_mul_i32 s6, s5, 0xfffff500
	v_add_u32_e32 v2, s6, v19
	v_cmp_lt_i32_e32 vcc, s23, v2
	v_ashrrev_i32_e32 v3, 31, v2
	s_lshl_b32 s18, s5, 6
	v_lshl_add_u64 v[2:3], v[2:3], 2, s[2:3]
	v_mov_b32_e32 v100, 0
	v_mov_b32_e32 v101, 0
	v_mov_b32_e32 v102, 0
	v_mov_b32_e32 v103, 0
	v_mov_b32_e32 v104, 0
	v_mov_b32_e32 v105, 0
	v_mov_b32_e32 v106, 0
	v_mov_b32_e32 v107, 0
	s_mov_b64 s[44:45], exec
	s_andn2_b64 exec, exec, vcc
	s_cbranch_execz .Lconv_merge_0
	v_add_u32_e32 v124, s18, v4
	v_mad_i64_i32 v[108:109], s[6:7], v124, s26, v[2:3]
	v_add_u32_e32 v124, s18, v5
	v_mad_i64_i32 v[110:111], s[6:7], v124, s26, v[2:3]
	v_add_u32_e32 v124, s18, v6
	v_mad_i64_i32 v[112:113], s[6:7], v124, s26, v[2:3]
	v_add_u32_e32 v124, s18, v7
	v_mad_i64_i32 v[114:115], s[6:7], v124, s26, v[2:3]
	v_add_u32_e32 v124, s18, v8
	v_mad_i64_i32 v[116:117], s[6:7], v124, s26, v[2:3]
	v_add_u32_e32 v124, s18, v9
	v_mad_i64_i32 v[118:119], s[6:7], v124, s26, v[2:3]
	v_add_u32_e32 v124, s18, v10
	v_mad_i64_i32 v[120:121], s[6:7], v124, s26, v[2:3]
	v_add_u32_e32 v124, s18, v11
	v_mad_i64_i32 v[122:123], s[6:7], v124, s26, v[2:3]
	global_load_dword v100, v[108:109], off
	global_load_dword v101, v[110:111], off
	global_load_dword v102, v[112:113], off
	global_load_dword v103, v[114:115], off
	global_load_dword v104, v[116:117], off
	global_load_dword v105, v[118:119], off
	global_load_dword v106, v[120:121], off
	global_load_dword v107, v[122:123], off
	s_waitcnt vmcnt(0)
.Lconv_merge_0:
	s_mov_b64 exec, s[44:45]
	ds_write_b32 v20, v100
	ds_write_b32 v20, v101 offset:2080
	ds_write_b32 v20, v102 offset:4160
	ds_write_b32 v20, v103 offset:6240
	ds_write_b32 v20, v104 offset:8320
	ds_write_b32 v20, v105 offset:10400
	ds_write_b32 v20, v106 offset:12480
	ds_write_b32 v20, v107 offset:14560
	s_waitcnt lgkmcnt(0)
	s_barrier
	s_branch .Lconv_store_0

.Lconv_store_1:
	s_ashr_i32 s3, s2, 31
	ds_read2_b32 v[2:3], v12 offset1:8
	s_mulk_i32 s5, 0xea00
	v_lshl_add_u64 v[22:23], s[2:3], 1, v[0:1]
	v_add_u32_e32 v21, s5, v18
	s_movk_i32 s2, 0xffe0
	v_and_or_b32 v24, v21, s2, v13
	v_ashrrev_i32_e32 v25, 31, v24
	v_lshlrev_b64 v[24:25], 11, v[24:25]
	s_waitcnt lgkmcnt(0)
	v_cvt_pk_bf16_f32 v2, v2, s0
	v_lshl_add_u64 v[24:25], v[22:23], 0, v[24:25]
	global_store_short v[24:25], v2, off
	v_add_u32_e32 v2, 16, v21
	v_and_or_b32 v2, v2, s2, v14
	v_cvt_pk_bf16_f32 v26, v3, s0
	v_ashrrev_i32_e32 v3, 31, v2
	v_lshlrev_b64 v[2:3], 11, v[2:3]
	ds_read2_b32 v[24:25], v12 offset0:16 offset1:24
	v_lshl_add_u64 v[2:3], v[22:23], 0, v[2:3]
	global_store_short v[2:3], v26, off
	v_add_u32_e32 v2, 32, v21
	v_and_or_b32 v2, v2, s2, v13
	v_ashrrev_i32_e32 v3, 31, v2
	v_lshlrev_b64 v[2:3], 11, v[2:3]
	s_waitcnt lgkmcnt(0)
	v_cvt_pk_bf16_f32 v24, v24, s0
	v_lshl_add_u64 v[2:3], v[22:23], 0, v[2:3]
	global_store_short v[2:3], v24, off
	v_add_u32_e32 v2, 48, v21
	v_and_or_b32 v2, v2, s2, v15
	v_ashrrev_i32_e32 v3, 31, v2
	v_lshlrev_b64 v[2:3], 11, v[2:3]
	v_cvt_pk_bf16_f32 v26, v25, s0
	ds_read2_b32 v[24:25], v12 offset0:32 offset1:40
	v_lshl_add_u64 v[2:3], v[22:23], 0, v[2:3]
	global_store_short v[2:3], v26, off
	v_add_u32_e32 v2, 64, v21
	v_and_or_b32 v2, v2, s2, v13
	v_ashrrev_i32_e32 v3, 31, v2
	v_lshlrev_b64 v[2:3], 11, v[2:3]
	s_waitcnt lgkmcnt(0)
	v_cvt_pk_bf16_f32 v24, v24, s0
	v_lshl_add_u64 v[2:3], v[22:23], 0, v[2:3]
	global_store_short v[2:3], v24, off
	v_add_u32_e32 v2, 0x50, v21
	v_and_or_b32 v2, v2, s2, v16
	v_ashrrev_i32_e32 v3, 31, v2
	v_lshlrev_b64 v[2:3], 11, v[2:3]
	v_cvt_pk_bf16_f32 v26, v25, s0
	ds_read2_b32 v[24:25], v12 offset0:48 offset1:56
	v_lshl_add_u64 v[2:3], v[22:23], 0, v[2:3]
	global_store_short v[2:3], v26, off
	v_add_u32_e32 v2, 0x60, v21
	v_and_or_b32 v2, v2, s2, v13
	v_ashrrev_i32_e32 v3, 31, v2
	v_lshlrev_b64 v[2:3], 11, v[2:3]
	s_waitcnt lgkmcnt(0)
	v_cvt_pk_bf16_f32 v24, v24, s0
	v_lshl_add_u64 v[2:3], v[22:23], 0, v[2:3]
	global_store_short v[2:3], v24, off
	v_add_u32_e32 v2, 0x70, v21
	v_and_or_b32 v2, v2, s2, v17
	v_ashrrev_i32_e32 v3, 31, v2
	v_readlane_b32 s2, v251, 1
	v_lshlrev_b64 v[2:3], 11, v[2:3]
	s_add_i32 s4, s4, s2
	v_readlane_b32 s2, v254, 58
	v_cvt_pk_bf16_f32 v21, v25, s0
	v_lshl_add_u64 v[2:3], v[22:23], 0, v[2:3]
	v_add_u32_e32 v18, s20, v18
	s_cmpk_lt_i32 s4, 0x2c0
	v_add_u32_e32 v19, s2, v19
	global_store_short v[2:3], v21, off
	s_waitcnt lgkmcnt(0)
	s_barrier
	v_readlane_b32 s3, v251, 2
	s_cbranch_scc0 .LBB0_300
.LBB0_292:
	s_mul_hi_i32 s2, s4, 0x2e8ba2e9
	s_lshr_b32 s3, s2, 31
	s_ashr_i32 s5, s2, 3
	s_add_i32 s5, s5, s3
	s_mul_i32 s2, s5, 0xfffff500
	v_add_u32_e32 v2, s2, v19
	v_cmp_lt_i32_e32 vcc, s21, v2
	v_ashrrev_i32_e32 v3, 31, v2
	s_lshl_b32 s2, s5, 6
	v_lshl_add_u64 v[2:3], v[2:3], 2, s[0:1]
	v_mov_b32_e32 v100, 0
	v_mov_b32_e32 v101, 0
	v_mov_b32_e32 v102, 0
	v_mov_b32_e32 v103, 0
	v_mov_b32_e32 v104, 0
	v_mov_b32_e32 v105, 0
	v_mov_b32_e32 v106, 0
	v_mov_b32_e32 v107, 0
	s_mov_b64 s[18:19], exec
	s_andn2_b64 exec, exec, vcc
	s_cbranch_execz .Lconv_merge_1
	v_add_u32_e32 v124, s2, v4
	v_mad_i64_i32 v[108:109], s[6:7], v124, s22, v[2:3]
	v_add_u32_e32 v124, s2, v5
	v_mad_i64_i32 v[110:111], s[6:7], v124, s22, v[2:3]
	v_add_u32_e32 v124, s2, v6
	v_mad_i64_i32 v[112:113], s[6:7], v124, s22, v[2:3]
	v_add_u32_e32 v124, s2, v7
	v_mad_i64_i32 v[114:115], s[6:7], v124, s22, v[2:3]
	v_add_u32_e32 v124, s2, v8
	v_mad_i64_i32 v[116:117], s[6:7], v124, s22, v[2:3]
	v_add_u32_e32 v124, s2, v9
	v_mad_i64_i32 v[118:119], s[6:7], v124, s22, v[2:3]
	v_add_u32_e32 v124, s2, v10
	v_mad_i64_i32 v[120:121], s[6:7], v124, s22, v[2:3]
	v_add_u32_e32 v124, s2, v11
	v_mad_i64_i32 v[122:123], s[6:7], v124, s22, v[2:3]
	global_load_dword v100, v[108:109], off
	global_load_dword v101, v[110:111], off
	global_load_dword v102, v[112:113], off
	global_load_dword v103, v[114:115], off
	global_load_dword v104, v[116:117], off
	global_load_dword v105, v[118:119], off
	global_load_dword v106, v[120:121], off
	global_load_dword v107, v[122:123], off
	s_waitcnt vmcnt(0)
.Lconv_merge_1:
	s_mov_b64 exec, s[18:19]
	ds_write_b32 v20, v100
	ds_write_b32 v20, v101 offset:2080
	ds_write_b32 v20, v102 offset:4160
	ds_write_b32 v20, v103 offset:6240
	ds_write_b32 v20, v104 offset:8320
	ds_write_b32 v20, v105 offset:10400
	ds_write_b32 v20, v106 offset:12480
	ds_write_b32 v20, v107 offset:14560
	s_waitcnt lgkmcnt(0)
	s_barrier
	s_branch .Lconv_store_1

.Lconv_store_2:
	ds_read2_b32 v[2:3], v13 offset1:8
	s_sub_i32 s5, 0, s5
	v_readlane_b32 s7, v255, 9
	s_ashr_i32 s3, s2, 31
	s_add_i32 s5, s5, s7
	v_lshl_add_u64 v[16:17], s[2:3], 1, v[0:1]
	v_add_u32_e32 v20, s5, v15
	s_movk_i32 s5, 0x1600
	s_waitcnt lgkmcnt(0)
	v_cvt_pk_bf16_f32 v2, v2, s0
	v_mad_i64_i32 v[18:19], s[2:3], v20, s5, v[16:17]
	global_store_short v[18:19], v2, off
	v_cvt_pk_bf16_f32 v21, v3, s0
	ds_read2_b32 v[2:3], v13 offset0:16 offset1:24
	v_add_u32_e32 v18, 8, v20
	v_mad_i64_i32 v[18:19], s[2:3], v18, s5, v[16:17]
	global_store_short v[18:19], v21, off
	v_add_u32_e32 v18, 16, v20
	s_waitcnt lgkmcnt(0)
	v_cvt_pk_bf16_f32 v2, v2, s0
	v_mad_i64_i32 v[18:19], s[2:3], v18, s5, v[16:17]
	global_store_short v[18:19], v2, off
	v_cvt_pk_bf16_f32 v21, v3, s0
	ds_read2_b32 v[2:3], v13 offset0:32 offset1:40
	v_add_u32_e32 v18, 24, v20
	v_mad_i64_i32 v[18:19], s[2:3], v18, s5, v[16:17]
	global_store_short v[18:19], v21, off
	v_add_u32_e32 v18, 32, v20
	s_waitcnt lgkmcnt(0)
	v_cvt_pk_bf16_f32 v2, v2, s0
	v_mad_i64_i32 v[18:19], s[2:3], v18, s5, v[16:17]
	global_store_short v[18:19], v2, off
	v_cvt_pk_bf16_f32 v21, v3, s0
	ds_read2_b32 v[2:3], v13 offset0:48 offset1:56
	v_add_u32_e32 v18, 40, v20
	v_mad_i64_i32 v[18:19], s[2:3], v18, s5, v[16:17]
	global_store_short v[18:19], v21, off
	v_add_u32_e32 v18, 48, v20
	s_waitcnt lgkmcnt(0)
	v_cvt_pk_bf16_f32 v2, v2, s0
	v_mad_i64_i32 v[18:19], s[2:3], v18, s5, v[16:17]
	global_store_short v[18:19], v2, off
	v_add_u32_e32 v2, 56, v20
	v_cvt_pk_bf16_f32 v18, v3, s0
	v_mad_i64_i32 v[2:3], s[2:3], v2, s5, v[16:17]
	v_readlane_b32 s2, v251, 1
	s_add_i32 s4, s4, s2
	v_readlane_b32 s2, v254, 58
	s_cmpk_lt_i32 s4, 0x2c0
	global_store_short v[2:3], v18, off
	v_add_u32_e32 v15, s2, v15
	v_add_u32_e32 v5, s2, v5
	s_waitcnt lgkmcnt(0)
	s_barrier
	v_readlane_b32 s3, v251, 2
	s_cbranch_scc0 .LBB0_311
.LBB0_303:
	s_ashr_i32 s2, s4, 31
	s_lshr_b32 s2, s2, 28
	s_add_i32 s2, s4, s2
	s_ashr_i32 s6, s2, 4
	s_lshl_b32 s5, s6, 10
	s_sub_i32 s2, s7, s5
	v_add_u32_e32 v2, s2, v5
	s_movk_i32 s2, 0x3ff
	v_cmp_lt_i32_e32 vcc, s2, v2
	v_ashrrev_i32_e32 v3, 31, v2
	s_lshl_b32 s2, s6, 6
	v_lshl_add_u64 v[2:3], v[2:3], 2, s[0:1]
	s_movk_i32 s3, 0x1000
	v_mov_b32_e32 v100, 0
	v_mov_b32_e32 v101, 0
	v_mov_b32_e32 v102, 0
	v_mov_b32_e32 v103, 0
	v_mov_b32_e32 v104, 0
	v_mov_b32_e32 v105, 0
	v_mov_b32_e32 v106, 0
	v_mov_b32_e32 v107, 0
	s_mov_b64 s[18:19], exec
	s_andn2_b64 exec, exec, vcc
	s_cbranch_execz .Lconv_merge_2
	v_add_u32_e32 v124, s2, v4
	v_mad_i64_i32 v[108:109], s[8:9], v124, s3, v[2:3]
	v_add_u32_e32 v124, s2, v6
	v_mad_i64_i32 v[110:111], s[8:9], v124, s3, v[2:3]
	v_add_u32_e32 v124, s2, v7
	v_mad_i64_i32 v[112:113], s[8:9], v124, s3, v[2:3]
	v_add_u32_e32 v124, s2, v8
	v_mad_i64_i32 v[114:115], s[8:9], v124, s3, v[2:3]
	v_add_u32_e32 v124, s2, v9
	v_mad_i64_i32 v[116:117], s[8:9], v124, s3, v[2:3]
	v_add_u32_e32 v124, s2, v10
	v_mad_i64_i32 v[118:119], s[8:9], v124, s3, v[2:3]
	v_add_u32_e32 v124, s2, v11
	v_mad_i64_i32 v[120:121], s[8:9], v124, s3, v[2:3]
	v_add_u32_e32 v124, s2, v12
	v_mad_i64_i32 v[122:123], s[8:9], v124, s3, v[2:3]
	global_load_dword v100, v[108:109], off
	global_load_dword v101, v[110:111], off
	global_load_dword v102, v[112:113], off
	global_load_dword v103, v[114:115], off
	global_load_dword v104, v[116:117], off
	global_load_dword v105, v[118:119], off
	global_load_dword v106, v[120:121], off
	global_load_dword v107, v[122:123], off
	s_waitcnt vmcnt(0)
.Lconv_merge_2:
	s_mov_b64 exec, s[18:19]
	ds_write_b32 v14, v100
	ds_write_b32 v14, v101 offset:2080
	ds_write_b32 v14, v102 offset:4160
	ds_write_b32 v14, v103 offset:6240
	ds_write_b32 v14, v104 offset:8320
	ds_write_b32 v14, v105 offset:10400
	ds_write_b32 v14, v106 offset:12480
	ds_write_b32 v14, v107 offset:14560
	s_waitcnt lgkmcnt(0)
	s_barrier
	s_branch .Lconv_store_2

.LBB0_595:
	s_mul_hi_i32 s0, s8, 0x3e0f83e1
	s_lshr_b32 s1, s0, 31
	s_ashr_i32 s0, s0, 5
	s_add_i32 s0, s0, s1
	s_mul_i32 s1, s0, 0x84
	s_sub_i32 s20, s8, s1
	s_and_b32 s19, s0, 1
	s_bfe_u32 s21, s0, 0x20001
	s_lshl_b32 s1, s20, 6
	s_cmp_lt_i32 s20, 4
	s_cselect_b32 s9, s7, s6
	v_mov_b32_e32 v16, v207
	s_add_i32 s9, s9, s1
	v_mov_b32_e32 v10, v207
	s_cmp_eq_u32 s19, 0
	s_barrier
	s_cselect_b64 s[42:43], -1, 0
	v_ashrrev_i32_e32 v4, 3, v10
	v_lshlrev_b32_e32 v0, 4, v10
	s_cmp_eq_u32 s19, 1
	v_and_b32_e32 v2, 0x70, v0
	v_add_u32_e32 v3, s9, v4
	v_mov_b64_e32 v[0:1], s[36:37]
	s_cselect_b64 s[2:3], -1, 0
	s_and_b32 s22, s0, -8
	v_mad_i64_i32 v[0:1], s[0:1], v3, s14, v[0:1]
	s_lshl_b32 s26, s21, 8
	s_lshl_b32 s18, s21, 7
	v_lshl_add_u64 v[0:1], v[0:1], 0, s[26:27]
	v_lshlrev_b32_e32 v128, 1, v2
	v_lshlrev_b32_e32 v3, 9, v4
	v_lshlrev_b32_e32 v5, 2, v2
	v_lshl_add_u64 v[0:1], v[0:1], 0, v[128:129]
	s_mov_b64 s[0:1], -1
	s_cmp_lg_u32 s22, 8
	v_add3_u32 v5, 0, v3, v5
	s_cbranch_scc0 .LBB0_613
	s_and_b64 s[0:1], s[42:43], exec
	s_cselect_b32 s26, s15, 0x1800
	v_lshl_add_u64 v[12:13], v[0:1], 0, s[26:27]
	global_load_dwordx4 v[6:9], v[12:13], off
	global_load_dwordx4 v[26:29], v[12:13], off offset:16
	v_or_b32_e32 v2, s18, v2
	v_lshlrev_b32_e32 v128, 2, v2
	v_lshl_add_u64 v[2:3], s[78:79], 0, v[128:129]
	s_waitcnt vmcnt(0) lgkmcnt(0)
	v_lshlrev_b32_e32 v11, 16, v6
	v_and_b32_e32 v25, 0xffff0000, v6
	global_load_dword v6, v[2:3], off
	v_lshlrev_b32_e32 v15, 16, v8
	v_and_b32_e32 v12, 0xffff0000, v8
	v_mul_f32_e32 v8, 0xbfb8aa3b, v11
	v_exp_f32_e32 v8, v8
	v_lshlrev_b32_e32 v20, 16, v9
	v_and_b32_e32 v17, 0xffff0000, v9
	v_lshlrev_b32_e32 v24, 16, v26
	v_add_f32_e32 v8, 1.0, v8
	v_rcp_f32_e32 v11, v8
	v_and_b32_e32 v21, 0xffff0000, v26
	v_lshlrev_b32_e32 v23, 16, v27
	v_and_b32_e32 v22, 0xffff0000, v27
	v_lshlrev_b32_e32 v19, 16, v28
	v_and_b32_e32 v18, 0xffff0000, v28
	v_mul_f32_e32 v8, 1.0, v11
	v_mul_f32_e32 v9, 0xbfb8aa3b, v25
	v_exp_f32_e32 v9, v9
	v_lshlrev_b32_e32 v30, 16, v7
	v_and_b32_e32 v31, 0xffff0000, v7
	v_lshlrev_b32_e32 v14, 16, v29
	v_add_f32_e32 v9, 1.0, v9
	v_rcp_f32_e32 v25, v9
	v_and_b32_e32 v13, 0xffff0000, v29
	v_mul_f32_e32 v15, 0xbfb8aa3b, v15
	v_exp_f32_e32 v15, v15
	v_mul_f32_e32 v9, 1.0, v25
	v_mul_f32_e32 v11, 0xbfb8aa3b, v30
	v_exp_f32_e32 v11, v11
	v_add_f32_e32 v15, 1.0, v15
	v_mul_f32_e32 v12, 0xbfb8aa3b, v12
	v_exp_f32_e32 v12, v12
	v_add_f32_e32 v11, 1.0, v11
	v_mul_f32_e32 v20, 0xbfb8aa3b, v20
	v_exp_f32_e32 v20, v20
	v_add_f32_e32 v12, 1.0, v12
	v_mul_f32_e32 v17, 0xbfb8aa3b, v17
	v_exp_f32_e32 v17, v17
	v_add_f32_e32 v20, 1.0, v20
	v_mul_f32_e32 v24, 0xbfb8aa3b, v24
	v_exp_f32_e32 v24, v24
	v_add_f32_e32 v17, 1.0, v17
	v_mul_f32_e32 v21, 0xbfb8aa3b, v21
	v_exp_f32_e32 v21, v21
	v_add_f32_e32 v24, 1.0, v24
	v_mul_f32_e32 v23, 0xbfb8aa3b, v23
	v_exp_f32_e32 v23, v23
	v_add_f32_e32 v21, 1.0, v21
	v_mul_f32_e32 v22, 0xbfb8aa3b, v22
	v_exp_f32_e32 v22, v22
	v_add_f32_e32 v23, 1.0, v23
	v_mul_f32_e32 v19, 0xbfb8aa3b, v19
	v_exp_f32_e32 v19, v19
	v_add_f32_e32 v22, 1.0, v22
	v_mul_f32_e32 v18, 0xbfb8aa3b, v18
	v_exp_f32_e32 v18, v18
	v_add_f32_e32 v19, 1.0, v19
	v_mul_f32_e32 v14, 0xbfb8aa3b, v14
	s_waitcnt vmcnt(0) lgkmcnt(0)
	v_sub_f32_e32 v7, 1.0, v6
	v_fmac_f32_e32 v6, v7, v8
	v_cmp_gt_f32_e32 vcc, s12, v6
	v_add_f32_e32 v18, 1.0, v18
	v_exp_f32_e32 v14, v14
	v_cndmask_b32_e64 v7, 0, 32, vcc
	v_ldexp_f32 v7, v6, v7
	v_log_f32_e32 v7, v7
	v_add_f32_e32 v14, 1.0, v14
	v_mul_f32_e32 v13, 0xbfb8aa3b, v13
	v_exp_f32_e32 v13, v13
	v_mul_f32_e32 v8, 0x3f317217, v7
	v_fma_f32 v8, v7, s86, -v8
	v_fmac_f32_e32 v8, 0x3377d1cf, v7
	v_fmac_f32_e32 v8, 0x3f317217, v7
	v_cmp_lt_f32_e64 s[0:1], |v7|, s87
	v_add_f32_e32 v13, 1.0, v13
	s_nop 0
	v_cndmask_b32_e64 v7, v7, v8, s[0:1]
	v_cndmask_b32_e32 v8, 0, v231, vcc
	v_sub_f32_e32 v7, v7, v8
	ds_write_b32 v5, v7
	global_load_dword v7, v[2:3], off offset:4
	s_waitcnt vmcnt(0) lgkmcnt(0)
	v_sub_f32_e32 v8, 1.0, v7
	v_fmac_f32_e32 v7, v8, v9
	v_cmp_gt_f32_e32 vcc, s12, v7
	s_nop 1
	v_cndmask_b32_e64 v8, 0, 32, vcc
	v_ldexp_f32 v8, v7, v8
	v_log_f32_e32 v8, v8
	s_nop 0
	v_mul_f32_e32 v9, 0x3f317217, v8
	v_fma_f32 v9, v8, s86, -v9
	v_fmac_f32_e32 v9, 0x3377d1cf, v8
	v_fmac_f32_e32 v9, 0x3f317217, v8
	v_cmp_lt_f32_e64 s[0:1], |v8|, s87
	s_nop 1
	v_cndmask_b32_e64 v8, v8, v9, s[0:1]
	v_cndmask_b32_e32 v9, 0, v231, vcc
	v_sub_f32_e32 v8, v8, v9
	ds_write_b32 v5, v8 offset:4
	global_load_dword v8, v[2:3], off offset:8
	v_rcp_f32_e32 v26, v11
	s_waitcnt vmcnt(0) lgkmcnt(0)
	v_sub_f32_e32 v9, 1.0, v8
	v_mul_f32_e32 v11, 1.0, v26
	v_mul_f32_e32 v25, 0xbfb8aa3b, v31
	v_exp_f32_e32 v25, v25
	v_fmac_f32_e32 v8, v11, v9
	v_add_f32_e32 v25, 1.0, v25
	v_rcp_f32_e32 v27, v25
	s_nop 0
	v_cmp_gt_f32_e32 vcc, s12, v8
	v_mul_f32_e32 v25, 1.0, v27
	s_nop 0
	v_cndmask_b32_e64 v9, 0, 32, vcc
	v_ldexp_f32 v9, v8, v9
	v_log_f32_e32 v9, v9
	s_nop 0
	v_mul_f32_e32 v11, 0x3f317217, v9
	v_fma_f32 v11, v9, s86, -v11
	v_fmac_f32_e32 v11, 0x3377d1cf, v9
	v_fmac_f32_e32 v11, 0x3f317217, v9
	v_cmp_lt_f32_e64 s[0:1], |v9|, s87
	s_nop 1
	v_cndmask_b32_e64 v9, v9, v11, s[0:1]
	v_cndmask_b32_e32 v11, 0, v231, vcc
	v_sub_f32_e32 v9, v9, v11
	ds_write_b32 v5, v9 offset:8
	global_load_dword v9, v[2:3], off offset:12
	s_waitcnt vmcnt(0) lgkmcnt(0)
	v_sub_f32_e32 v11, 1.0, v9
	v_fmac_f32_e32 v9, v25, v11
	v_cmp_gt_f32_e32 vcc, s12, v9
	s_nop 1
	v_cndmask_b32_e64 v11, 0, 32, vcc
	v_ldexp_f32 v11, v9, v11
	v_log_f32_e32 v11, v11
	s_nop 0
	v_mul_f32_e32 v25, 0x3f317217, v11
	v_fma_f32 v25, v11, s86, -v25
	v_fmac_f32_e32 v25, 0x3377d1cf, v11
	v_fmac_f32_e32 v25, 0x3f317217, v11
	v_cmp_lt_f32_e64 s[0:1], |v11|, s87
	s_nop 1
	v_cndmask_b32_e64 v11, v11, v25, s[0:1]
	v_cndmask_b32_e32 v25, 0, v231, vcc
	v_sub_f32_e32 v11, v11, v25
	ds_write_b32 v5, v11 offset:12
	global_load_dword v11, v[2:3], off offset:16
	v_rcp_f32_e32 v27, v15
	s_waitcnt vmcnt(0) lgkmcnt(0)
	v_sub_f32_e32 v25, 1.0, v11
	v_mul_f32_e32 v15, 1.0, v27
	v_rcp_f32_e32 v27, v12
	v_fmac_f32_e32 v11, v15, v25
	v_cmp_gt_f32_e32 vcc, s12, v11
	v_mul_f32_e32 v26, 1.0, v27
	s_nop 0
	v_cndmask_b32_e64 v12, 0, 32, vcc
	v_ldexp_f32 v12, v11, v12
	v_log_f32_e32 v12, v12
	s_nop 0
	v_mul_f32_e32 v15, 0x3f317217, v12
	v_fma_f32 v15, v12, s86, -v15
	v_fmac_f32_e32 v15, 0x3377d1cf, v12
	v_fmac_f32_e32 v15, 0x3f317217, v12
	v_cmp_lt_f32_e64 s[0:1], |v12|, s87
	s_nop 1
	v_cndmask_b32_e64 v12, v12, v15, s[0:1]
	v_cndmask_b32_e32 v15, 0, v231, vcc
	v_sub_f32_e32 v12, v12, v15
	ds_write_b32 v5, v12 offset:16
	global_load_dword v12, v[2:3], off offset:20
	s_waitcnt vmcnt(0) lgkmcnt(0)
	v_sub_f32_e32 v15, 1.0, v12
	v_fmac_f32_e32 v12, v26, v15
	v_cmp_gt_f32_e32 vcc, s12, v12
	s_nop 1
	v_cndmask_b32_e64 v15, 0, 32, vcc
	v_ldexp_f32 v15, v12, v15
	v_log_f32_e32 v15, v15
	s_nop 0
	v_mul_f32_e32 v25, 0x3f317217, v15
	v_fma_f32 v25, v15, s86, -v25
	v_fmac_f32_e32 v25, 0x3377d1cf, v15
	v_fmac_f32_e32 v25, 0x3f317217, v15
	v_cmp_lt_f32_e64 s[0:1], |v15|, s87
	s_nop 1
	v_cndmask_b32_e64 v15, v15, v25, s[0:1]
	v_cndmask_b32_e32 v25, 0, v231, vcc
	v_sub_f32_e32 v15, v15, v25
	ds_write_b32 v5, v15 offset:20
	global_load_dword v15, v[2:3], off offset:24
	v_rcp_f32_e32 v27, v20
	s_waitcnt vmcnt(0) lgkmcnt(0)
	v_sub_f32_e32 v25, 1.0, v15
	v_mul_f32_e32 v20, 1.0, v27
	v_rcp_f32_e32 v27, v17
	v_fmac_f32_e32 v15, v20, v25
	v_cmp_gt_f32_e32 vcc, s12, v15
	v_mul_f32_e32 v26, 1.0, v27
	s_nop 0
	v_cndmask_b32_e64 v17, 0, 32, vcc
	v_ldexp_f32 v17, v15, v17
	v_log_f32_e32 v17, v17
	s_nop 0
	v_mul_f32_e32 v20, 0x3f317217, v17
	v_fma_f32 v20, v17, s86, -v20
	v_fmac_f32_e32 v20, 0x3377d1cf, v17
	v_fmac_f32_e32 v20, 0x3f317217, v17
	v_cmp_lt_f32_e64 s[0:1], |v17|, s87
	s_nop 1
	v_cndmask_b32_e64 v17, v17, v20, s[0:1]
	v_cndmask_b32_e32 v20, 0, v231, vcc
	v_sub_f32_e32 v17, v17, v20
	ds_write_b32 v5, v17 offset:24
	global_load_dword v17, v[2:3], off offset:28
	s_waitcnt vmcnt(0) lgkmcnt(0)
	v_sub_f32_e32 v20, 1.0, v17
	v_fmac_f32_e32 v17, v26, v20
	v_cmp_gt_f32_e32 vcc, s12, v17
	s_nop 1
	v_cndmask_b32_e64 v20, 0, 32, vcc
	v_ldexp_f32 v20, v17, v20
	v_log_f32_e32 v20, v20
	s_nop 0
	v_mul_f32_e32 v25, 0x3f317217, v20
	v_fma_f32 v25, v20, s86, -v25
	v_fmac_f32_e32 v25, 0x3377d1cf, v20
	v_fmac_f32_e32 v25, 0x3f317217, v20
	v_cmp_lt_f32_e64 s[0:1], |v20|, s87
	s_nop 1
	v_cndmask_b32_e64 v20, v20, v25, s[0:1]
	v_cndmask_b32_e32 v25, 0, v231, vcc
	v_sub_f32_e32 v20, v20, v25
	ds_write_b32 v5, v20 offset:28
	global_load_dword v20, v[2:3], off offset:32
	v_rcp_f32_e32 v27, v24
	s_waitcnt vmcnt(0) lgkmcnt(0)
	v_sub_f32_e32 v25, 1.0, v20
	v_mul_f32_e32 v24, 1.0, v27
	v_rcp_f32_e32 v27, v21
	v_fmac_f32_e32 v20, v24, v25
	v_cmp_gt_f32_e32 vcc, s12, v20
	v_mul_f32_e32 v26, 1.0, v27
	s_nop 0
	v_cndmask_b32_e64 v21, 0, 32, vcc
	v_ldexp_f32 v21, v20, v21
	v_log_f32_e32 v21, v21
	s_nop 0
	v_mul_f32_e32 v24, 0x3f317217, v21
	v_fma_f32 v24, v21, s86, -v24
	v_fmac_f32_e32 v24, 0x3377d1cf, v21
	v_fmac_f32_e32 v24, 0x3f317217, v21
	v_cmp_lt_f32_e64 s[0:1], |v21|, s87
	s_nop 1
	v_cndmask_b32_e64 v21, v21, v24, s[0:1]
	v_cndmask_b32_e32 v24, 0, v231, vcc
	v_sub_f32_e32 v21, v21, v24
	ds_write_b32 v5, v21 offset:32
	global_load_dword v21, v[2:3], off offset:36
	s_waitcnt vmcnt(0) lgkmcnt(0)
	v_sub_f32_e32 v24, 1.0, v21
	v_fmac_f32_e32 v21, v26, v24
	v_cmp_gt_f32_e32 vcc, s12, v21
	s_nop 1
	v_cndmask_b32_e64 v24, 0, 32, vcc
	v_ldexp_f32 v24, v21, v24
	v_log_f32_e32 v24, v24
	s_nop 0
	v_mul_f32_e32 v25, 0x3f317217, v24
	v_fma_f32 v25, v24, s86, -v25
	v_fmac_f32_e32 v25, 0x3377d1cf, v24
	v_fmac_f32_e32 v25, 0x3f317217, v24
	v_cmp_lt_f32_e64 s[0:1], |v24|, s87
	s_nop 1
	v_cndmask_b32_e64 v24, v24, v25, s[0:1]
	v_cndmask_b32_e32 v25, 0, v231, vcc
	v_sub_f32_e32 v24, v24, v25
	ds_write_b32 v5, v24 offset:36
	global_load_dword v24, v[2:3], off offset:40
	v_rcp_f32_e32 v27, v23
	s_waitcnt vmcnt(0) lgkmcnt(0)
	v_sub_f32_e32 v25, 1.0, v24
	v_mul_f32_e32 v23, 1.0, v27
	v_rcp_f32_e32 v27, v22
	v_fmac_f32_e32 v24, v23, v25
	v_cmp_gt_f32_e32 vcc, s12, v24
	v_mul_f32_e32 v26, 1.0, v27
	s_nop 0
	v_cndmask_b32_e64 v22, 0, 32, vcc
	v_ldexp_f32 v22, v24, v22
	v_log_f32_e32 v22, v22
	s_nop 0
	v_mul_f32_e32 v23, 0x3f317217, v22
	v_fma_f32 v23, v22, s86, -v23
	v_fmac_f32_e32 v23, 0x3377d1cf, v22
	v_fmac_f32_e32 v23, 0x3f317217, v22
	v_cmp_lt_f32_e64 s[0:1], |v22|, s87
	s_nop 1
	v_cndmask_b32_e64 v22, v22, v23, s[0:1]
	v_cndmask_b32_e32 v23, 0, v231, vcc
	v_sub_f32_e32 v22, v22, v23
	ds_write_b32 v5, v22 offset:40
	global_load_dword v22, v[2:3], off offset:44
	s_waitcnt vmcnt(0) lgkmcnt(0)
	v_sub_f32_e32 v23, 1.0, v22
	v_fmac_f32_e32 v22, v26, v23
	v_cmp_gt_f32_e32 vcc, s12, v22
	s_nop 1
	v_cndmask_b32_e64 v23, 0, 32, vcc
	v_ldexp_f32 v23, v22, v23
	v_log_f32_e32 v23, v23
	s_nop 0
	v_mul_f32_e32 v25, 0x3f317217, v23
	v_fma_f32 v25, v23, s86, -v25
	v_fmac_f32_e32 v25, 0x3377d1cf, v23
	v_fmac_f32_e32 v25, 0x3f317217, v23
	v_cmp_lt_f32_e64 s[0:1], |v23|, s87
	s_nop 1
	v_cndmask_b32_e64 v23, v23, v25, s[0:1]
	v_cndmask_b32_e32 v25, 0, v231, vcc
	v_sub_f32_e32 v23, v23, v25
	ds_write_b32 v5, v23 offset:44
	global_load_dword v23, v[2:3], off offset:48
	v_rcp_f32_e32 v27, v19
	s_waitcnt vmcnt(0) lgkmcnt(0)
	v_sub_f32_e32 v25, 1.0, v23
	v_mul_f32_e32 v19, 1.0, v27
	v_rcp_f32_e32 v27, v18
	v_fmac_f32_e32 v23, v19, v25
	v_cmp_gt_f32_e32 vcc, s12, v23
	v_mul_f32_e32 v26, 1.0, v27
	s_nop 0
	v_cndmask_b32_e64 v18, 0, 32, vcc
	v_ldexp_f32 v18, v23, v18
	v_log_f32_e32 v18, v18
	s_nop 0
	v_mul_f32_e32 v19, 0x3f317217, v18
	v_fma_f32 v19, v18, s86, -v19
	v_fmac_f32_e32 v19, 0x3377d1cf, v18
	v_fmac_f32_e32 v19, 0x3f317217, v18
	v_cmp_lt_f32_e64 s[0:1], |v18|, s87
	s_nop 1
	v_cndmask_b32_e64 v18, v18, v19, s[0:1]
	v_cndmask_b32_e32 v19, 0, v231, vcc
	v_sub_f32_e32 v18, v18, v19
	ds_write_b32 v5, v18 offset:48
	global_load_dword v18, v[2:3], off offset:52
	s_waitcnt vmcnt(0) lgkmcnt(0)
	v_sub_f32_e32 v19, 1.0, v18
	v_fmac_f32_e32 v18, v26, v19
	v_cmp_gt_f32_e32 vcc, s12, v18
	s_nop 1
	v_cndmask_b32_e64 v19, 0, 32, vcc
	v_ldexp_f32 v19, v18, v19
	v_log_f32_e32 v19, v19
	s_nop 0
	v_mul_f32_e32 v25, 0x3f317217, v19
	v_fma_f32 v25, v19, s86, -v25
	v_fmac_f32_e32 v25, 0x3377d1cf, v19
	v_fmac_f32_e32 v25, 0x3f317217, v19
	v_cmp_lt_f32_e64 s[0:1], |v19|, s87
	s_nop 1
	v_cndmask_b32_e64 v19, v19, v25, s[0:1]
	v_cndmask_b32_e32 v25, 0, v231, vcc
	v_sub_f32_e32 v19, v19, v25
	ds_write_b32 v5, v19 offset:52
	global_load_dword v25, v[2:3], off offset:56
	v_rcp_f32_e32 v27, v14
	s_waitcnt vmcnt(0) lgkmcnt(0)
	v_sub_f32_e32 v19, 1.0, v25
	v_mul_f32_e32 v14, 1.0, v27
	v_rcp_f32_e32 v27, v13
	v_fmac_f32_e32 v25, v14, v19
	v_cmp_gt_f32_e32 vcc, s12, v25
	v_mul_f32_e32 v13, 1.0, v27
	s_nop 0
	v_cndmask_b32_e64 v14, 0, 32, vcc
	v_ldexp_f32 v14, v25, v14
	v_log_f32_e32 v14, v14
	s_nop 0
	v_mul_f32_e32 v19, 0x3f317217, v14
	v_fma_f32 v19, v14, s86, -v19
	v_fmac_f32_e32 v19, 0x3377d1cf, v14
	v_fmac_f32_e32 v19, 0x3f317217, v14
	v_cmp_lt_f32_e64 s[0:1], |v14|, s87
	s_nop 1
	v_cndmask_b32_e64 v14, v14, v19, s[0:1]
	v_cndmask_b32_e32 v19, 0, v231, vcc
	v_sub_f32_e32 v14, v14, v19
	ds_write_b32 v5, v14 offset:56
	global_load_dword v3, v[2:3], off offset:60
	s_waitcnt vmcnt(0) lgkmcnt(0)
	v_sub_f32_e32 v2, 1.0, v3
	v_fmac_f32_e32 v3, v13, v2
	v_cmp_gt_f32_e32 vcc, s12, v3
	s_nop 1
	v_cndmask_b32_e64 v2, 0, 32, vcc
	v_ldexp_f32 v2, v3, v2
	v_log_f32_e32 v2, v2
	s_nop 0
	v_mul_f32_e32 v13, 0x3f317217, v2
	v_fma_f32 v13, v2, s86, -v13
	v_fmac_f32_e32 v13, 0x3377d1cf, v2
	v_fmac_f32_e32 v13, 0x3f317217, v2
	v_cmp_lt_f32_e64 s[0:1], |v2|, s87
	s_nop 1
	v_cndmask_b32_e64 v2, v2, v13, s[0:1]
	v_cndmask_b32_e32 v13, 0, v231, vcc
	v_sub_f32_e32 v2, v2, v13
	v_ashrrev_i32_e32 v13, 7, v10
	v_and_b32_e32 v10, 0x7f, v10
	v_lshlrev_b32_e32 v14, 13, v13
	v_lshlrev_b32_e32 v19, 2, v10
	ds_write_b32 v5, v2 offset:60
	v_add3_u32 v2, 0, v19, v14
	s_mov_b64 s[0:1], -1
	s_and_b64 vcc, exec, s[2:3]
	s_waitcnt lgkmcnt(0)
	s_barrier
	s_cbranch_vccz .LBB0_598
	ds_read2st64_b32 v[26:27], v2 offset0:28 offset1:30
	s_mov_b64 s[0:1], 0
	s_waitcnt lgkmcnt(0)
	v_add_f32_e32 v27, 0, v27
	v_add_f32_e32 v28, v27, v26
	ds_write2st64_b32 v2, v28, v27 offset0:28 offset1:30
	ds_read2st64_b32 v[26:27], v2 offset0:24 offset1:26
	s_waitcnt lgkmcnt(0)
	v_add_f32_e32 v27, v28, v27
	v_add_f32_e32 v28, v27, v26
	ds_write2st64_b32 v2, v28, v27 offset0:24 offset1:26
	ds_read2st64_b32 v[26:27], v2 offset0:20 offset1:22
	s_waitcnt lgkmcnt(0)
	v_add_f32_e32 v27, v28, v27
	v_add_f32_e32 v28, v27, v26
	ds_write2st64_b32 v2, v28, v27 offset0:20 offset1:22
	ds_read2st64_b32 v[26:27], v2 offset0:16 offset1:18
	s_waitcnt lgkmcnt(0)
	v_add_f32_e32 v27, v28, v27
	v_add_f32_e32 v28, v27, v26
	ds_write2st64_b32 v2, v28, v27 offset0:16 offset1:18
	ds_read2st64_b32 v[26:27], v2 offset0:12 offset1:14
	s_waitcnt lgkmcnt(0)
	v_add_f32_e32 v27, v28, v27
	v_add_f32_e32 v28, v27, v26
	ds_write2st64_b32 v2, v28, v27 offset0:12 offset1:14
	ds_read2st64_b32 v[26:27], v2 offset0:8 offset1:10
	s_waitcnt lgkmcnt(0)
	v_add_f32_e32 v27, v28, v27
	v_add_f32_e32 v28, v27, v26
	ds_write2st64_b32 v2, v28, v27 offset0:8 offset1:10
	ds_read2st64_b32 v[26:27], v2 offset0:4 offset1:6
	s_waitcnt lgkmcnt(0)
	v_add_f32_e32 v27, v28, v27
	v_add_f32_e32 v28, v27, v26
	ds_write2st64_b32 v2, v28, v27 offset0:4 offset1:6
	ds_read2st64_b32 v[26:27], v2 offset1:2
	s_waitcnt lgkmcnt(0)
	v_add_f32_e32 v27, v28, v27
	v_add_f32_e32 v26, v27, v26
	ds_write2st64_b32 v2, v26, v27 offset1:2

.LBB0_729:
	s_waitcnt lgkmcnt(3)
	v_pk_mul_f32 v[18:19], v[22:23], v[22:23]
	v_pk_mul_f32 v[20:21], v[24:25], v[24:25]
	v_add_f32_e32 v17, v18, v19
	v_add_f32_e32 v17, v17, v20
	s_waitcnt lgkmcnt(2)
	v_pk_mul_f32 v[26:27], v[8:9], v[8:9]
	v_add_f32_e32 v17, v17, v21
	v_add_f32_e32 v17, v17, v26
	v_pk_mul_f32 v[28:29], v[10:11], v[10:11]
	v_add_f32_e32 v17, v17, v27
	v_add_f32_e32 v17, v17, v28
	s_waitcnt lgkmcnt(1)
	v_pk_mul_f32 v[30:31], v[4:5], v[4:5]
	v_add_f32_e32 v17, v17, v29
	v_add_f32_e32 v17, v17, v30
	v_pk_mul_f32 v[32:33], v[6:7], v[6:7]
	v_add_f32_e32 v17, v17, v31
	v_add_f32_e32 v17, v17, v32
	s_waitcnt lgkmcnt(0)
	v_pk_mul_f32 v[36:37], v[0:1], v[0:1]
	v_add_f32_e32 v17, v17, v33
	v_add_f32_e32 v17, v17, v36
	v_pk_mul_f32 v[38:39], v[2:3], v[2:3]
	v_add_f32_e32 v17, v17, v37
	v_cmp_lt_i32_e32 vcc, v16, v13
	v_add_f32_e32 v17, v17, v38
	v_add_f32_e32 v17, v17, v39
	v_cndmask_b32_e32 v16, v12, v16, vcc
	v_lshlrev_b32_e32 v16, 2, v16
	ds_bpermute_b32 v16, v16, v17
	v_cmp_lt_i32_e32 vcc, v15, v13
	s_add_u32 s0, s0, s82
	s_addc_u32 s1, s1, s83
	v_cndmask_b32_e32 v15, v12, v15, vcc
	s_waitcnt lgkmcnt(0)
	v_add_f32_e32 v16, v17, v16
	v_lshlrev_b32_e32 v15, 2, v15
	ds_bpermute_b32 v15, v15, v16
	v_cmp_lt_i32_e32 vcc, v14, v13
	s_lshl_b32 s3, s20, 2
	s_add_u32 s0, s0, s3
	v_cndmask_b32_e32 v12, v12, v14, vcc
	s_waitcnt lgkmcnt(0)
	v_add_f32_e32 v15, v16, v15
	v_lshlrev_b32_e32 v12, 2, v12
	ds_bpermute_b32 v12, v12, v15
	s_addc_u32 s1, s1, 0
	s_lshl_b32 s26, s2, 1
	v_lshlrev_b32_e32 v128, 1, v66
	s_waitcnt lgkmcnt(0)
	v_add_f32_e32 v12, v15, v12
	v_fmamk_f32 v12, v12, 0x3c000000, v198
	v_cmp_gt_f32_e32 vcc, s12, v12
	v_mul_f32_e32 v13, 0x4b800000, v12
	s_nop 0
	v_cndmask_b32_e32 v12, v12, v13, vcc
	v_rsq_f32_e32 v12, v12
	s_nop 0
	v_mul_f32_e32 v13, 0x45800000, v12
	v_cndmask_b32_e32 v38, v12, v13, vcc
	v_lshl_add_u64 v[12:13], v[68:69], 0, s[26:27]
	s_lshl_b32 s26, s20, 1
	v_lshl_add_u64 v[12:13], v[12:13], 0, s[26:27]
	v_lshl_add_u64 v[12:13], v[12:13], 0, v[128:129]
	global_load_dwordx4 v[26:29], v[12:13], off
	s_nop 0
	global_load_dwordx4 v[12:15], v[12:13], off offset:16
	s_waitcnt vmcnt(0) lgkmcnt(0)
	v_lshlrev_b32_e32 v39, 16, v26
	v_mul_f32_e32 v16, 0xbfb8aa3b, v39
	v_exp_f32_e32 v40, v16
	v_pk_mul_f32 v[42:43], v[22:23], v[38:39] op_sel_hi:[1,0]
	global_load_dwordx4 v[16:19], v34, s[0:1] offset:48
	global_load_dwordx4 v[20:23], v34, s[0:1] offset:32
	global_load_dwordx4 v[30:33], v34, s[0:1] offset:16
	s_nop 0
	global_load_dwordx4 v[34:37], v34, s[0:1]
	v_and_b32_e32 v26, 0xffff0000, v26
	v_mul_f32_e32 v41, 0xbfb8aa3b, v26
	v_exp_f32_e32 v41, v41
	s_waitcnt vmcnt(0)
	v_pk_mul_f32 v[34:35], v[34:35], v[42:43]
	v_pk_add_f32 v[40:41], v[40:41], 1.0 op_sel_hi:[1,0]
	s_nop 0
	v_rcp_f32_e32 v43, v41
	s_nop 0
	v_mul_f32_e32 v41, v26, v43
	v_rcp_f32_e32 v42, v40
	s_nop 0
	v_mul_f32_e32 v40, v39, v42
	v_pk_mul_f32 v[34:35], v[40:41], v[34:35]
	v_lshlrev_b32_e32 v39, 16, v27
	v_and_b32_e32 v40, 0xffff0000, v27
	v_mul_f32_e32 v26, 0xbfb8aa3b, v39
	v_mul_f32_e32 v27, 0xbfb8aa3b, v40
	v_exp_f32_e32 v26, v26
	v_exp_f32_e32 v27, v27
	v_pk_mul_f32 v[24:25], v[24:25], v[38:39] op_sel_hi:[1,0]
	v_pk_mul_f32 v[8:9], v[8:9], v[38:39] op_sel_hi:[1,0]
	v_pk_mul_f32 v[24:25], v[36:37], v[24:25]
	v_pk_add_f32 v[26:27], v[26:27], 1.0 op_sel_hi:[1,0]
	v_pk_mul_f32 v[8:9], v[30:31], v[8:9]
	v_rcp_f32_e32 v37, v27
	s_nop 0
	v_mul_f32_e32 v27, v40, v37
	v_rcp_f32_e32 v37, v26
	s_nop 0
	v_mul_f32_e32 v26, v39, v37
	v_lshlrev_b32_e32 v36, 16, v28
	v_and_b32_e32 v28, 0xffff0000, v28
	v_pk_mul_f32 v[24:25], v[26:27], v[24:25]
	v_mul_f32_e32 v26, 0xbfb8aa3b, v36
	v_mul_f32_e32 v27, 0xbfb8aa3b, v28
	v_exp_f32_e32 v26, v26
	v_exp_f32_e32 v27, v27
	s_nop 0
	v_pk_add_f32 v[26:27], v[26:27], 1.0 op_sel_hi:[1,0]
	s_nop 0
	v_rcp_f32_e32 v31, v27
	s_nop 0
	v_mul_f32_e32 v27, v28, v31
	v_rcp_f32_e32 v30, v26
	s_nop 0
	v_mul_f32_e32 v26, v36, v30
	v_lshlrev_b32_e32 v28, 16, v29
	v_and_b32_e32 v29, 0xffff0000, v29
	v_pk_mul_f32 v[8:9], v[26:27], v[8:9]
	v_mul_f32_e32 v26, 0xbfb8aa3b, v28
	v_mul_f32_e32 v27, 0xbfb8aa3b, v29
	v_exp_f32_e32 v26, v26
	v_exp_f32_e32 v27, v27
	v_pk_mul_f32 v[10:11], v[10:11], v[38:39] op_sel_hi:[1,0]
	v_pk_mul_f32 v[4:5], v[4:5], v[38:39] op_sel_hi:[1,0]
	v_pk_mul_f32 v[10:11], v[32:33], v[10:11]
	v_pk_add_f32 v[26:27], v[26:27], 1.0 op_sel_hi:[1,0]
	v_pk_mul_f32 v[4:5], v[4:5], v[20:21]
	v_rcp_f32_e32 v31, v27
	v_pk_mul_f32 v[6:7], v[6:7], v[38:39] op_sel_hi:[1,0]
	v_pk_mul_f32 v[0:1], v[0:1], v[38:39] op_sel_hi:[1,0]
	v_pk_mul_f32 v[6:7], v[6:7], v[22:23]
	v_mul_f32_e32 v27, v29, v31
	v_rcp_f32_e32 v30, v26
	v_pk_mul_f32 v[0:1], v[0:1], v[16:17]
	v_pk_mul_f32 v[2:3], v[2:3], v[38:39] op_sel_hi:[1,0]
	v_mul_f32_e32 v26, v28, v30
	v_lshlrev_b32_e32 v28, 16, v12
	v_and_b32_e32 v12, 0xffff0000, v12
	v_pk_mul_f32 v[10:11], v[26:27], v[10:11]
	v_mul_f32_e32 v26, 0xbfb8aa3b, v28
	v_mul_f32_e32 v20, 0xbfb8aa3b, v12
	v_exp_f32_e32 v26, v26
	v_exp_f32_e32 v27, v20
	v_pk_mul_f32 v[2:3], v[2:3], v[18:19]
	v_pk_add_f32 v[20:21], v[26:27], 1.0 op_sel_hi:[1,0]
	s_nop 0
	v_rcp_f32_e32 v27, v21
	s_nop 0
	v_mul_f32_e32 v21, v12, v27
	v_rcp_f32_e32 v26, v20
	s_nop 0
	v_mul_f32_e32 v20, v28, v26
	v_pk_mul_f32 v[4:5], v[20:21], v[4:5]
	v_lshlrev_b32_e32 v20, 16, v13
	v_and_b32_e32 v21, 0xffff0000, v13
	v_mul_f32_e32 v12, 0xbfb8aa3b, v20
	v_mul_f32_e32 v13, 0xbfb8aa3b, v21
	v_exp_f32_e32 v12, v12
	v_exp_f32_e32 v13, v13
	v_cvt_pk_bf16_f32 v4, v4, v5
	v_pk_add_f32 v[12:13], v[12:13], 1.0 op_sel_hi:[1,0]
	s_nop 0
	v_rcp_f32_e32 v23, v13
	s_nop 0
	v_mul_f32_e32 v13, v21, v23
	v_rcp_f32_e32 v22, v12
	s_nop 0
	v_mul_f32_e32 v12, v20, v22
	v_lshlrev_b32_e32 v20, 16, v14
	v_and_b32_e32 v14, 0xffff0000, v14
	v_pk_mul_f32 v[6:7], v[12:13], v[6:7]
	v_mul_f32_e32 v12, 0xbfb8aa3b, v20
	v_mul_f32_e32 v13, 0xbfb8aa3b, v14
	v_exp_f32_e32 v12, v12
	v_exp_f32_e32 v13, v13
	v_cvt_pk_bf16_f32 v5, v6, v7
	v_pk_add_f32 v[12:13], v[12:13], 1.0 op_sel_hi:[1,0]
	s_nop 0
	v_rcp_f32_e32 v17, v13
	s_nop 0
	v_mul_f32_e32 v13, v14, v17
	v_rcp_f32_e32 v16, v12
	s_nop 0
	v_mul_f32_e32 v12, v20, v16
	v_lshlrev_b32_e32 v14, 16, v15
	v_and_b32_e32 v15, 0xffff0000, v15
	v_pk_mul_f32 v[12:13], v[12:13], v[0:1]
	v_mul_f32_e32 v0, 0xbfb8aa3b, v14
	v_mul_f32_e32 v1, 0xbfb8aa3b, v15
	v_exp_f32_e32 v0, v0
	v_exp_f32_e32 v1, v1
	v_cvt_pk_bf16_f32 v6, v12, v13
	v_pk_add_f32 v[0:1], v[0:1], 1.0 op_sel_hi:[1,0]
	s_nop 0
	v_rcp_f32_e32 v17, v1
	s_nop 0
	v_mul_f32_e32 v1, v15, v17
	v_rcp_f32_e32 v16, v0
	v_readlane_b32 s0, v251, 3
	v_readlane_b32 s1, v251, 4
	v_mul_f32_e32 v0, v14, v16
	v_pk_mul_f32 v[14:15], v[0:1], v[2:3]
	v_cvt_pk_bf16_f32 v2, v8, v9
	v_lshlrev_b64 v[8:9], 11, v[64:65]
	v_lshl_add_u64 v[8:9], s[0:1], 0, v[8:9]
	s_lshl_b32 s0, s75, 9
	s_ashr_i32 s1, s0, 31
	v_lshl_add_u64 v[8:9], s[0:1], 1, v[8:9]
	v_readlane_b32 s0, v251, 1
	v_lshl_add_u64 v[8:9], v[8:9], 0, s[26:27]
	s_add_i32 s74, s74, s0
	v_readlane_b32 s0, v255, 36
	v_cvt_pk_bf16_f32 v0, v34, v35
	v_cvt_pk_bf16_f32 v1, v24, v25
	v_cvt_pk_bf16_f32 v3, v10, v11
	v_lshl_add_u64 v[8:9], v[8:9], 0, v[128:129]
	s_cmp_ge_i32 s74, s0
	v_cvt_pk_bf16_f32 v7, v14, v15
	global_store_dwordx4 v[8:9], v[0:3], off
	global_store_dwordx4 v[8:9], v[4:7], off offset:16
	v_readlane_b32 s1, v251, 2
	s_cbranch_scc1 .LBB0_726

.LBB0_736:
	s_xor_b64 s[18:19], s[92:93], -1
	s_or_b32 s0, s95, s23
	s_mul_hi_i32 s8, s0, 0x84
	s_mul_i32 s9, s0, 0x84
	s_and_b64 s[0:1], s[92:93], exec
	s_cselect_b32 s0, s21, s94
	s_ashr_i32 s1, s0, 31
	s_add_u32 s0, s9, s0
	s_addc_u32 s1, s8, s1
	s_lshl_b64 s[0:1], s[0:1], 15
	v_lshl_add_u64 v[16:17], v[86:87], 0, s[0:1]
	global_load_dwordx4 v[60:63], v[16:17], off
	global_load_dwordx4 v[56:59], v[16:17], off offset:32
	global_load_dwordx4 v[52:55], v[16:17], off offset:64
	global_load_dwordx4 v[48:51], v[16:17], off offset:96
	global_load_dwordx4 v[44:47], v[16:17], off offset:128
	global_load_dwordx4 v[40:43], v[16:17], off offset:160
	global_load_dwordx4 v[36:39], v[16:17], off offset:192
	global_load_dwordx4 v[32:35], v[16:17], off offset:224
	v_mov_b32_e32 v113, v207
	s_and_b64 vcc, exec, s[96:97]
	v_ashrrev_i32_e32 v110, 3, v113
	v_lshlrev_b32_e32 v16, 4, v113
	v_and_b32_e32 v111, 0x70, v16
	v_add_u32_e32 v18, s22, v110
	v_mov_b64_e32 v[16:17], s[2:3]
	v_mad_i64_i32 v[16:17], s[0:1], v18, s14, v[16:17]
	v_lshlrev_b32_e32 v128, 1, v111
	v_lshl_add_u64 v[90:91], v[16:17], 0, v[128:129]
	v_lshlrev_b32_e32 v16, 9, v110
	v_lshlrev_b32_e32 v17, 2, v111
	v_add3_u32 v109, 0, v16, v17
	s_mov_b64 s[0:1], -1
	s_cbranch_vccz .LBB0_754
	s_and_b64 s[0:1], s[92:93], exec
	s_cselect_b32 s26, s15, 0x1800
	v_lshl_add_u64 v[20:21], v[90:91], 0, s[26:27]
	global_load_dwordx4 v[16:19], v[20:21], off
	global_load_dwordx4 v[116:119], v[20:21], off offset:16
	s_waitcnt vmcnt(0) lgkmcnt(0)
	v_lshlrev_b32_e32 v20, 16, v16
	v_and_b32_e32 v112, 0xffff0000, v16
	v_or_b32_e32 v16, s20, v111
	v_lshlrev_b32_e32 v128, 2, v16
	v_lshlrev_b32_e32 v115, 16, v17
	v_and_b32_e32 v120, 0xffff0000, v17
	v_lshl_add_u64 v[16:17], s[78:79], 0, v[128:129]
	global_load_dword v111, v[16:17], off
	v_lshlrev_b32_e32 v31, 16, v19
	v_and_b32_e32 v30, 0xffff0000, v19
	v_mul_f32_e32 v19, 0xbfb8aa3b, v20
	v_exp_f32_e32 v19, v19
	v_lshlrev_b32_e32 v29, 16, v116
	v_and_b32_e32 v28, 0xffff0000, v116
	v_lshlrev_b32_e32 v27, 16, v117
	v_add_f32_e32 v19, 1.0, v19
	v_rcp_f32_e32 v116, v19
	v_and_b32_e32 v26, 0xffff0000, v117
	v_lshlrev_b32_e32 v25, 16, v118
	v_and_b32_e32 v24, 0xffff0000, v118
	v_lshlrev_b32_e32 v23, 16, v119
	v_and_b32_e32 v22, 0xffff0000, v119
	v_mul_f32_e32 v19, 1.0, v116
	v_mul_f32_e32 v20, 0xbfb8aa3b, v112
	v_exp_f32_e32 v20, v20
	v_lshlrev_b32_e32 v114, 16, v18
	v_and_b32_e32 v21, 0xffff0000, v18
	v_mul_f32_e32 v114, 0xbfb8aa3b, v114
	v_add_f32_e32 v20, 1.0, v20
	v_rcp_f32_e32 v116, v20
	v_exp_f32_e32 v114, v114
	v_mul_f32_e32 v21, 0xbfb8aa3b, v21
	v_exp_f32_e32 v21, v21
	v_mul_f32_e32 v20, 1.0, v116
	v_add_f32_e32 v114, 1.0, v114
	v_add_f32_e32 v21, 1.0, v21
	v_mul_f32_e32 v31, 0xbfb8aa3b, v31
	v_exp_f32_e32 v31, v31
	v_mul_f32_e32 v30, 0xbfb8aa3b, v30
	v_exp_f32_e32 v30, v30
	v_mul_f32_e32 v29, 0xbfb8aa3b, v29
	v_add_f32_e32 v31, 1.0, v31
	v_exp_f32_e32 v29, v29
	v_add_f32_e32 v30, 1.0, v30
	v_mul_f32_e32 v28, 0xbfb8aa3b, v28
	v_exp_f32_e32 v28, v28
	v_add_f32_e32 v29, 1.0, v29
	v_mul_f32_e32 v27, 0xbfb8aa3b, v27
	v_exp_f32_e32 v27, v27
	v_add_f32_e32 v28, 1.0, v28
	v_mul_f32_e32 v26, 0xbfb8aa3b, v26
	v_exp_f32_e32 v26, v26
	v_add_f32_e32 v27, 1.0, v27
	v_mul_f32_e32 v25, 0xbfb8aa3b, v25
	v_exp_f32_e32 v25, v25
	v_add_f32_e32 v26, 1.0, v26
	v_mul_f32_e32 v24, 0xbfb8aa3b, v24
	v_exp_f32_e32 v24, v24
	v_add_f32_e32 v25, 1.0, v25
	v_mul_f32_e32 v23, 0xbfb8aa3b, v23
	v_exp_f32_e32 v23, v23
	v_add_f32_e32 v24, 1.0, v24
	v_mul_f32_e32 v22, 0xbfb8aa3b, v22
	v_exp_f32_e32 v22, v22
	v_add_f32_e32 v23, 1.0, v23
	s_waitcnt vmcnt(0) lgkmcnt(0)
	v_sub_f32_e32 v18, 1.0, v111
	v_fmac_f32_e32 v111, v18, v19
	v_cmp_gt_f32_e32 vcc, s12, v111
	v_add_f32_e32 v22, 1.0, v22
	s_nop 0
	v_cndmask_b32_e64 v18, 0, 32, vcc
	v_ldexp_f32 v18, v111, v18
	v_log_f32_e32 v18, v18
	s_nop 0
	v_mul_f32_e32 v19, 0x3f317217, v18
	v_fma_f32 v19, v18, s86, -v19
	v_fmac_f32_e32 v19, 0x3377d1cf, v18
	v_fmac_f32_e32 v19, 0x3f317217, v18
	v_cmp_lt_f32_e64 s[0:1], |v18|, s87
	s_nop 1
	v_cndmask_b32_e64 v18, v18, v19, s[0:1]
	v_cndmask_b32_e32 v19, 0, v231, vcc
	v_sub_f32_e32 v18, v18, v19
	ds_write_b32 v109, v18
	global_load_dword v112, v[16:17], off offset:4
	s_waitcnt vmcnt(0) lgkmcnt(0)
	v_sub_f32_e32 v18, 1.0, v112
	v_fmac_f32_e32 v112, v18, v20
	v_cmp_gt_f32_e32 vcc, s12, v112
	v_mul_f32_e32 v20, 0xbfb8aa3b, v115
	v_exp_f32_e32 v20, v20
	v_cndmask_b32_e64 v18, 0, 32, vcc
	v_ldexp_f32 v18, v112, v18
	v_log_f32_e32 v18, v18
	v_add_f32_e32 v20, 1.0, v20
	v_mul_f32_e32 v19, 0x3f317217, v18
	v_fma_f32 v19, v18, s86, -v19
	v_fmac_f32_e32 v19, 0x3377d1cf, v18
	v_fmac_f32_e32 v19, 0x3f317217, v18
	v_cmp_lt_f32_e64 s[0:1], |v18|, s87
	s_nop 1
	v_cndmask_b32_e64 v18, v18, v19, s[0:1]
	v_cndmask_b32_e32 v19, 0, v231, vcc
	v_sub_f32_e32 v18, v18, v19
	ds_write_b32 v109, v18 offset:4
	global_load_dword v18, v[16:17], off offset:8
	v_rcp_f32_e32 v116, v20
	s_waitcnt vmcnt(0) lgkmcnt(0)
	v_sub_f32_e32 v19, 1.0, v18
	v_mul_f32_e32 v20, 1.0, v116
	v_mul_f32_e32 v115, 0xbfb8aa3b, v120
	v_exp_f32_e32 v115, v115
	v_fmac_f32_e32 v18, v20, v19
	v_add_f32_e32 v115, 1.0, v115
	v_rcp_f32_e32 v117, v115
	s_nop 0
	v_cmp_gt_f32_e32 vcc, s12, v18
	v_mul_f32_e32 v115, 1.0, v117
	s_nop 0
	v_cndmask_b32_e64 v19, 0, 32, vcc
	v_ldexp_f32 v19, v18, v19
	v_log_f32_e32 v19, v19
	s_nop 0
	v_mul_f32_e32 v20, 0x3f317217, v19
	v_fma_f32 v20, v19, s86, -v20
	v_fmac_f32_e32 v20, 0x3377d1cf, v19
	v_fmac_f32_e32 v20, 0x3f317217, v19
	v_cmp_lt_f32_e64 s[0:1], |v19|, s87
	s_nop 1
	v_cndmask_b32_e64 v19, v19, v20, s[0:1]
	v_cndmask_b32_e32 v20, 0, v231, vcc
	v_sub_f32_e32 v19, v19, v20
	ds_write_b32 v109, v19 offset:8
	global_load_dword v19, v[16:17], off offset:12
	s_waitcnt vmcnt(0) lgkmcnt(0)
	v_sub_f32_e32 v20, 1.0, v19
	v_fmac_f32_e32 v19, v115, v20
	v_cmp_gt_f32_e32 vcc, s12, v19
	s_nop 1
	v_cndmask_b32_e64 v20, 0, 32, vcc
	v_ldexp_f32 v20, v19, v20
	v_log_f32_e32 v20, v20
	s_nop 0
	v_mul_f32_e32 v115, 0x3f317217, v20
	v_fma_f32 v115, v20, s86, -v115
	v_fmac_f32_e32 v115, 0x3377d1cf, v20
	v_fmac_f32_e32 v115, 0x3f317217, v20
	v_cmp_lt_f32_e64 s[0:1], |v20|, s87
	s_nop 1
	v_cndmask_b32_e64 v20, v20, v115, s[0:1]
	v_cndmask_b32_e32 v115, 0, v231, vcc
	v_sub_f32_e32 v20, v20, v115
	ds_write_b32 v109, v20 offset:12
	global_load_dword v20, v[16:17], off offset:16
	v_rcp_f32_e32 v117, v114
	s_waitcnt vmcnt(0) lgkmcnt(0)
	v_sub_f32_e32 v115, 1.0, v20
	v_mul_f32_e32 v114, 1.0, v117
	v_rcp_f32_e32 v117, v21
	v_fmac_f32_e32 v20, v114, v115
	v_cmp_gt_f32_e32 vcc, s12, v20
	v_mul_f32_e32 v116, 1.0, v117
	s_nop 0
	v_cndmask_b32_e64 v21, 0, 32, vcc
	v_ldexp_f32 v21, v20, v21
	v_log_f32_e32 v21, v21
	s_nop 0
	v_mul_f32_e32 v114, 0x3f317217, v21
	v_fma_f32 v114, v21, s86, -v114
	v_fmac_f32_e32 v114, 0x3377d1cf, v21
	v_fmac_f32_e32 v114, 0x3f317217, v21
	v_cmp_lt_f32_e64 s[0:1], |v21|, s87
	s_nop 1
	v_cndmask_b32_e64 v21, v21, v114, s[0:1]
	v_cndmask_b32_e32 v114, 0, v231, vcc
	v_sub_f32_e32 v21, v21, v114
	ds_write_b32 v109, v21 offset:16
	global_load_dword v21, v[16:17], off offset:20
	s_waitcnt vmcnt(0) lgkmcnt(0)
	v_sub_f32_e32 v114, 1.0, v21
	v_fmac_f32_e32 v21, v116, v114
	v_cmp_gt_f32_e32 vcc, s12, v21
	s_nop 1
	v_cndmask_b32_e64 v114, 0, 32, vcc
	v_ldexp_f32 v114, v21, v114
	v_log_f32_e32 v114, v114
	s_nop 0
	v_mul_f32_e32 v115, 0x3f317217, v114
	v_fma_f32 v115, v114, s86, -v115
	v_fmac_f32_e32 v115, 0x3377d1cf, v114
	v_fmac_f32_e32 v115, 0x3f317217, v114
	v_cmp_lt_f32_e64 s[0:1], |v114|, s87
	s_nop 1
	v_cndmask_b32_e64 v114, v114, v115, s[0:1]
	v_cndmask_b32_e32 v115, 0, v231, vcc
	v_sub_f32_e32 v114, v114, v115
	ds_write_b32 v109, v114 offset:20
	global_load_dword v114, v[16:17], off offset:24
	v_rcp_f32_e32 v117, v31
	s_waitcnt vmcnt(0) lgkmcnt(0)
	v_sub_f32_e32 v115, 1.0, v114
	v_mul_f32_e32 v31, 1.0, v117
	v_rcp_f32_e32 v117, v30
	v_fmac_f32_e32 v114, v31, v115
	v_cmp_gt_f32_e32 vcc, s12, v114
	v_mul_f32_e32 v30, 1.0, v117
	s_nop 0
	v_cndmask_b32_e64 v31, 0, 32, vcc
	v_ldexp_f32 v31, v114, v31
	v_log_f32_e32 v31, v31
	s_nop 0
	v_mul_f32_e32 v115, 0x3f317217, v31
	v_fma_f32 v115, v31, s86, -v115
	v_fmac_f32_e32 v115, 0x3377d1cf, v31
	v_fmac_f32_e32 v115, 0x3f317217, v31
	v_cmp_lt_f32_e64 s[0:1], |v31|, s87
	s_nop 1
	v_cndmask_b32_e64 v31, v31, v115, s[0:1]
	v_cndmask_b32_e32 v115, 0, v231, vcc
	v_sub_f32_e32 v31, v31, v115
	ds_write_b32 v109, v31 offset:24
	global_load_dword v115, v[16:17], off offset:28
	s_waitcnt vmcnt(0) lgkmcnt(0)
	v_sub_f32_e32 v31, 1.0, v115
	v_fmac_f32_e32 v115, v30, v31
	v_cmp_gt_f32_e32 vcc, s12, v115
	s_nop 1
	v_cndmask_b32_e64 v30, 0, 32, vcc
	v_ldexp_f32 v30, v115, v30
	v_log_f32_e32 v30, v30
	s_nop 0
	v_mul_f32_e32 v31, 0x3f317217, v30
	v_fma_f32 v31, v30, s86, -v31
	v_fmac_f32_e32 v31, 0x3377d1cf, v30
	v_fmac_f32_e32 v31, 0x3f317217, v30
	v_cmp_lt_f32_e64 s[0:1], |v30|, s87
	s_nop 1
	v_cndmask_b32_e64 v30, v30, v31, s[0:1]
	v_cndmask_b32_e32 v31, 0, v231, vcc
	v_sub_f32_e32 v30, v30, v31
	ds_write_b32 v109, v30 offset:28
	global_load_dword v116, v[16:17], off offset:32
	v_rcp_f32_e32 v117, v29
	s_waitcnt vmcnt(0) lgkmcnt(0)
	v_sub_f32_e32 v30, 1.0, v116
	v_mul_f32_e32 v29, 1.0, v117
	v_rcp_f32_e32 v117, v28
	v_fmac_f32_e32 v116, v29, v30
	v_cmp_gt_f32_e32 vcc, s12, v116
	v_mul_f32_e32 v28, 1.0, v117
	s_nop 0
	v_cndmask_b32_e64 v29, 0, 32, vcc
	v_ldexp_f32 v29, v116, v29
	v_log_f32_e32 v29, v29
	s_nop 0
	v_mul_f32_e32 v30, 0x3f317217, v29
	v_fma_f32 v30, v29, s86, -v30
	v_fmac_f32_e32 v30, 0x3377d1cf, v29
	v_fmac_f32_e32 v30, 0x3f317217, v29
	v_cmp_lt_f32_e64 s[0:1], |v29|, s87
	s_nop 1
	v_cndmask_b32_e64 v29, v29, v30, s[0:1]
	v_cndmask_b32_e32 v30, 0, v231, vcc
	v_sub_f32_e32 v29, v29, v30
	ds_write_b32 v109, v29 offset:32
	global_load_dword v117, v[16:17], off offset:36
	s_waitcnt vmcnt(0) lgkmcnt(0)
	v_sub_f32_e32 v29, 1.0, v117
	v_fmac_f32_e32 v117, v28, v29
	v_cmp_gt_f32_e32 vcc, s12, v117
	s_nop 1
	v_cndmask_b32_e64 v28, 0, 32, vcc
	v_ldexp_f32 v28, v117, v28
	v_log_f32_e32 v28, v28
	s_nop 0
	v_mul_f32_e32 v29, 0x3f317217, v28
	v_fma_f32 v29, v28, s86, -v29
	v_fmac_f32_e32 v29, 0x3377d1cf, v28
	v_fmac_f32_e32 v29, 0x3f317217, v28
	v_cmp_lt_f32_e64 s[0:1], |v28|, s87
	s_nop 1
	v_cndmask_b32_e64 v28, v28, v29, s[0:1]
	v_cndmask_b32_e32 v29, 0, v231, vcc
	v_sub_f32_e32 v28, v28, v29
	ds_write_b32 v109, v28 offset:36
	global_load_dword v118, v[16:17], off offset:40
	v_rcp_f32_e32 v30, v27
	s_waitcnt vmcnt(0) lgkmcnt(0)
	v_sub_f32_e32 v28, 1.0, v118
	v_mul_f32_e32 v27, 1.0, v30
	v_rcp_f32_e32 v30, v26
	v_fmac_f32_e32 v118, v27, v28
	v_cmp_gt_f32_e32 vcc, s12, v118
	v_mul_f32_e32 v29, 1.0, v30
	s_nop 0
	v_cndmask_b32_e64 v26, 0, 32, vcc
	v_ldexp_f32 v26, v118, v26
	v_log_f32_e32 v26, v26
	s_nop 0
	v_mul_f32_e32 v27, 0x3f317217, v26
	v_fma_f32 v27, v26, s86, -v27
	v_fmac_f32_e32 v27, 0x3377d1cf, v26
	v_fmac_f32_e32 v27, 0x3f317217, v26
	v_cmp_lt_f32_e64 s[0:1], |v26|, s87
	s_nop 1
	v_cndmask_b32_e64 v26, v26, v27, s[0:1]
	v_cndmask_b32_e32 v27, 0, v231, vcc
	v_sub_f32_e32 v26, v26, v27
	ds_write_b32 v109, v26 offset:40
	global_load_dword v26, v[16:17], off offset:44
	s_waitcnt vmcnt(0) lgkmcnt(0)
	v_sub_f32_e32 v27, 1.0, v26
	v_fmac_f32_e32 v26, v29, v27
	v_cmp_gt_f32_e32 vcc, s12, v26
	s_nop 1
	v_cndmask_b32_e64 v27, 0, 32, vcc
	v_ldexp_f32 v27, v26, v27
	v_log_f32_e32 v27, v27
	s_nop 0
	v_mul_f32_e32 v28, 0x3f317217, v27
	v_fma_f32 v28, v27, s86, -v28
	v_fmac_f32_e32 v28, 0x3377d1cf, v27
	v_fmac_f32_e32 v28, 0x3f317217, v27
	v_cmp_lt_f32_e64 s[0:1], |v27|, s87
	s_nop 1
	v_cndmask_b32_e64 v27, v27, v28, s[0:1]
	v_cndmask_b32_e32 v28, 0, v231, vcc
	v_sub_f32_e32 v27, v27, v28
	ds_write_b32 v109, v27 offset:44
	global_load_dword v27, v[16:17], off offset:48
	v_rcp_f32_e32 v30, v25
	s_waitcnt vmcnt(0) lgkmcnt(0)
	v_sub_f32_e32 v28, 1.0, v27
	v_mul_f32_e32 v25, 1.0, v30
	v_rcp_f32_e32 v30, v24
	v_fmac_f32_e32 v27, v25, v28
	v_cmp_gt_f32_e32 vcc, s12, v27
	v_mul_f32_e32 v29, 1.0, v30
	s_nop 0
	v_cndmask_b32_e64 v24, 0, 32, vcc
	v_ldexp_f32 v24, v27, v24
	v_log_f32_e32 v24, v24
	s_nop 0
	v_mul_f32_e32 v25, 0x3f317217, v24
	v_fma_f32 v25, v24, s86, -v25
	v_fmac_f32_e32 v25, 0x3377d1cf, v24
	v_fmac_f32_e32 v25, 0x3f317217, v24
	v_cmp_lt_f32_e64 s[0:1], |v24|, s87
	s_nop 1
	v_cndmask_b32_e64 v24, v24, v25, s[0:1]
	v_cndmask_b32_e32 v25, 0, v231, vcc
	v_sub_f32_e32 v24, v24, v25
	ds_write_b32 v109, v24 offset:48
	global_load_dword v24, v[16:17], off offset:52
	s_waitcnt vmcnt(0) lgkmcnt(0)
	v_sub_f32_e32 v25, 1.0, v24
	v_fmac_f32_e32 v24, v29, v25
	v_cmp_gt_f32_e32 vcc, s12, v24
	s_nop 1
	v_cndmask_b32_e64 v25, 0, 32, vcc
	v_ldexp_f32 v25, v24, v25
	v_log_f32_e32 v25, v25
	s_nop 0
	v_mul_f32_e32 v28, 0x3f317217, v25
	v_fma_f32 v28, v25, s86, -v28
	v_fmac_f32_e32 v28, 0x3377d1cf, v25
	v_fmac_f32_e32 v28, 0x3f317217, v25
	v_cmp_lt_f32_e64 s[0:1], |v25|, s87
	s_nop 1
	v_cndmask_b32_e64 v25, v25, v28, s[0:1]
	v_cndmask_b32_e32 v28, 0, v231, vcc
	v_sub_f32_e32 v25, v25, v28
	ds_write_b32 v109, v25 offset:52
	global_load_dword v25, v[16:17], off offset:56
	v_rcp_f32_e32 v30, v23
	s_waitcnt vmcnt(0) lgkmcnt(0)
	v_sub_f32_e32 v28, 1.0, v25
	v_mul_f32_e32 v23, 1.0, v30
	v_rcp_f32_e32 v30, v22
	v_fmac_f32_e32 v25, v23, v28
	v_cmp_gt_f32_e32 vcc, s12, v25
	v_mul_f32_e32 v22, 1.0, v30
	s_nop 0
	v_cndmask_b32_e64 v23, 0, 32, vcc
	v_ldexp_f32 v23, v25, v23
	v_log_f32_e32 v23, v23
	s_nop 0
	v_mul_f32_e32 v28, 0x3f317217, v23
	v_fma_f32 v28, v23, s86, -v28
	v_fmac_f32_e32 v28, 0x3377d1cf, v23
	v_fmac_f32_e32 v28, 0x3f317217, v23
	v_cmp_lt_f32_e64 s[0:1], |v23|, s87
	s_nop 1
	v_cndmask_b32_e64 v23, v23, v28, s[0:1]
	v_cndmask_b32_e32 v28, 0, v231, vcc
	v_sub_f32_e32 v23, v23, v28
	ds_write_b32 v109, v23 offset:56
	global_load_dword v16, v[16:17], off offset:60
	s_waitcnt vmcnt(0) lgkmcnt(0)
	v_sub_f32_e32 v17, 1.0, v16
	v_fmac_f32_e32 v16, v22, v17
	v_cmp_gt_f32_e32 vcc, s12, v16
	s_nop 1
	v_cndmask_b32_e64 v17, 0, 32, vcc
	v_ldexp_f32 v17, v16, v17
	v_log_f32_e32 v17, v17
	s_nop 0
	v_mul_f32_e32 v22, 0x3f317217, v17
	v_fma_f32 v22, v17, s86, -v22
	v_fmac_f32_e32 v22, 0x3377d1cf, v17
	v_fmac_f32_e32 v22, 0x3f317217, v17
	v_cmp_lt_f32_e64 s[0:1], |v17|, s87
	s_nop 1
	v_cndmask_b32_e64 v17, v17, v22, s[0:1]
	v_cndmask_b32_e32 v22, 0, v231, vcc
	v_sub_f32_e32 v17, v17, v22
	ds_write_b32 v109, v17 offset:60
	v_ashrrev_i32_e32 v17, 7, v113
	v_and_b32_e32 v22, 0x7f, v113
	v_lshlrev_b32_e32 v23, 13, v17
	v_lshlrev_b32_e32 v28, 2, v22
	v_add3_u32 v113, 0, v28, v23
	s_mov_b64 s[0:1], -1
	s_and_b64 vcc, exec, s[18:19]
	s_waitcnt lgkmcnt(0)
	s_barrier
	s_cbranch_vccz .LBB0_739
	ds_read2st64_b32 v[30:31], v113 offset0:28 offset1:30
	s_mov_b64 s[0:1], 0
	s_waitcnt lgkmcnt(0)
	v_add_f32_e32 v29, 0, v31
	v_add_f32_e32 v119, v29, v30
	ds_read2st64_b32 v[30:31], v113 offset0:24 offset1:26
	ds_write2st64_b32 v113, v119, v29 offset0:28 offset1:30
	s_waitcnt lgkmcnt(1)
	v_add_f32_e32 v29, v119, v31
	v_add_f32_e32 v119, v29, v30
	ds_read2st64_b32 v[30:31], v113 offset0:20 offset1:22
	ds_write2st64_b32 v113, v119, v29 offset0:24 offset1:26
	s_waitcnt lgkmcnt(1)
	v_add_f32_e32 v29, v119, v31
	v_add_f32_e32 v119, v29, v30
	ds_read2st64_b32 v[30:31], v113 offset0:16 offset1:18
	ds_write2st64_b32 v113, v119, v29 offset0:20 offset1:22
	s_waitcnt lgkmcnt(1)
	v_add_f32_e32 v29, v119, v31
	v_add_f32_e32 v119, v29, v30
	ds_read2st64_b32 v[30:31], v113 offset0:12 offset1:14
	ds_write2st64_b32 v113, v119, v29 offset0:16 offset1:18
	s_waitcnt lgkmcnt(1)
	v_add_f32_e32 v29, v119, v31
	v_add_f32_e32 v119, v29, v30
	ds_read2st64_b32 v[30:31], v113 offset0:8 offset1:10
	ds_write2st64_b32 v113, v119, v29 offset0:12 offset1:14
	s_waitcnt lgkmcnt(1)
	v_add_f32_e32 v29, v119, v31
	v_add_f32_e32 v119, v29, v30
	ds_read2st64_b32 v[30:31], v113 offset0:4 offset1:6
	ds_write2st64_b32 v113, v119, v29 offset0:8 offset1:10
	s_waitcnt lgkmcnt(1)
	v_add_f32_e32 v29, v119, v31
	v_add_f32_e32 v119, v29, v30
	ds_read2st64_b32 v[30:31], v113 offset1:2
	ds_write2st64_b32 v113, v119, v29 offset0:4 offset1:6
	s_waitcnt lgkmcnt(1)
	v_add_f32_e32 v29, v119, v31
	v_add_f32_e32 v30, v29, v30
	ds_write2st64_b32 v113, v30, v29 offset1:2

.LBB0_1754:
	v_sub_f32_e32 v64, v64, v238
	v_exp_f32_e32 v154, v64
	v_sub_f32_e32 v64, v96, v238
	v_exp_f32_e32 v155, v64
	v_sub_f32_e32 v64, v65, v238
	v_exp_f32_e32 v156, v64
	v_sub_f32_e32 v64, v97, v238
	v_exp_f32_e32 v157, v64
	v_sub_f32_e32 v64, v66, v238
	v_exp_f32_e32 v158, v64
	v_sub_f32_e32 v64, v98, v238
	v_exp_f32_e32 v159, v64
	v_sub_f32_e32 v64, v67, v238
	v_exp_f32_e32 v160, v64
	v_sub_f32_e32 v64, v99, v238
	v_sub_f32_e32 v88, v88, v239
	v_exp_f32_e32 v161, v64
	v_sub_f32_e32 v64, v68, v238
	v_exp_f32_e32 v135, v88
	v_sub_f32_e32 v88, v89, v239
	v_exp_f32_e32 v162, v64
	v_sub_f32_e32 v64, v100, v238
	v_exp_f32_e32 v134, v88
	v_sub_f32_e32 v88, v118, v239
	v_exp_f32_e32 v163, v64
	v_sub_f32_e32 v64, v69, v238
	v_exp_f32_e32 v138, v88
	v_sub_f32_e32 v88, v119, v239
	v_exp_f32_e32 v164, v64
	v_sub_f32_e32 v64, v101, v238
	v_exp_f32_e32 v139, v88
	v_sub_f32_e32 v88, v116, v239
	v_exp_f32_e32 v165, v64
	v_sub_f32_e32 v64, v70, v238
	v_exp_f32_e32 v140, v88
	v_sub_f32_e32 v88, v117, v239
	v_exp_f32_e32 v166, v64
	v_sub_f32_e32 v64, v102, v238
	v_exp_f32_e32 v141, v88
	v_sub_f32_e32 v88, v114, v239
	v_exp_f32_e32 v167, v64
	v_sub_f32_e32 v64, v71, v238
	v_exp_f32_e32 v142, v88
	v_sub_f32_e32 v88, v115, v239
	v_exp_f32_e32 v168, v64
	v_sub_f32_e32 v64, v103, v238
	v_exp_f32_e32 v143, v88
	v_sub_f32_e32 v88, v112, v239
	v_exp_f32_e32 v169, v64
	v_sub_f32_e32 v64, v72, v238
	v_exp_f32_e32 v144, v88
	v_sub_f32_e32 v88, v113, v239
	v_exp_f32_e32 v113, v64
	v_sub_f32_e32 v64, v104, v238
	v_exp_f32_e32 v115, v64
	v_sub_f32_e32 v64, v73, v238
	v_exp_f32_e32 v112, v64
	v_sub_f32_e32 v64, v105, v238
	v_exp_f32_e32 v114, v64
	v_sub_f32_e32 v64, v74, v238
	v_exp_f32_e32 v105, v64
	v_sub_f32_e32 v64, v106, v238
	v_exp_f32_e32 v117, v64
	v_sub_f32_e32 v64, v75, v238
	v_exp_f32_e32 v104, v64
	v_lshlrev_b32_e32 v64, 6, v211
	v_sub_u32_e32 v64, v128, v64
	v_sub_f32_e32 v69, v107, v238
	v_add_u32_e32 v68, v64, v130
	v_exp_f32_e32 v116, v69
	v_sub_f32_e32 v69, v76, v238
	v_add_u32_e32 v98, 0x8800, v68
	v_exp_f32_e32 v107, v69
	v_sub_f32_e32 v69, v108, v238
	v_add_u32_e32 v100, 0x9800, v68
	ds_read2_b64 v[64:67], v98 offset0:128 offset1:130
	v_exp_f32_e32 v119, v69
	ds_read2_b64 v[68:71], v100 offset0:192 offset1:194
	v_sub_f32_e32 v72, v77, v238
	v_exp_f32_e32 v106, v72
	v_sub_f32_e32 v72, v109, v238
	v_exp_f32_e32 v118, v72
	v_sub_f32_e32 v72, v78, v238
	v_exp_f32_e32 v109, v72
	v_sub_f32_e32 v72, v110, v238
	v_sub_f32_e32 v86, v86, v239
	v_sub_f32_e32 v84, v84, v239
	v_sub_f32_e32 v82, v82, v239
	v_sub_f32_e32 v80, v80, v239
	v_exp_f32_e32 v137, v72
	v_sub_f32_e32 v72, v79, v238
	v_exp_f32_e32 v146, v86
	v_sub_f32_e32 v86, v87, v239
	v_exp_f32_e32 v148, v84
	v_sub_f32_e32 v84, v85, v239
	v_exp_f32_e32 v150, v82
	v_sub_f32_e32 v82, v83, v239
	v_exp_f32_e32 v152, v80
	v_sub_f32_e32 v80, v81, v239
	v_exp_f32_e32 v108, v72
	v_cvt_pk_bf16_f32 v72, v154, v156
	v_cvt_pk_bf16_f32 v73, v158, v160
	v_cvt_pk_bf16_f32 v74, v162, v164
	v_cvt_pk_bf16_f32 v75, v166, v168
	ds_read2_b64 v[76:79], v98 offset0:132 offset1:134
	v_exp_f32_e32 v147, v86
	v_exp_f32_e32 v149, v84
	v_exp_f32_e32 v151, v82
	v_exp_f32_e32 v153, v80
	s_waitcnt lgkmcnt(2)
	v_mfma_f32_32x32x16_bf16 v[16:31], v[64:67], v[72:75], v[16:31]
	v_cvt_pk_bf16_f32 v83, v146, v147
	v_cvt_pk_bf16_f32 v82, v148, v149
	v_cvt_pk_bf16_f32 v81, v150, v151
	v_cvt_pk_bf16_f32 v80, v152, v153
	v_pk_mov_b32 v[84:85], v[112:113], v[112:113] op_sel:[1,0]
	v_pk_mov_b32 v[86:87], v[104:105], v[104:105] op_sel:[1,0]
	v_cvt_pk_bf16_f32 v84, v84, v85
	s_waitcnt lgkmcnt(1)
	v_mfma_f32_32x32x16_bf16 v[0:15], v[68:71], v[72:75], v[0:15]
	v_cvt_pk_bf16_f32 v85, v86, v87
	v_pk_mov_b32 v[86:87], v[106:107], v[106:107] op_sel:[1,0]
	v_pk_mov_b32 v[96:97], v[108:109], v[108:109] op_sel:[1,0]
	v_cvt_pk_bf16_f32 v86, v86, v87
	v_cvt_pk_bf16_f32 v87, v96, v97
	v_add_f32_e32 v110, v154, v155
	v_add_f32_e32 v110, 0, v110
	v_mfma_f32_32x32x16_bf16 v[32:47], v[64:67], v[80:83], v[32:47]
	v_sub_f32_e32 v64, v111, v238
	v_add_f32_e32 v111, v156, v157
	v_add_f32_e32 v110, v111, v110
	v_add_f32_e32 v111, v158, v159
	v_exp_f32_e32 v136, v64
	v_cvt_pk_bf16_f32 v64, v155, v157
	v_cvt_pk_bf16_f32 v65, v159, v161
	v_mfma_f32_32x32x16_bf16 v[48:63], v[68:71], v[80:83], v[48:63]
	ds_read2_b64 v[68:71], v100 offset0:196 offset1:198
	ds_read2_b64 v[72:75], v98 offset0:136 offset1:138
	ds_read2_b64 v[80:83], v100 offset0:200 offset1:202
	v_cvt_pk_bf16_f32 v66, v163, v165
	v_cvt_pk_bf16_f32 v67, v167, v169
	v_sub_f32_e32 v126, v126, v239
	v_sub_f32_e32 v124, v124, v239
	v_sub_f32_e32 v122, v122, v239
	v_sub_f32_e32 v120, v120, v239
	s_waitcnt lgkmcnt(3)
	v_mfma_f32_32x32x16_bf16 v[16:31], v[76:79], v[84:87], v[16:31]
	v_sub_f32_e32 v94, v94, v239
	v_sub_f32_e32 v92, v92, v239
	v_sub_f32_e32 v90, v90, v239
	v_exp_f32_e32 v133, v126
	v_sub_f32_e32 v126, v127, v239
	v_exp_f32_e32 v127, v124
	v_sub_f32_e32 v124, v125, v239
	s_waitcnt lgkmcnt(2)
	v_mfma_f32_32x32x16_bf16 v[0:15], v[68:71], v[84:87], v[0:15]
	v_add_f32_e32 v84, v111, v110
	v_add_f32_e32 v85, v160, v161
	v_add_f32_e32 v84, v85, v84
	v_add_f32_e32 v85, v162, v163
	v_add_f32_e32 v84, v85, v84
	v_add_f32_e32 v85, v164, v165
	v_add_f32_e32 v84, v85, v84
	v_add_f32_e32 v85, v166, v167
	v_add_f32_e32 v84, v85, v84
	v_add_f32_e32 v85, v168, v169
	s_waitcnt lgkmcnt(1)
	v_mfma_f32_32x32x16_bf16 v[16:31], v[72:75], v[64:67], v[16:31]
	v_add_f32_e32 v86, v85, v84
	v_pk_mov_b32 v[84:85], v[114:115], v[114:115] op_sel:[1,0]
	v_pk_add_f32 v[110:111], v[112:113], v[114:115]
	v_cvt_pk_bf16_f32 v84, v84, v85
	v_exp_f32_e32 v125, v122
	v_sub_f32_e32 v122, v123, v239
	v_exp_f32_e32 v123, v120
	s_waitcnt lgkmcnt(0)
	v_mfma_f32_32x32x16_bf16 v[0:15], v[80:83], v[64:67], v[0:15]
	v_pk_mov_b32 v[64:65], v[116:117], v[116:117] op_sel:[1,0]
	v_add_f32_e32 v66, v111, v86
	v_cvt_pk_bf16_f32 v85, v64, v65
	v_pk_mov_b32 v[64:65], v[118:119], v[118:119] op_sel:[1,0]
	v_add_f32_e32 v66, v110, v66
	v_cvt_pk_bf16_f32 v86, v64, v65
	v_pk_mov_b32 v[64:65], v[136:137], v[136:137] op_sel:[1,0]
	v_sub_f32_e32 v120, v121, v239
	v_cvt_pk_bf16_f32 v87, v64, v65
	v_pk_add_f32 v[64:65], v[104:105], v[116:117]
	v_exp_f32_e32 v121, v94
	v_sub_f32_e32 v94, v95, v239
	v_exp_f32_e32 v95, v92
	v_sub_f32_e32 v92, v93, v239
	v_exp_f32_e32 v93, v90
	v_sub_f32_e32 v90, v91, v239
	v_exp_f32_e32 v145, v88
	v_add_f32_e32 v65, v65, v66
	v_exp_f32_e32 v132, v126
	v_exp_f32_e32 v126, v124
	v_exp_f32_e32 v124, v122
	v_exp_f32_e32 v122, v120
	v_exp_f32_e32 v120, v94
	v_exp_f32_e32 v94, v92
	v_exp_f32_e32 v92, v90
	ds_read2_b64 v[96:99], v98 offset0:140 offset1:142
	ds_read2_b64 v[100:103], v100 offset0:204 offset1:206
	v_add_f32_e32 v66, v64, v65
	v_pk_add_f32 v[64:65], v[106:107], v[118:119]
	s_waitcnt lgkmcnt(1)
	v_mfma_f32_32x32x16_bf16 v[16:31], v[96:99], v[84:87], v[16:31]
	v_add_f32_e32 v65, v65, v66
	v_add_f32_e32 v104, v64, v65
	v_add_f32_e32 v64, v144, v152
	v_add_f32_e32 v64, 0, v64
	v_add_f32_e32 v65, v145, v153
	v_add_f32_e32 v105, v65, v64
	v_pk_mov_b32 v[64:65], v[134:135], v[134:135] op_sel:[1,0]
	v_pk_mov_b32 v[66:67], v[92:93], v[92:93] op_sel:[1,0]
	s_waitcnt lgkmcnt(0)
	v_mfma_f32_32x32x16_bf16 v[0:15], v[100:103], v[84:87], v[0:15]
	v_cvt_pk_bf16_f32 v64, v64, v65
	v_cvt_pk_bf16_f32 v65, v66, v67
	v_pk_mov_b32 v[66:67], v[94:95], v[94:95] op_sel:[1,0]
	v_pk_mov_b32 v[86:87], v[120:121], v[120:121] op_sel:[1,0]
	v_add_f32_e32 v106, v142, v150
	v_cvt_pk_bf16_f32 v66, v66, v67
	v_cvt_pk_bf16_f32 v67, v86, v87
	v_cvt_pk_bf16_f32 v91, v138, v139
	v_cvt_pk_bf16_f32 v90, v140, v141
	v_mfma_f32_32x32x16_bf16 v[32:47], v[76:79], v[64:67], v[32:47]
	v_add_f32_e32 v76, v106, v105
	v_add_f32_e32 v77, v143, v151
	v_add_f32_e32 v76, v77, v76
	v_add_f32_e32 v77, v140, v148
	v_add_f32_e32 v76, v77, v76
	v_add_f32_e32 v77, v141, v149
	v_add_f32_e32 v76, v77, v76
	v_mfma_f32_32x32x16_bf16 v[48:63], v[68:71], v[64:67], v[48:63]
	v_add_f32_e32 v64, v138, v146
	v_add_f32_e32 v64, v64, v76
	v_add_f32_e32 v65, v139, v147
	v_add_f32_e32 v68, v65, v64
	v_pk_mov_b32 v[64:65], v[122:123], v[122:123] op_sel:[1,0]
	v_pk_add_f32 v[66:67], v[122:123], v[134:135]
	v_cvt_pk_bf16_f32 v64, v64, v65
	v_add_f32_e32 v65, v67, v68
	v_add_f32_e32 v68, v66, v65
	v_pk_mov_b32 v[66:67], v[124:125], v[124:125] op_sel:[1,0]
	v_cvt_pk_bf16_f32 v89, v142, v143
	v_cvt_pk_bf16_f32 v65, v66, v67
	v_pk_add_f32 v[66:67], v[124:125], v[92:93]
	v_cvt_pk_bf16_f32 v88, v144, v145
	v_add_f32_e32 v67, v67, v68
	v_add_f32_e32 v70, v66, v67
	v_pk_mov_b32 v[66:67], v[126:127], v[126:127] op_sel:[1,0]
	v_pk_add_f32 v[68:69], v[126:127], v[94:95]
	v_cvt_pk_bf16_f32 v66, v66, v67
	v_add_f32_e32 v67, v69, v70
	v_add_f32_e32 v70, v68, v67
	v_pk_mov_b32 v[68:69], v[132:133], v[132:133] op_sel:[1,0]
	s_lshl_b32 s2, s0, 10
	v_cvt_pk_bf16_f32 v67, v68, v69
	v_pk_add_f32 v[68:69], v[132:133], v[120:121]
	v_mfma_f32_32x32x16_bf16 v[32:47], v[72:75], v[88:91], v[32:47]
	v_add_f32_e32 v69, v69, v70
	v_cmp_lt_i32_e32 vcc, v223, v222
	s_and_b32 s2, s2, 0xffffe000
	v_add_f32_e32 v68, v68, v69
	v_cndmask_b32_e32 v69, v205, v223, vcc
	s_or_b32 s2, s2, s1
	v_add_f32_e32 v68, v193, v68
	v_mfma_f32_32x32x16_bf16 v[48:63], v[80:83], v[88:91], v[48:63]
	v_lshlrev_b32_e32 v69, 2, v69
	s_ashr_i32 s3, s2, 31
	ds_bpermute_b32 v70, v69, v68
	s_lshl_b64 s[2:3], s[2:3], 11
	v_readlane_b32 s8, v251, 3
	v_readlane_b32 s9, v251, 4
	s_add_u32 s1, s8, s2
	s_addc_u32 s2, s9, s3
	s_lshl_b32 s0, s0, 7
	s_and_b32 s0, s0, 0x380
	s_add_u32 s0, s1, s0
	v_mfma_f32_32x32x16_bf16 v[32:47], v[96:99], v[64:67], v[32:47]
	s_addc_u32 s1, s2, 0
	v_add_f32_e64 v84, v108, v136
	v_add_f32_e64 v85, v109, v137
	s_waitcnt lgkmcnt(0)
	v_add_f32_e32 v71, v85, v104
	v_add_f32_e32 v71, v84, v71
	v_add_f32_e32 v71, v131, v71
	v_mov_b32_e32 v131, v129
	v_mfma_f32_32x32x16_bf16 v[48:63], v[100:103], v[64:67], v[48:63]
	v_add_f32_e32 v64, v68, v70
	v_rcp_f32_e32 v66, v64
	s_barrier
	v_mul_f32_e32 v64, 1.0, v66
	v_lshlrev_b64 v[66:67], 11, v[208:209]
	v_pk_mul_f32 v[32:33], v[32:33], v[64:65] op_sel_hi:[1,0]
	v_pk_mul_f32 v[34:35], v[34:35], v[64:65] op_sel_hi:[1,0]
	v_lshl_add_u64 v[66:67], s[0:1], 0, v[66:67]
	v_cvt_pk_bf16_f32 v32, v32, v33
	v_cvt_pk_bf16_f32 v33, v34, v35
	s_nop 1
	v_pk_mul_f32 v[34:35], v[48:49], v[64:65] op_sel_hi:[1,0]
	v_pk_mul_f32 v[48:49], v[50:51], v[64:65] op_sel_hi:[1,0]
	v_lshl_add_u64 v[66:67], v[66:67], 0, v[130:131]
	v_cvt_pk_bf16_f32 v34, v34, v35
	v_cvt_pk_bf16_f32 v35, v48, v49
	global_store_dwordx2 v[66:67], v[32:33], off offset:1024
	global_store_dwordx2 v[66:67], v[34:35], off offset:1088
	v_pk_mul_f32 v[34:35], v[38:39], v[64:65] op_sel_hi:[1,0]
	ds_bpermute_b32 v38, v69, v71
	v_pk_mul_f32 v[32:33], v[36:37], v[64:65] op_sel_hi:[1,0]
	v_pk_mul_f32 v[36:37], v[54:55], v[64:65] op_sel_hi:[1,0]
	v_cvt_pk_bf16_f32 v32, v32, v33
	v_cvt_pk_bf16_f32 v33, v34, v35
	v_pk_mul_f32 v[34:35], v[52:53], v[64:65] op_sel_hi:[1,0]
	s_waitcnt lgkmcnt(0)
	v_add_f32_e32 v38, v71, v38
	v_cvt_pk_bf16_f32 v34, v34, v35
	v_cvt_pk_bf16_f32 v35, v36, v37
	global_store_dwordx2 v[66:67], v[32:33], off offset:1040
	global_store_dwordx2 v[66:67], v[34:35], off offset:1104
	v_pk_mul_f32 v[32:33], v[40:41], v[64:65] op_sel_hi:[1,0]
	v_pk_mul_f32 v[34:35], v[42:43], v[64:65] op_sel_hi:[1,0]
	v_cvt_pk_bf16_f32 v32, v32, v33
	v_cvt_pk_bf16_f32 v33, v34, v35
	v_pk_mul_f32 v[34:35], v[56:57], v[64:65] op_sel_hi:[1,0]
	v_pk_mul_f32 v[36:37], v[58:59], v[64:65] op_sel_hi:[1,0]
	v_rcp_f32_e32 v40, v38
	v_cvt_pk_bf16_f32 v34, v34, v35
	v_cvt_pk_bf16_f32 v35, v36, v37
	global_store_dwordx2 v[66:67], v[32:33], off offset:1056
	global_store_dwordx2 v[66:67], v[34:35], off offset:1120
	v_pk_mul_f32 v[32:33], v[44:45], v[64:65] op_sel_hi:[1,0]
	v_pk_mul_f32 v[34:35], v[46:47], v[64:65] op_sel_hi:[1,0]
	v_cvt_pk_bf16_f32 v32, v32, v33
	v_cvt_pk_bf16_f32 v33, v34, v35
	v_pk_mul_f32 v[34:35], v[60:61], v[64:65] op_sel_hi:[1,0]
	v_pk_mul_f32 v[36:37], v[62:63], v[64:65] op_sel_hi:[1,0]
	v_cvt_pk_bf16_f32 v34, v34, v35
	v_cvt_pk_bf16_f32 v35, v36, v37
	global_store_dwordx2 v[66:67], v[32:33], off offset:1072
	global_store_dwordx2 v[66:67], v[34:35], off offset:1136
	v_or_b32_e32 v34, 32, v206
	v_ashrrev_i32_e32 v35, 31, v34
	v_mul_f32_e32 v32, 1.0, v40
	v_lshlrev_b64 v[34:35], 11, v[34:35]
	v_lshl_add_u64 v[34:35], s[0:1], 0, v[34:35]
	v_pk_mul_f32 v[16:17], v[16:17], v[32:33] op_sel_hi:[1,0]
	v_pk_mul_f32 v[18:19], v[18:19], v[32:33] op_sel_hi:[1,0]
	v_pk_mul_f32 v[0:1], v[0:1], v[32:33] op_sel_hi:[1,0]
	v_pk_mul_f32 v[2:3], v[2:3], v[32:33] op_sel_hi:[1,0]
	v_lshl_add_u64 v[34:35], v[34:35], 0, v[130:131]
	v_cvt_pk_bf16_f32 v16, v16, v17
	v_cvt_pk_bf16_f32 v17, v18, v19
	v_cvt_pk_bf16_f32 v0, v0, v1
	v_cvt_pk_bf16_f32 v1, v2, v3
	global_store_dwordx2 v[34:35], v[16:17], off offset:1024
	global_store_dwordx2 v[34:35], v[0:1], off offset:1088
	v_pk_mul_f32 v[0:1], v[20:21], v[32:33] op_sel_hi:[1,0]
	v_pk_mul_f32 v[2:3], v[22:23], v[32:33] op_sel_hi:[1,0]
	v_cvt_pk_bf16_f32 v0, v0, v1
	v_cvt_pk_bf16_f32 v1, v2, v3
	v_pk_mul_f32 v[2:3], v[4:5], v[32:33] op_sel_hi:[1,0]
	v_pk_mul_f32 v[4:5], v[6:7], v[32:33] op_sel_hi:[1,0]
	v_cvt_pk_bf16_f32 v2, v2, v3
	v_cvt_pk_bf16_f32 v3, v4, v5
	global_store_dwordx2 v[34:35], v[0:1], off offset:1040
	global_store_dwordx2 v[34:35], v[2:3], off offset:1104
	v_pk_mul_f32 v[0:1], v[24:25], v[32:33] op_sel_hi:[1,0]
	v_pk_mul_f32 v[2:3], v[26:27], v[32:33] op_sel_hi:[1,0]
	v_cvt_pk_bf16_f32 v0, v0, v1
	v_cvt_pk_bf16_f32 v1, v2, v3
	v_pk_mul_f32 v[2:3], v[8:9], v[32:33] op_sel_hi:[1,0]
	v_pk_mul_f32 v[4:5], v[10:11], v[32:33] op_sel_hi:[1,0]
	v_cvt_pk_bf16_f32 v2, v2, v3
	v_cvt_pk_bf16_f32 v3, v4, v5
	global_store_dwordx2 v[34:35], v[0:1], off offset:1056
	global_store_dwordx2 v[34:35], v[2:3], off offset:1120
	v_pk_mul_f32 v[0:1], v[28:29], v[32:33] op_sel_hi:[1,0]
	v_pk_mul_f32 v[2:3], v[30:31], v[32:33] op_sel_hi:[1,0]
	v_cvt_pk_bf16_f32 v0, v0, v1
	v_cvt_pk_bf16_f32 v1, v2, v3
	v_pk_mul_f32 v[2:3], v[12:13], v[32:33] op_sel_hi:[1,0]
	v_pk_mul_f32 v[4:5], v[14:15], v[32:33] op_sel_hi:[1,0]
	v_cvt_pk_bf16_f32 v2, v2, v3
	v_cvt_pk_bf16_f32 v3, v4, v5
	global_store_dwordx2 v[34:35], v[0:1], off offset:1072
	global_store_dwordx2 v[34:35], v[2:3], off offset:1136

.LBB0_1886:
	s_or_b64 exec, exec, s[0:1]
	s_bitcmp1_b32 s2, 0
	s_cselect_b32 s1, 0, 0x5800
	s_cselect_b32 s0, 0x5800, 0
	s_add_i32 s1, s1, 0
	v_add3_u32 v121, s1, v117, v104
	global_load_dwordx4 v[92:95], v[106:107], off
	ds_read_b128 v[32:35], v121 offset:6656
	ds_read_b128 v[36:39], v121
	ds_read_b128 v[122:125], v121 offset:32
	ds_read_b128 v[130:133], v121 offset:6688
	s_waitcnt lgkmcnt(0)
	v_mfma_f32_32x32x16_bf16 v[48:63], v[36:39], v[84:87], 0
	v_add3_u32 v126, s1, v119, v102
	v_add_u32_e32 v127, 0x3000, v126
	v_add_u32_e32 v126, 0x4000, v126
	s_add_i32 s3, s0, 0
	v_mfma_f32_32x32x16_bf16 v[32:47], v[32:35], v[84:87], 0
	v_mfma_f32_32x32x16_bf16 v[48:63], v[122:125], v[80:83], v[48:63]
	v_mfma_f32_32x32x16_bf16 v[32:47], v[130:133], v[80:83], v[32:47]
	ds_read_b128 v[122:125], v121 offset:64
	ds_read_b128 v[130:133], v121 offset:6720
	s_waitcnt lgkmcnt(0)
	v_mfma_f32_32x32x16_bf16 v[48:63], v[122:125], v[76:79], v[48:63]
	v_mfma_f32_32x32x16_bf16 v[32:47], v[130:133], v[76:79], v[32:47]
	ds_read_b128 v[122:125], v121 offset:96
	ds_read_b128 v[130:133], v121 offset:6752
	s_waitcnt lgkmcnt(0)
	v_mfma_f32_32x32x16_bf16 v[48:63], v[122:125], v[72:75], v[48:63]
	v_mfma_f32_32x32x16_bf16 v[32:47], v[130:133], v[72:75], v[32:47]
	ds_read_b128 v[122:125], v121 offset:128
	ds_read_b128 v[130:133], v121 offset:6784
	s_waitcnt lgkmcnt(0)
	v_mfma_f32_32x32x16_bf16 v[48:63], v[122:125], v[68:71], v[48:63]
	v_mfma_f32_32x32x16_bf16 v[32:47], v[130:133], v[68:71], v[32:47]
	ds_read_b128 v[122:125], v121 offset:160
	ds_read_b128 v[130:133], v121 offset:6816
	s_waitcnt lgkmcnt(0)
	v_mfma_f32_32x32x16_bf16 v[48:63], v[122:125], v[64:67], v[48:63]
	v_mfma_f32_32x32x16_bf16 v[32:47], v[130:133], v[64:67], v[32:47]
	s_nop 10
	v_max_f32_e32 v122, v48, v48
	ds_read2_b64 v[130:133], v127 offset0:128 offset1:130
	ds_read2_b64 v[134:137], v127 offset0:132 offset1:134
	v_max_f32_e32 v121, v32, v32
	v_max_f32_e32 v121, v122, v121
	v_max3_f32 v121, v121, v49, v33
	v_max3_f32 v121, v121, v50, v34
	v_max3_f32 v121, v121, v51, v35
	v_max3_f32 v121, v121, v52, v36
	v_max3_f32 v121, v121, v53, v37
	v_max3_f32 v121, v121, v54, v38
	v_max3_f32 v121, v121, v55, v39
	v_max3_f32 v121, v121, v56, v40
	v_max3_f32 v121, v121, v57, v41
	v_max3_f32 v121, v121, v58, v42
	v_max3_f32 v121, v121, v59, v43
	v_max3_f32 v121, v121, v60, v44
	v_max3_f32 v121, v121, v61, v45
	v_max3_f32 v121, v121, v62, v46
	v_max3_f32 v121, v121, v63, v47
	ds_bpermute_b32 v122, v103, v121
	s_waitcnt lgkmcnt(0)
	v_max3_f32 v121, v112, v121, v122
	v_sub_f32_e32 v112, v112, v121
	v_sub_f32_e32 v48, v48, v121
	v_sub_f32_e32 v49, v49, v121
	v_sub_f32_e32 v50, v50, v121
	v_sub_f32_e32 v51, v51, v121
	v_sub_f32_e32 v52, v52, v121
	v_sub_f32_e32 v53, v53, v121
	v_sub_f32_e32 v54, v54, v121
	v_sub_f32_e32 v55, v55, v121
	v_exp_f32_e32 v112, v112
	v_exp_f32_e32 v48, v48
	v_exp_f32_e32 v49, v49
	v_exp_f32_e32 v50, v50
	v_exp_f32_e32 v51, v51
	v_exp_f32_e32 v52, v52
	v_exp_f32_e32 v53, v53
	v_exp_f32_e32 v54, v54
	v_exp_f32_e32 v55, v55
	v_pk_mul_f32 v[30:31], v[30:31], v[112:113] op_sel_hi:[1,0]
	v_pk_mul_f32 v[28:29], v[28:29], v[112:113] op_sel_hi:[1,0]
	v_pk_mul_f32 v[26:27], v[26:27], v[112:113] op_sel_hi:[1,0]
	v_pk_mul_f32 v[24:25], v[24:25], v[112:113] op_sel_hi:[1,0]
	v_pk_mul_f32 v[22:23], v[22:23], v[112:113] op_sel_hi:[1,0]
	v_pk_mul_f32 v[20:21], v[20:21], v[112:113] op_sel_hi:[1,0]
	v_pk_mul_f32 v[18:19], v[18:19], v[112:113] op_sel_hi:[1,0]
	v_pk_mul_f32 v[16:17], v[16:17], v[112:113] op_sel_hi:[1,0]
	v_cvt_pk_bf16_f32 v122, v48, v49
	v_cvt_pk_bf16_f32 v123, v50, v51
	v_cvt_pk_bf16_f32 v124, v52, v53
	v_cvt_pk_bf16_f32 v125, v54, v55
	v_pk_mul_f32 v[14:15], v[14:15], v[112:113] op_sel_hi:[1,0]
	v_pk_mul_f32 v[12:13], v[12:13], v[112:113] op_sel_hi:[1,0]
	v_mfma_f32_32x32x16_bf16 v[16:31], v[130:133], v[122:125], v[16:31]
	ds_read2_b64 v[130:133], v126 offset0:192 offset1:194
	v_mul_f32_e64 v10, v10, v112
	v_mul_f32_e64 v11, v11, v112
	v_mul_f32_e64 v8, v8, v112
	v_mul_f32_e64 v9, v9, v112
	v_pk_mul_f32 v[6:7], v[6:7], v[112:113] op_sel_hi:[1,0]
	v_pk_mul_f32 v[4:5], v[4:5], v[112:113] op_sel_hi:[1,0]
	v_pk_mul_f32 v[2:3], v[2:3], v[112:113] op_sel_hi:[1,0]
	v_pk_mul_f32 v[0:1], v[0:1], v[112:113] op_sel_hi:[1,0]
	v_sub_f32_e32 v56, v56, v121
	v_sub_f32_e32 v57, v57, v121
	s_waitcnt lgkmcnt(0)
	v_mfma_f32_32x32x16_bf16 v[0:15], v[130:133], v[122:125], v[0:15]
	ds_read2_b64 v[130:133], v126 offset0:196 offset1:198
	v_sub_f32_e32 v58, v58, v121
	v_sub_f32_e32 v59, v59, v121
	v_sub_f32_e32 v60, v60, v121
	v_sub_f32_e32 v61, v61, v121
	v_sub_f32_e32 v62, v62, v121
	v_sub_f32_e32 v63, v63, v121
	v_exp_f32_e32 v56, v56
	v_exp_f32_e32 v57, v57
	v_exp_f32_e32 v58, v58
	v_exp_f32_e32 v59, v59
	v_exp_f32_e32 v60, v60
	v_exp_f32_e32 v61, v61
	v_exp_f32_e32 v62, v62
	v_exp_f32_e32 v63, v63
	v_cvt_pk_bf16_f32 v122, v56, v57
	v_cvt_pk_bf16_f32 v123, v58, v59
	v_cvt_pk_bf16_f32 v124, v60, v61
	v_cvt_pk_bf16_f32 v125, v62, v63
	v_sub_f32_e32 v32, v32, v121
	v_sub_f32_e32 v33, v33, v121
	s_waitcnt lgkmcnt(0)
	v_mfma_f32_32x32x16_bf16 v[0:15], v[130:133], v[122:125], v[0:15]
	ds_read2_b64 v[130:133], v127 offset0:136 offset1:138
	v_sub_f32_e32 v34, v34, v121
	v_sub_f32_e32 v35, v35, v121
	v_sub_f32_e32 v36, v36, v121
	v_sub_f32_e32 v37, v37, v121
	v_sub_f32_e32 v38, v38, v121
	v_sub_f32_e32 v39, v39, v121
	v_mfma_f32_32x32x16_bf16 v[16:31], v[134:137], v[122:125], v[16:31]
	v_exp_f32_e32 v32, v32
	v_exp_f32_e32 v33, v33
	v_exp_f32_e32 v34, v34
	v_exp_f32_e32 v35, v35
	v_exp_f32_e32 v36, v36
	v_exp_f32_e32 v37, v37
	v_exp_f32_e32 v38, v38
	v_exp_f32_e32 v39, v39
	v_cvt_pk_bf16_f32 v122, v32, v33
	v_cvt_pk_bf16_f32 v123, v34, v35
	v_cvt_pk_bf16_f32 v124, v36, v37
	v_cvt_pk_bf16_f32 v125, v38, v39
	v_sub_f32_e32 v40, v40, v121
	v_sub_f32_e32 v41, v41, v121
	s_waitcnt lgkmcnt(0)
	v_mfma_f32_32x32x16_bf16 v[16:31], v[130:133], v[122:125], v[16:31]
	ds_read2_b64 v[130:133], v126 offset0:200 offset1:202
	v_sub_f32_e32 v42, v42, v121
	v_sub_f32_e32 v43, v43, v121
	v_sub_f32_e32 v44, v44, v121
	v_sub_f32_e32 v45, v45, v121
	v_sub_f32_e32 v46, v46, v121
	v_sub_f32_e32 v47, v47, v121
	s_waitcnt lgkmcnt(0)
	v_mfma_f32_32x32x16_bf16 v[0:15], v[130:133], v[122:125], v[0:15]
	ds_read2_b64 v[130:133], v127 offset0:140 offset1:142
	v_exp_f32_e32 v40, v40
	v_exp_f32_e32 v41, v41
	v_exp_f32_e32 v42, v42
	v_exp_f32_e32 v43, v43
	v_exp_f32_e32 v44, v44
	v_exp_f32_e32 v45, v45
	v_exp_f32_e32 v46, v46
	v_exp_f32_e32 v47, v47
	v_cvt_pk_bf16_f32 v122, v40, v41
	v_cvt_pk_bf16_f32 v123, v42, v43
	v_cvt_pk_bf16_f32 v124, v44, v45
	v_cvt_pk_bf16_f32 v125, v46, v47
	s_waitcnt lgkmcnt(0)
	s_nop 0
	v_mfma_f32_32x32x16_bf16 v[16:31], v[130:133], v[122:125], v[16:31]
	ds_read2_b64 v[130:133], v126 offset0:204 offset1:206
	s_waitcnt lgkmcnt(0)
	v_mfma_f32_32x32x16_bf16 v[0:15], v[130:133], v[122:125], v[0:15]
	v_add3_u32 v122, s3, v113, v114
	s_waitcnt vmcnt(0)
	ds_write_b128 v122, v[96:99]
	s_and_saveexec_b64 s[0:1], vcc
	v_add3_u32 v96, s3, v116, v115
	ds_write_b128 v96, v[88:91]
	s_or_b64 exec, exec, s[0:1]
	v_add_f32_e32 v32, v48, v32
	v_add_f32_e32 v33, v49, v33
	v_add_f32_e32 v32, 0, v32
	v_add_f32_e32 v34, v50, v34
	v_add_f32_e32 v32, v33, v32
	v_add_f32_e32 v35, v51, v35
	v_add_f32_e32 v32, v34, v32
	v_add_f32_e32 v36, v52, v36
	v_add_f32_e32 v32, v35, v32
	v_add_f32_e32 v37, v53, v37
	v_add_f32_e32 v32, v36, v32
	v_add_f32_e32 v38, v54, v38
	v_add_f32_e32 v32, v37, v32
	v_add_f32_e32 v39, v55, v39
	v_add_f32_e32 v32, v38, v32
	v_add_f32_e32 v40, v56, v40
	v_add_f32_e32 v32, v39, v32
	v_add_f32_e32 v41, v57, v41
	v_add_f32_e32 v32, v40, v32
	v_add_f32_e32 v42, v58, v42
	v_add_f32_e32 v32, v41, v32
	v_add_f32_e32 v43, v59, v43
	v_add_f32_e32 v32, v42, v32
	v_add_f32_e32 v44, v60, v44
	v_add_f32_e32 v32, v43, v32
	v_add_f32_e32 v45, v61, v45
	v_add_f32_e32 v32, v44, v32
	v_add_f32_e32 v46, v62, v46
	v_add_f32_e32 v32, v45, v32
	v_add_f32_e32 v47, v63, v47
	v_add_f32_e32 v32, v46, v32
	v_add_f32_e32 v96, v47, v32
	s_add_i32 s2, s2, 1
	v_fmac_f32_e32 v96, v120, v112
	v_add3_u32 v32, s3, v118, v128
	v_lshl_add_u64 v[106:107], v[106:107], 0, s[24:25]
	v_lshl_add_u64 v[108:109], v[108:109], 0, s[16:17]
	s_cmp_lg_u32 s2, 4
	v_lshl_add_u64 v[110:111], v[110:111], 0, s[16:17]
	ds_write_b128 v32, v[92:95] offset:13312
	s_waitcnt lgkmcnt(0)
	s_barrier
	s_cbranch_scc1 .LBB0_1884
	v_add_u32_e32 v88, 0, v117
	v_add_u32_e32 v89, v88, v104
	ds_read_b128 v[32:35], v89 offset:22528
	ds_read_b128 v[48:51], v89 offset:29184
	s_lshl_b32 s0, s20, 5
	s_and_b32 s0, s0, 0x7fffff00
	s_add_i32 s26, s0, 0x4000
	s_lshl_b64 s[0:1], s[26:27], 11
	v_readlane_b32 s2, v251, 3
	v_readlane_b32 s3, v251, 4
	s_add_u32 s0, s2, s0
	s_waitcnt lgkmcnt(1)
	v_mfma_f32_32x32x16_bf16 v[32:47], v[32:35], v[84:87], 0
	s_addc_u32 s1, s3, s1
	s_lshl_b32 s2, s66, 7
	s_and_b32 s2, s2, 0x380
	s_add_u32 s0, s0, s2
	s_addc_u32 s1, s1, 0
	s_waitcnt lgkmcnt(0)
	v_mfma_f32_32x32x16_bf16 v[48:63], v[48:51], v[84:87], 0
	ds_read_b128 v[84:87], v89 offset:22560
	s_waitcnt lgkmcnt(0)
	v_mfma_f32_32x32x16_bf16 v[32:47], v[84:87], v[80:83], v[32:47]
	ds_read_b128 v[84:87], v89 offset:29216
	s_waitcnt lgkmcnt(0)
	v_mfma_f32_32x32x16_bf16 v[48:63], v[84:87], v[80:83], v[48:63]
	ds_read_b128 v[80:83], v89 offset:22592
	s_waitcnt lgkmcnt(0)
	v_mfma_f32_32x32x16_bf16 v[32:47], v[80:83], v[76:79], v[32:47]
	ds_read_b128 v[80:83], v89 offset:29248
	s_waitcnt lgkmcnt(0)
	v_mfma_f32_32x32x16_bf16 v[48:63], v[80:83], v[76:79], v[48:63]
	ds_read_b128 v[76:79], v89 offset:22624
	s_waitcnt lgkmcnt(0)
	v_mfma_f32_32x32x16_bf16 v[32:47], v[76:79], v[72:75], v[32:47]
	ds_read_b128 v[76:79], v89 offset:29280
	s_waitcnt lgkmcnt(0)
	v_mfma_f32_32x32x16_bf16 v[48:63], v[76:79], v[72:75], v[48:63]
	ds_read_b128 v[72:75], v89 offset:22656
	s_waitcnt lgkmcnt(0)
	v_mfma_f32_32x32x16_bf16 v[32:47], v[72:75], v[68:71], v[32:47]
	ds_read_b128 v[72:75], v89 offset:29312
	s_waitcnt lgkmcnt(0)
	v_mfma_f32_32x32x16_bf16 v[48:63], v[72:75], v[68:71], v[48:63]
	ds_read_b128 v[68:71], v89 offset:29344
	s_waitcnt lgkmcnt(0)
	v_mfma_f32_32x32x16_bf16 v[48:63], v[68:71], v[64:67], v[48:63]
	ds_read_b128 v[68:71], v89 offset:22688
	s_waitcnt lgkmcnt(0)
	v_mfma_f32_32x32x16_bf16 v[32:47], v[68:71], v[64:67], v[32:47]
	s_nop 8
	v_max_f32_e32 v72, v48, v48
	s_nop 1
	v_max_f32_e32 v64, v32, v32
	v_max_f32_e32 v64, v64, v72
	v_max3_f32 v64, v64, v33, v49
	v_max3_f32 v64, v64, v34, v50
	v_max3_f32 v64, v64, v35, v51
	v_max3_f32 v64, v64, v36, v52
	v_max3_f32 v64, v64, v37, v53
	v_max3_f32 v64, v64, v38, v54
	v_max3_f32 v64, v64, v39, v55
	v_max3_f32 v64, v64, v40, v56
	v_max3_f32 v64, v64, v41, v57
	v_max3_f32 v64, v64, v42, v58
	v_max3_f32 v64, v64, v43, v59
	v_max3_f32 v64, v64, v44, v60
	v_max3_f32 v64, v64, v45, v61
	v_max3_f32 v64, v64, v46, v62
	v_max3_f32 v64, v64, v47, v63
	ds_bpermute_b32 v65, v103, v64
	s_waitcnt lgkmcnt(0)
	v_max3_f32 v65, v121, v64, v65
	v_sub_f32_e32 v32, v32, v65
	v_exp_f32_e32 v82, v32
	v_sub_f32_e32 v32, v48, v65
	v_exp_f32_e32 v83, v32
	v_sub_f32_e32 v32, v33, v65
	v_exp_f32_e32 v84, v32
	v_sub_f32_e32 v32, v49, v65
	v_exp_f32_e32 v85, v32
	v_sub_f32_e32 v32, v34, v65
	v_exp_f32_e32 v86, v32
	v_sub_f32_e32 v32, v50, v65
	v_exp_f32_e32 v87, v32
	v_sub_f32_e32 v32, v35, v65
	v_exp_f32_e32 v89, v32
	v_sub_f32_e32 v32, v51, v65
	v_exp_f32_e32 v90, v32
	v_sub_f32_e32 v32, v36, v65
	v_exp_f32_e32 v91, v32
	v_sub_f32_e32 v32, v52, v65
	v_exp_f32_e32 v92, v32
	v_sub_f32_e32 v32, v37, v65
	v_exp_f32_e32 v93, v32
	v_sub_f32_e32 v32, v53, v65
	v_exp_f32_e32 v94, v32
	v_sub_f32_e32 v32, v38, v65
	v_exp_f32_e32 v95, v32
	v_sub_f32_e32 v32, v54, v65
	v_exp_f32_e32 v97, v32
	v_sub_f32_e32 v32, v39, v65
	v_exp_f32_e32 v98, v32
	v_sub_f32_e32 v32, v55, v65
	v_exp_f32_e32 v99, v32
	v_sub_f32_e32 v32, v40, v65
	v_exp_f32_e32 v51, v32
	v_sub_f32_e32 v32, v56, v65
	v_exp_f32_e32 v53, v32
	v_sub_f32_e32 v32, v41, v65
	v_exp_f32_e32 v50, v32
	v_sub_f32_e32 v32, v57, v65
	v_exp_f32_e32 v52, v32
	v_sub_f32_e32 v32, v42, v65
	v_exp_f32_e32 v41, v32
	v_sub_f32_e32 v32, v58, v65
	v_exp_f32_e32 v49, v32
	v_sub_f32_e32 v32, v43, v65
	v_exp_f32_e32 v40, v32
	v_sub_f32_e32 v32, v59, v65
	v_exp_f32_e32 v48, v32
	v_sub_f32_e32 v32, v44, v65
	v_exp_f32_e32 v37, v32
	v_sub_f32_e32 v32, v60, v65
	v_exp_f32_e32 v39, v32
	v_sub_f32_e32 v32, v45, v65
	v_exp_f32_e32 v36, v32
	v_sub_f32_e32 v32, v61, v65
	v_lshlrev_b32_e32 v42, 6, v105
	v_exp_f32_e32 v38, v32
	v_sub_f32_e32 v32, v46, v65
	v_sub_u32_e32 v42, v88, v42
	v_exp_f32_e32 v33, v32
	v_sub_f32_e32 v32, v62, v65
	v_add_u32_e32 v46, v42, v102
	v_exp_f32_e32 v35, v32
	v_sub_f32_e32 v32, v47, v65
	v_add_u32_e32 v47, 0x8800, v46
	ds_read2_b64 v[42:45], v47 offset0:128 offset1:130
	v_add_u32_e32 v46, 0x9800, v46
	ds_read2_b64 v[58:61], v46 offset0:192 offset1:194
	v_sub_f32_e32 v64, v121, v65
	v_exp_f32_e32 v64, v64
	v_cvt_pk_bf16_f32 v54, v82, v84
	v_cvt_pk_bf16_f32 v55, v86, v89
	v_cvt_pk_bf16_f32 v56, v91, v93
	v_pk_mul_f32 v[30:31], v[30:31], v[64:65] op_sel_hi:[1,0]
	v_pk_mul_f32 v[28:29], v[28:29], v[64:65] op_sel_hi:[1,0]
	v_pk_mul_f32 v[26:27], v[26:27], v[64:65] op_sel_hi:[1,0]
	v_pk_mul_f32 v[24:25], v[24:25], v[64:65] op_sel_hi:[1,0]
	v_pk_mul_f32 v[22:23], v[22:23], v[64:65] op_sel_hi:[1,0]
	v_pk_mul_f32 v[20:21], v[20:21], v[64:65] op_sel_hi:[1,0]
	v_pk_mul_f32 v[18:19], v[18:19], v[64:65] op_sel_hi:[1,0]
	v_pk_mul_f32 v[16:17], v[16:17], v[64:65] op_sel_hi:[1,0]
	v_cvt_pk_bf16_f32 v57, v95, v98
	v_pk_mul_f32 v[14:15], v[14:15], v[64:65] op_sel_hi:[1,0]
	v_pk_mul_f32 v[12:13], v[12:13], v[64:65] op_sel_hi:[1,0]
	s_waitcnt lgkmcnt(1)
	v_mfma_f32_32x32x16_bf16 v[16:31], v[42:45], v[54:57], v[16:31]
	ds_read2_b64 v[42:45], v47 offset0:132 offset1:134
	v_mul_f32_e64 v10, v10, v64
	v_mul_f32_e64 v11, v11, v64
	v_mul_f32_e64 v8, v8, v64
	v_mul_f32_e64 v9, v9, v64
	v_pk_mul_f32 v[6:7], v[6:7], v[64:65] op_sel_hi:[1,0]
	v_pk_mul_f32 v[4:5], v[4:5], v[64:65] op_sel_hi:[1,0]
	v_pk_mul_f32 v[2:3], v[2:3], v[64:65] op_sel_hi:[1,0]
	v_pk_mul_f32 v[0:1], v[0:1], v[64:65] op_sel_hi:[1,0]
	v_exp_f32_e32 v32, v32
	v_sub_f32_e32 v34, v63, v65
	s_waitcnt lgkmcnt(1)
	v_mfma_f32_32x32x16_bf16 v[0:15], v[58:61], v[54:57], v[0:15]
	ds_read2_b64 v[54:57], v46 offset0:196 offset1:198
	ds_read2_b64 v[66:69], v47 offset0:136 offset1:138
	ds_read2_b64 v[70:73], v46 offset0:200 offset1:202
	ds_read2_b64 v[74:77], v47 offset0:140 offset1:142
	ds_read2_b64 v[78:81], v46 offset0:204 offset1:206
	v_add_f32_e32 v46, v82, v83
	v_add_f32_e32 v46, 0, v46
	v_add_f32_e32 v47, v84, v85
	v_add_f32_e32 v62, v47, v46
	v_pk_mov_b32 v[46:47], v[50:51], v[50:51] op_sel:[1,0]
	v_cvt_pk_bf16_f32 v58, v83, v85
	v_cvt_pk_bf16_f32 v82, v46, v47
	v_pk_mov_b32 v[46:47], v[40:41], v[40:41] op_sel:[1,0]
	v_add_f32_e32 v63, v86, v87
	v_cvt_pk_bf16_f32 v83, v46, v47
	v_pk_mov_b32 v[46:47], v[36:37], v[36:37] op_sel:[1,0]
	v_exp_f32_e32 v34, v34
	v_cvt_pk_bf16_f32 v84, v46, v47
	v_pk_mov_b32 v[46:47], v[32:33], v[32:33] op_sel:[1,0]
	v_pk_add_f32 v[40:41], v[40:41], v[48:49]
	v_cvt_pk_bf16_f32 v85, v46, v47
	v_pk_add_f32 v[36:37], v[36:37], v[38:39]
	v_pk_add_f32 v[32:33], v[32:33], v[34:35]
	s_waitcnt lgkmcnt(5)
	v_mfma_f32_32x32x16_bf16 v[16:31], v[42:45], v[82:85], v[16:31]
	v_add_f32_e32 v42, v63, v62
	v_add_f32_e32 v43, v89, v90
	v_add_f32_e32 v42, v43, v42
	v_add_f32_e32 v43, v91, v92
	v_add_f32_e32 v42, v43, v42
	v_add_f32_e32 v43, v93, v94
	v_add_f32_e32 v42, v43, v42
	v_add_f32_e32 v43, v95, v97
	v_add_f32_e32 v42, v43, v42
	v_add_f32_e32 v43, v98, v99
	v_add_f32_e32 v46, v43, v42
	v_pk_mov_b32 v[42:43], v[52:53], v[52:53] op_sel:[1,0]
	v_pk_add_f32 v[44:45], v[50:51], v[52:53]
	v_cvt_pk_bf16_f32 v42, v42, v43
	v_add_f32_e32 v43, v45, v46
	v_add_f32_e32 v46, v44, v43
	v_pk_mov_b32 v[44:45], v[48:49], v[48:49] op_sel:[1,0]
	v_add_f32_e32 v41, v41, v46
	v_cvt_pk_bf16_f32 v43, v44, v45
	v_add_f32_e32 v45, v40, v41
	s_waitcnt lgkmcnt(4)
	v_mfma_f32_32x32x16_bf16 v[0:15], v[54:57], v[82:85], v[0:15]
	v_add_f32_e32 v37, v37, v45
	v_pk_mov_b32 v[40:41], v[38:39], v[38:39] op_sel:[1,0]
	v_add_f32_e32 v38, v36, v37
	v_add_f32_e32 v33, v33, v38
	v_add_f32_e32 v32, v32, v33
	v_fmac_f32_e32 v32, v96, v64
	ds_bpermute_b32 v33, v103, v32
	v_cvt_pk_bf16_f32 v59, v87, v90
	v_cvt_pk_bf16_f32 v60, v92, v94
	v_cvt_pk_bf16_f32 v61, v97, v99
	v_pk_mov_b32 v[36:37], v[34:35], v[34:35] op_sel:[1,0]
	s_waitcnt lgkmcnt(0)
	v_add_f32_e32 v32, v32, v33
	v_mfma_f32_32x32x16_bf16 v[16:31], v[66:69], v[58:61], v[16:31]
	v_rcp_f32_e32 v34, v32
	v_cvt_pk_bf16_f32 v44, v40, v41
	v_cvt_pk_bf16_f32 v45, v36, v37
	v_mov_b32_e32 v103, v129
	v_mfma_f32_32x32x16_bf16 v[0:15], v[70:73], v[58:61], v[0:15]
	v_mfma_f32_32x32x16_bf16 v[16:31], v[74:77], v[42:45], v[16:31]
	v_mul_f32_e32 v32, 1.0, v34
	v_lshlrev_b64 v[34:35], 11, v[100:101]
	v_lshl_add_u64 v[34:35], s[0:1], 0, v[34:35]
	v_lshl_add_u64 v[34:35], v[34:35], 0, v[102:103]
	s_barrier
	v_mfma_f32_32x32x16_bf16 v[0:15], v[78:81], v[42:45], v[0:15]
	s_nop 4
	s_nop 0
	v_mul_f32_e64 v16, v16, v32
	v_mul_f32_e64 v17, v17, v32
	v_mul_f32_e64 v18, v18, v32
	v_mul_f32_e64 v19, v19, v32
	v_cvt_pk_bf16_f32 v16, v16, v17
	v_cvt_pk_bf16_f32 v17, v18, v19
	s_nop 0
	v_pk_mul_f32 v[0:1], v[0:1], v[32:33] op_sel_hi:[1,0]
	v_pk_mul_f32 v[2:3], v[2:3], v[32:33] op_sel_hi:[1,0]
	v_cvt_pk_bf16_f32 v0, v0, v1
	v_cvt_pk_bf16_f32 v1, v2, v3
	global_store_dwordx2 v[34:35], v[16:17], off offset:1024
	global_store_dwordx2 v[34:35], v[0:1], off offset:1088
	v_pk_mul_f32 v[0:1], v[20:21], v[32:33] op_sel_hi:[1,0]
	v_pk_mul_f32 v[2:3], v[22:23], v[32:33] op_sel_hi:[1,0]
	v_cvt_pk_bf16_f32 v0, v0, v1
	v_cvt_pk_bf16_f32 v1, v2, v3
	v_pk_mul_f32 v[2:3], v[4:5], v[32:33] op_sel_hi:[1,0]
	v_pk_mul_f32 v[4:5], v[6:7], v[32:33] op_sel_hi:[1,0]
	v_cvt_pk_bf16_f32 v2, v2, v3
	v_cvt_pk_bf16_f32 v3, v4, v5
	global_store_dwordx2 v[34:35], v[0:1], off offset:1040
	global_store_dwordx2 v[34:35], v[2:3], off offset:1104
	v_pk_mul_f32 v[0:1], v[24:25], v[32:33] op_sel_hi:[1,0]
	v_pk_mul_f32 v[2:3], v[26:27], v[32:33] op_sel_hi:[1,0]
	v_cvt_pk_bf16_f32 v0, v0, v1
	v_cvt_pk_bf16_f32 v1, v2, v3
	v_pk_mul_f32 v[2:3], v[8:9], v[32:33] op_sel_hi:[1,0]
	v_pk_mul_f32 v[4:5], v[10:11], v[32:33] op_sel_hi:[1,0]
	v_cvt_pk_bf16_f32 v2, v2, v3
	v_cvt_pk_bf16_f32 v3, v4, v5
	global_store_dwordx2 v[34:35], v[0:1], off offset:1056
	global_store_dwordx2 v[34:35], v[2:3], off offset:1120
	v_pk_mul_f32 v[0:1], v[28:29], v[32:33] op_sel_hi:[1,0]
	v_pk_mul_f32 v[2:3], v[30:31], v[32:33] op_sel_hi:[1,0]
	v_cvt_pk_bf16_f32 v0, v0, v1
	v_cvt_pk_bf16_f32 v1, v2, v3
	v_pk_mul_f32 v[2:3], v[12:13], v[32:33] op_sel_hi:[1,0]
	v_pk_mul_f32 v[4:5], v[14:15], v[32:33] op_sel_hi:[1,0]
	v_cvt_pk_bf16_f32 v2, v2, v3
	v_cvt_pk_bf16_f32 v3, v4, v5
	global_store_dwordx2 v[34:35], v[0:1], off offset:1072
	global_store_dwordx2 v[34:35], v[2:3], off offset:1136
	s_cbranch_execnz .LBB0_1755
	s_branch .LBB0_1892

.LBB0_1968:
	s_lshl_b32 s0, s21, 8
	v_mov_b32_e32 v138, v128
	v_mov_b32_e32 v139, v144
	s_add_i32 s0, s0, s59
	v_mul_f32_e32 v124, 0xbfb8aa3b, v124
	v_add_u32_e32 v140, s0, v138
	s_lshl_b32 s0, s20, 8
	s_or_b32 s0, s0, s60
	v_lshl_add_u32 v138, v139, 2, s0
	v_ashrrev_i32_e32 v141, 31, v140
	v_lshlrev_b64 v[142:143], 10, v[140:141]
	v_ashrrev_i32_e32 v139, 31, v138
	v_lshl_add_u64 v[142:143], s[44:45], 0, v[142:143]
	v_lshlrev_b64 v[138:139], 1, v[138:139]
	v_lshl_add_u64 v[142:143], v[142:143], 0, v[138:139]
	global_load_dwordx2 v[150:151], v[142:143], off
	v_mul_f32_e32 v125, 0xbfb8aa3b, v125
	v_exp_f32_e32 v124, v124
	v_exp_f32_e32 v125, v125
	v_lshlrev_b64 v[148:149], 11, v[140:141]
	v_mul_f32_e32 v126, 0xbfb8aa3b, v126
	v_mul_f32_e32 v127, 0xbfb8aa3b, v127
	v_pk_add_f32 v[124:125], v[124:125], 1.0 op_sel_hi:[1,0]
	v_exp_f32_e32 v126, v126
	v_div_scale_f32 v141, s[0:1], v125, v125, 1.0
	v_rcp_f32_e32 v147, v141
	v_exp_f32_e32 v127, v127
	v_mul_f32_e32 v120, 0xbfb8aa3b, v120
	v_mul_f32_e32 v121, 0xbfb8aa3b, v121
	v_exp_f32_e32 v120, v120
	v_pk_add_f32 v[126:127], v[126:127], 1.0 op_sel_hi:[1,0]
	v_exp_f32_e32 v121, v121
	v_readlane_b32 s2, v251, 3
	v_readlane_b32 s3, v251, 4
	v_mul_f32_e32 v122, 0xbfb8aa3b, v122
	v_pk_add_f32 v[120:121], v[120:121], 1.0 op_sel_hi:[1,0]
	v_mul_f32_e32 v123, 0xbfb8aa3b, v123
	v_exp_f32_e32 v122, v122
	v_exp_f32_e32 v123, v123
	v_mul_f32_e32 v116, 0xbfb8aa3b, v116
	v_mul_f32_e32 v117, 0xbfb8aa3b, v117
	v_exp_f32_e32 v116, v116
	v_pk_add_f32 v[122:123], v[122:123], 1.0 op_sel_hi:[1,0]
	v_exp_f32_e32 v117, v117
	v_mul_f32_e32 v118, 0xbfb8aa3b, v118
	v_mul_f32_e32 v119, 0xbfb8aa3b, v119
	v_exp_f32_e32 v118, v118
	v_pk_add_f32 v[116:117], v[116:117], 1.0 op_sel_hi:[1,0]
	v_exp_f32_e32 v119, v119
	v_mul_f32_e32 v112, 0xbfb8aa3b, v112
	v_mul_f32_e32 v113, 0xbfb8aa3b, v113
	v_exp_f32_e32 v112, v112
	v_pk_add_f32 v[118:119], v[118:119], 1.0 op_sel_hi:[1,0]
	v_exp_f32_e32 v113, v113
	v_mul_f32_e32 v114, 0xbfb8aa3b, v114
	v_mul_f32_e32 v115, 0xbfb8aa3b, v115
	v_exp_f32_e32 v114, v114
	v_pk_add_f32 v[112:113], v[112:113], 1.0 op_sel_hi:[1,0]
	v_exp_f32_e32 v115, v115
	v_mul_f32_e32 v108, 0xbfb8aa3b, v108
	v_mul_f32_e32 v109, 0xbfb8aa3b, v109
	v_exp_f32_e32 v108, v108
	v_pk_add_f32 v[114:115], v[114:115], 1.0 op_sel_hi:[1,0]
	v_exp_f32_e32 v109, v109
	v_mul_f32_e32 v110, 0xbfb8aa3b, v110
	v_mul_f32_e32 v111, 0xbfb8aa3b, v111
	v_exp_f32_e32 v110, v110
	v_pk_add_f32 v[108:109], v[108:109], 1.0 op_sel_hi:[1,0]
	v_exp_f32_e32 v111, v111
	v_mul_f32_e32 v104, 0xbfb8aa3b, v104
	v_mul_f32_e32 v105, 0xbfb8aa3b, v105
	v_exp_f32_e32 v104, v104
	v_pk_add_f32 v[110:111], v[110:111], 1.0 op_sel_hi:[1,0]
	v_exp_f32_e32 v105, v105
	v_mul_f32_e32 v106, 0xbfb8aa3b, v106
	v_mul_f32_e32 v107, 0xbfb8aa3b, v107
	v_exp_f32_e32 v106, v106
	v_pk_add_f32 v[104:105], v[104:105], 1.0 op_sel_hi:[1,0]
	v_exp_f32_e32 v107, v107
	v_mul_f32_e32 v100, 0xbfb8aa3b, v100
	v_mul_f32_e32 v101, 0xbfb8aa3b, v101
	v_exp_f32_e32 v100, v100
	v_pk_add_f32 v[106:107], v[106:107], 1.0 op_sel_hi:[1,0]
	v_exp_f32_e32 v101, v101
	v_mul_f32_e32 v102, 0xbfb8aa3b, v102
	v_mul_f32_e32 v103, 0xbfb8aa3b, v103
	v_exp_f32_e32 v102, v102
	v_pk_add_f32 v[100:101], v[100:101], 1.0 op_sel_hi:[1,0]
	v_exp_f32_e32 v103, v103
	v_mul_f32_e32 v96, 0xbfb8aa3b, v96
	v_mul_f32_e32 v97, 0xbfb8aa3b, v97
	v_exp_f32_e32 v96, v96
	v_pk_add_f32 v[102:103], v[102:103], 1.0 op_sel_hi:[1,0]
	v_exp_f32_e32 v97, v97
	s_waitcnt vmcnt(0) lgkmcnt(0)
	v_lshlrev_b32_e32 v152, 16, v150
	v_and_b32_e32 v153, 0xffff0000, v150
	v_fma_f32 v150, -v141, v147, 1.0
	v_fmac_f32_e32 v147, v150, v147
	v_div_scale_f32 v150, vcc, 1.0, v125, 1.0
	v_mul_f32_e32 v154, v150, v147
	v_fma_f32 v155, -v141, v154, v150
	v_fmac_f32_e32 v154, v155, v147
	v_fma_f32 v141, -v141, v154, v150
	v_div_fmas_f32 v141, v141, v147, v154
	v_div_fixup_f32 v125, v141, v125, 1.0
	v_rcp_f32_e32 v147, v124
	v_pk_add_f32 v[96:97], v[96:97], 1.0 op_sel_hi:[1,0]
	v_mul_f32_e32 v98, 0xbfb8aa3b, v98
	v_mul_f32_e32 v99, 0xbfb8aa3b, v99
	v_mul_f32_e32 v124, 1.0, v147
	v_rcp_f32_e32 v147, v127
	v_pk_mul_f32 v[124:125], v[124:125], v[152:153]
	v_lshlrev_b32_e32 v150, 16, v151
	v_and_b32_e32 v151, 0xffff0000, v151
	v_mul_f32_e32 v127, 1.0, v147
	v_rcp_f32_e32 v147, v126
	v_exp_f32_e32 v98, v98
	v_exp_f32_e32 v99, v99
	v_mul_f32_e32 v92, 0xbfb8aa3b, v92
	v_mul_f32_e32 v126, 1.0, v147
	v_pk_mul_f32 v[126:127], v[126:127], v[150:151]
	v_cvt_pk_bf16_f32 v150, v124, v125
	v_cvt_pk_bf16_f32 v151, v126, v127
	global_load_dwordx2 v[126:127], v[142:143], off offset:32
	v_lshl_add_u64 v[124:125], s[2:3], 0, v[148:149]
	v_lshl_add_u64 v[124:125], v[124:125], 0, v[138:139]
	global_store_dwordx2 v[124:125], v[150:151], off
	v_pk_add_f32 v[98:99], v[98:99], 1.0 op_sel_hi:[1,0]
	v_mul_f32_e32 v93, 0xbfb8aa3b, v93
	v_exp_f32_e32 v92, v92
	v_exp_f32_e32 v93, v93
	v_mul_f32_e32 v94, 0xbfb8aa3b, v94
	v_mul_f32_e32 v95, 0xbfb8aa3b, v95
	v_exp_f32_e32 v94, v94
	v_pk_add_f32 v[92:93], v[92:93], 1.0 op_sel_hi:[1,0]
	v_exp_f32_e32 v95, v95
	v_mul_f32_e32 v88, 0xbfb8aa3b, v88
	v_mul_f32_e32 v89, 0xbfb8aa3b, v89
	v_exp_f32_e32 v88, v88
	v_pk_add_f32 v[94:95], v[94:95], 1.0 op_sel_hi:[1,0]
	v_exp_f32_e32 v89, v89
	v_mul_f32_e32 v90, 0xbfb8aa3b, v90
	v_mul_f32_e32 v91, 0xbfb8aa3b, v91
	v_exp_f32_e32 v90, v90
	v_pk_add_f32 v[88:89], v[88:89], 1.0 op_sel_hi:[1,0]
	v_exp_f32_e32 v91, v91
	v_mul_f32_e32 v84, 0xbfb8aa3b, v84
	v_mul_f32_e32 v85, 0xbfb8aa3b, v85
	v_exp_f32_e32 v84, v84
	v_pk_add_f32 v[90:91], v[90:91], 1.0 op_sel_hi:[1,0]
	v_exp_f32_e32 v85, v85
	v_mul_f32_e32 v86, 0xbfb8aa3b, v86
	v_mul_f32_e32 v87, 0xbfb8aa3b, v87
	v_exp_f32_e32 v86, v86
	v_pk_add_f32 v[84:85], v[84:85], 1.0 op_sel_hi:[1,0]
	v_exp_f32_e32 v87, v87
	v_mul_f32_e32 v80, 0xbfb8aa3b, v80
	v_mul_f32_e32 v81, 0xbfb8aa3b, v81
	v_exp_f32_e32 v80, v80
	v_pk_add_f32 v[86:87], v[86:87], 1.0 op_sel_hi:[1,0]
	v_exp_f32_e32 v81, v81
	v_mul_f32_e32 v82, 0xbfb8aa3b, v82
	v_mul_f32_e32 v83, 0xbfb8aa3b, v83
	v_exp_f32_e32 v82, v82
	v_pk_add_f32 v[80:81], v[80:81], 1.0 op_sel_hi:[1,0]
	v_exp_f32_e32 v83, v83
	v_mul_f32_e32 v76, 0xbfb8aa3b, v76
	v_mul_f32_e32 v77, 0xbfb8aa3b, v77
	v_exp_f32_e32 v76, v76
	v_pk_add_f32 v[82:83], v[82:83], 1.0 op_sel_hi:[1,0]
	v_exp_f32_e32 v77, v77
	v_mul_f32_e32 v78, 0xbfb8aa3b, v78
	v_mul_f32_e32 v79, 0xbfb8aa3b, v79
	v_exp_f32_e32 v78, v78
	v_pk_add_f32 v[76:77], v[76:77], 1.0 op_sel_hi:[1,0]
	v_exp_f32_e32 v79, v79
	v_mul_f32_e32 v72, 0xbfb8aa3b, v72
	v_mul_f32_e32 v73, 0xbfb8aa3b, v73
	v_exp_f32_e32 v72, v72
	v_pk_add_f32 v[78:79], v[78:79], 1.0 op_sel_hi:[1,0]
	v_exp_f32_e32 v73, v73
	v_mul_f32_e32 v74, 0xbfb8aa3b, v74
	v_mul_f32_e32 v75, 0xbfb8aa3b, v75
	v_exp_f32_e32 v74, v74
	v_pk_add_f32 v[72:73], v[72:73], 1.0 op_sel_hi:[1,0]
	v_exp_f32_e32 v75, v75
	v_mul_f32_e32 v68, 0xbfb8aa3b, v68
	v_mul_f32_e32 v69, 0xbfb8aa3b, v69
	v_exp_f32_e32 v68, v68
	v_pk_add_f32 v[74:75], v[74:75], 1.0 op_sel_hi:[1,0]
	v_exp_f32_e32 v69, v69
	v_mul_f32_e32 v70, 0xbfb8aa3b, v70
	v_mul_f32_e32 v71, 0xbfb8aa3b, v71
	v_exp_f32_e32 v70, v70
	v_pk_add_f32 v[68:69], v[68:69], 1.0 op_sel_hi:[1,0]
	v_exp_f32_e32 v71, v71
	v_mul_f32_e32 v64, 0xbfb8aa3b, v64
	v_mul_f32_e32 v65, 0xbfb8aa3b, v65
	v_exp_f32_e32 v64, v64
	v_pk_add_f32 v[70:71], v[70:71], 1.0 op_sel_hi:[1,0]
	v_exp_f32_e32 v65, v65
	v_mul_f32_e32 v66, 0xbfb8aa3b, v66
	v_mul_f32_e32 v67, 0xbfb8aa3b, v67
	s_waitcnt vmcnt(0) lgkmcnt(0)
	v_lshlrev_b32_e32 v148, 16, v126
	v_and_b32_e32 v149, 0xffff0000, v126
	v_rcp_f32_e32 v141, v121
	v_pk_add_f32 v[64:65], v[64:65], 1.0 op_sel_hi:[1,0]
	v_exp_f32_e32 v66, v66
	v_exp_f32_e32 v67, v67
	v_mul_f32_e32 v121, 1.0, v141
	v_div_scale_f32 v126, s[0:1], v120, v120, 1.0
	v_rcp_f32_e32 v141, v126
	v_pk_add_f32 v[66:67], v[66:67], 1.0 op_sel_hi:[1,0]
	v_mul_f32_e32 v60, 0xbfb8aa3b, v60
	v_mul_f32_e32 v61, 0xbfb8aa3b, v61
	v_fma_f32 v147, -v126, v141, 1.0
	v_fmac_f32_e32 v141, v147, v141
	v_div_scale_f32 v147, vcc, 1.0, v120, 1.0
	v_mul_f32_e32 v150, v147, v141
	v_fma_f32 v151, -v126, v150, v147
	v_fmac_f32_e32 v150, v151, v141
	v_fma_f32 v126, -v126, v150, v147
	v_div_fmas_f32 v126, v126, v141, v150
	v_rcp_f32_e32 v147, v123
	v_div_fixup_f32 v120, v126, v120, 1.0
	v_pk_mul_f32 v[120:121], v[120:121], v[148:149]
	v_lshlrev_b32_e32 v126, 16, v127
	v_mul_f32_e32 v123, 1.0, v147
	v_rcp_f32_e32 v147, v122
	v_and_b32_e32 v127, 0xffff0000, v127
	v_cvt_pk_bf16_f32 v120, v120, v121
	v_exp_f32_e32 v60, v60
	v_mul_f32_e32 v122, 1.0, v147
	v_pk_mul_f32 v[122:123], v[122:123], v[126:127]
	v_exp_f32_e32 v61, v61
	v_cvt_pk_bf16_f32 v121, v122, v123
	global_store_dwordx2 v[124:125], v[120:121], off offset:32
	global_load_dwordx2 v[120:121], v[142:143], off offset:256
	v_pk_add_f32 v[60:61], v[60:61], 1.0 op_sel_hi:[1,0]
	v_mul_f32_e32 v62, 0xbfb8aa3b, v62
	v_mul_f32_e32 v63, 0xbfb8aa3b, v63
	v_exp_f32_e32 v62, v62
	v_exp_f32_e32 v63, v63
	v_mul_f32_e32 v56, 0xbfb8aa3b, v56
	v_mul_f32_e32 v57, 0xbfb8aa3b, v57
	v_exp_f32_e32 v56, v56
	v_pk_add_f32 v[62:63], v[62:63], 1.0 op_sel_hi:[1,0]
	v_exp_f32_e32 v57, v57
	v_mul_f32_e32 v58, 0xbfb8aa3b, v58
	v_mul_f32_e32 v59, 0xbfb8aa3b, v59
	v_exp_f32_e32 v58, v58
	v_pk_add_f32 v[56:57], v[56:57], 1.0 op_sel_hi:[1,0]
	v_exp_f32_e32 v59, v59
	v_mul_f32_e32 v52, 0xbfb8aa3b, v52
	v_mul_f32_e32 v53, 0xbfb8aa3b, v53
	v_exp_f32_e32 v52, v52
	v_pk_add_f32 v[58:59], v[58:59], 1.0 op_sel_hi:[1,0]
	v_exp_f32_e32 v53, v53
	v_mul_f32_e32 v54, 0xbfb8aa3b, v54
	v_mul_f32_e32 v55, 0xbfb8aa3b, v55
	v_exp_f32_e32 v54, v54
	v_pk_add_f32 v[52:53], v[52:53], 1.0 op_sel_hi:[1,0]
	v_exp_f32_e32 v55, v55
	v_mul_f32_e32 v48, 0xbfb8aa3b, v48
	v_mul_f32_e32 v49, 0xbfb8aa3b, v49
	v_exp_f32_e32 v48, v48
	v_pk_add_f32 v[54:55], v[54:55], 1.0 op_sel_hi:[1,0]
	v_exp_f32_e32 v49, v49
	v_mul_f32_e32 v50, 0xbfb8aa3b, v50
	v_mul_f32_e32 v51, 0xbfb8aa3b, v51
	v_exp_f32_e32 v50, v50
	v_pk_add_f32 v[48:49], v[48:49], 1.0 op_sel_hi:[1,0]
	v_exp_f32_e32 v51, v51
	v_mul_f32_e32 v44, 0xbfb8aa3b, v44
	v_mul_f32_e32 v45, 0xbfb8aa3b, v45
	v_exp_f32_e32 v44, v44
	v_pk_add_f32 v[50:51], v[50:51], 1.0 op_sel_hi:[1,0]
	v_exp_f32_e32 v45, v45
	v_mul_f32_e32 v46, 0xbfb8aa3b, v46
	v_mul_f32_e32 v47, 0xbfb8aa3b, v47
	v_exp_f32_e32 v46, v46
	v_pk_add_f32 v[44:45], v[44:45], 1.0 op_sel_hi:[1,0]
	v_exp_f32_e32 v47, v47
	v_mul_f32_e32 v40, 0xbfb8aa3b, v40
	v_mul_f32_e32 v41, 0xbfb8aa3b, v41
	v_exp_f32_e32 v40, v40
	v_pk_add_f32 v[46:47], v[46:47], 1.0 op_sel_hi:[1,0]
	v_exp_f32_e32 v41, v41
	v_mul_f32_e32 v42, 0xbfb8aa3b, v42
	v_mul_f32_e32 v43, 0xbfb8aa3b, v43
	v_exp_f32_e32 v42, v42
	v_pk_add_f32 v[40:41], v[40:41], 1.0 op_sel_hi:[1,0]
	v_exp_f32_e32 v43, v43
	v_mul_f32_e32 v36, 0xbfb8aa3b, v36
	v_mul_f32_e32 v37, 0xbfb8aa3b, v37
	v_exp_f32_e32 v36, v36
	v_pk_add_f32 v[42:43], v[42:43], 1.0 op_sel_hi:[1,0]
	v_exp_f32_e32 v37, v37
	v_mul_f32_e32 v38, 0xbfb8aa3b, v38
	v_mul_f32_e32 v39, 0xbfb8aa3b, v39
	v_exp_f32_e32 v38, v38
	v_pk_add_f32 v[36:37], v[36:37], 1.0 op_sel_hi:[1,0]
	v_exp_f32_e32 v39, v39
	v_mul_f32_e32 v32, 0xbfb8aa3b, v32
	v_mul_f32_e32 v33, 0xbfb8aa3b, v33
	v_exp_f32_e32 v32, v32
	v_pk_add_f32 v[38:39], v[38:39], 1.0 op_sel_hi:[1,0]
	v_exp_f32_e32 v33, v33
	v_mul_f32_e32 v34, 0xbfb8aa3b, v34
	v_mul_f32_e32 v35, 0xbfb8aa3b, v35
	v_exp_f32_e32 v34, v34
	v_pk_add_f32 v[32:33], v[32:33], 1.0 op_sel_hi:[1,0]
	v_exp_f32_e32 v35, v35
	v_mul_f32_e32 v28, 0xbfb8aa3b, v28
	v_mul_f32_e32 v29, 0xbfb8aa3b, v29
	v_exp_f32_e32 v28, v28
	v_pk_add_f32 v[34:35], v[34:35], 1.0 op_sel_hi:[1,0]
	s_waitcnt vmcnt(0) lgkmcnt(0)
	v_lshlrev_b32_e32 v122, 16, v120
	v_and_b32_e32 v123, 0xffff0000, v120
	v_rcp_f32_e32 v126, v117
	v_exp_f32_e32 v29, v29
	v_mul_f32_e32 v30, 0xbfb8aa3b, v30
	v_mul_f32_e32 v31, 0xbfb8aa3b, v31
	v_mul_f32_e32 v117, 1.0, v126
	v_rcp_f32_e32 v126, v116
	v_pk_add_f32 v[28:29], v[28:29], 1.0 op_sel_hi:[1,0]
	v_exp_f32_e32 v30, v30
	v_exp_f32_e32 v31, v31
	v_mul_f32_e32 v116, 1.0, v126
	v_pk_mul_f32 v[116:117], v[116:117], v[122:123]
	v_rcp_f32_e32 v123, v119
	v_lshlrev_b32_e32 v120, 16, v121
	v_and_b32_e32 v121, 0xffff0000, v121
	v_cvt_pk_bf16_f32 v116, v116, v117
	v_mul_f32_e32 v119, 1.0, v123
	v_rcp_f32_e32 v123, v118
	v_pk_add_f32 v[30:31], v[30:31], 1.0 op_sel_hi:[1,0]
	v_mul_f32_e32 v24, 0xbfb8aa3b, v24
	v_mul_f32_e32 v25, 0xbfb8aa3b, v25
	v_mul_f32_e32 v118, 1.0, v123
	v_pk_mul_f32 v[118:119], v[118:119], v[120:121]
	v_exp_f32_e32 v24, v24
	v_cvt_pk_bf16_f32 v117, v118, v119
	global_store_dwordx2 v[124:125], v[116:117], off offset:256
	global_load_dwordx2 v[116:117], v[142:143], off offset:288
	v_exp_f32_e32 v25, v25
	v_mul_f32_e32 v26, 0xbfb8aa3b, v26
	v_mul_f32_e32 v27, 0xbfb8aa3b, v27
	v_exp_f32_e32 v26, v26
	v_pk_add_f32 v[24:25], v[24:25], 1.0 op_sel_hi:[1,0]
	v_exp_f32_e32 v27, v27
	v_mul_f32_e32 v20, 0xbfb8aa3b, v20
	v_mul_f32_e32 v21, 0xbfb8aa3b, v21
	v_exp_f32_e32 v20, v20
	v_pk_add_f32 v[26:27], v[26:27], 1.0 op_sel_hi:[1,0]
	v_exp_f32_e32 v21, v21
	v_mul_f32_e32 v22, 0xbfb8aa3b, v22
	v_mul_f32_e32 v23, 0xbfb8aa3b, v23
	v_exp_f32_e32 v22, v22
	v_pk_add_f32 v[20:21], v[20:21], 1.0 op_sel_hi:[1,0]
	v_exp_f32_e32 v23, v23
	v_mul_f32_e32 v16, 0xbfb8aa3b, v16
	v_mul_f32_e32 v17, 0xbfb8aa3b, v17
	v_exp_f32_e32 v16, v16
	v_pk_add_f32 v[22:23], v[22:23], 1.0 op_sel_hi:[1,0]
	v_exp_f32_e32 v17, v17
	v_mul_f32_e32 v18, 0xbfb8aa3b, v18
	v_mul_f32_e32 v19, 0xbfb8aa3b, v19
	v_exp_f32_e32 v18, v18
	v_pk_add_f32 v[16:17], v[16:17], 1.0 op_sel_hi:[1,0]
	v_exp_f32_e32 v19, v19
	v_mul_f32_e32 v12, 0xbfb8aa3b, v12
	v_mul_f32_e32 v13, 0xbfb8aa3b, v13
	v_exp_f32_e32 v12, v12
	v_pk_add_f32 v[18:19], v[18:19], 1.0 op_sel_hi:[1,0]
	v_exp_f32_e32 v13, v13
	v_mul_f32_e32 v14, 0xbfb8aa3b, v14
	v_mul_f32_e32 v15, 0xbfb8aa3b, v15
	v_exp_f32_e32 v14, v14
	v_pk_add_f32 v[12:13], v[12:13], 1.0 op_sel_hi:[1,0]
	v_exp_f32_e32 v15, v15
	v_mul_f32_e32 v8, 0xbfb8aa3b, v8
	v_mul_f32_e32 v9, 0xbfb8aa3b, v9
	v_exp_f32_e32 v8, v8
	v_pk_add_f32 v[14:15], v[14:15], 1.0 op_sel_hi:[1,0]
	v_exp_f32_e32 v9, v9
	v_mul_f32_e32 v10, 0xbfb8aa3b, v10
	v_mul_f32_e32 v11, 0xbfb8aa3b, v11
	v_exp_f32_e32 v10, v10
	v_pk_add_f32 v[8:9], v[8:9], 1.0 op_sel_hi:[1,0]
	v_exp_f32_e32 v11, v11
	v_mul_f32_e32 v4, 0xbfb8aa3b, v4
	v_mul_f32_e32 v5, 0xbfb8aa3b, v5
	v_exp_f32_e32 v4, v4
	v_pk_add_f32 v[10:11], v[10:11], 1.0 op_sel_hi:[1,0]
	v_exp_f32_e32 v5, v5
	v_mul_f32_e32 v6, 0xbfb8aa3b, v6
	v_mul_f32_e32 v7, 0xbfb8aa3b, v7
	v_exp_f32_e32 v6, v6
	v_pk_add_f32 v[4:5], v[4:5], 1.0 op_sel_hi:[1,0]
	v_exp_f32_e32 v7, v7
	v_mul_f32_e32 v0, 0xbfb8aa3b, v0
	v_mul_f32_e32 v1, 0xbfb8aa3b, v1
	v_exp_f32_e32 v0, v0
	v_pk_add_f32 v[6:7], v[6:7], 1.0 op_sel_hi:[1,0]
	v_exp_f32_e32 v1, v1
	v_mul_f32_e32 v2, 0xbfb8aa3b, v2
	v_mul_f32_e32 v3, 0xbfb8aa3b, v3
	v_exp_f32_e32 v2, v2
	v_pk_add_f32 v[0:1], v[0:1], 1.0 op_sel_hi:[1,0]
	v_exp_f32_e32 v3, v3
	s_mov_b32 s20, s48
	s_mov_b32 s21, s50
	s_mov_b64 s[18:19], s[52:53]
	v_pk_add_f32 v[2:3], v[2:3], 1.0 op_sel_hi:[1,0]
	s_waitcnt vmcnt(0) lgkmcnt(0)
	v_lshlrev_b32_e32 v118, 16, v116
	v_and_b32_e32 v119, 0xffff0000, v116
	v_rcp_f32_e32 v120, v113
	s_nop 0
	v_mul_f32_e32 v113, 1.0, v120
	v_rcp_f32_e32 v120, v112
	s_nop 0
	v_mul_f32_e32 v112, 1.0, v120
	v_pk_mul_f32 v[112:113], v[112:113], v[118:119]
	v_rcp_f32_e32 v119, v115
	v_lshlrev_b32_e32 v116, 16, v117
	v_and_b32_e32 v117, 0xffff0000, v117
	v_cvt_pk_bf16_f32 v112, v112, v113
	v_mul_f32_e32 v115, 1.0, v119
	v_rcp_f32_e32 v119, v114
	s_nop 0
	v_mul_f32_e32 v114, 1.0, v119
	v_pk_mul_f32 v[114:115], v[114:115], v[116:117]
	s_nop 0
	v_cvt_pk_bf16_f32 v113, v114, v115
	global_store_dwordx2 v[124:125], v[112:113], off offset:288
	v_add_u32_e32 v112, 16, v140
	v_ashrrev_i32_e32 v113, 31, v112
	v_lshlrev_b64 v[116:117], 10, v[112:113]
	v_lshlrev_b64 v[114:115], 11, v[112:113]
	v_lshl_add_u64 v[112:113], s[44:45], 0, v[116:117]
	v_lshl_add_u64 v[112:113], v[112:113], 0, v[138:139]
	global_load_dwordx2 v[116:117], v[112:113], off
	s_waitcnt vmcnt(0) lgkmcnt(0)
	v_lshlrev_b32_e32 v118, 16, v116
	v_and_b32_e32 v119, 0xffff0000, v116
	v_rcp_f32_e32 v120, v109
	s_nop 0
	v_mul_f32_e32 v109, 1.0, v120
	v_rcp_f32_e32 v120, v108
	s_nop 0
	v_mul_f32_e32 v108, 1.0, v120
	v_pk_mul_f32 v[108:109], v[108:109], v[118:119]
	v_rcp_f32_e32 v119, v111
	v_lshlrev_b32_e32 v116, 16, v117
	v_and_b32_e32 v117, 0xffff0000, v117
	v_mul_f32_e32 v111, 1.0, v119
	v_rcp_f32_e32 v119, v110
	s_nop 0
	v_mul_f32_e32 v110, 1.0, v119
	v_pk_mul_f32 v[110:111], v[110:111], v[116:117]
	v_cvt_pk_bf16_f32 v116, v108, v109
	v_cvt_pk_bf16_f32 v117, v110, v111
	global_load_dwordx2 v[110:111], v[112:113], off offset:32
	v_lshl_add_u64 v[108:109], s[2:3], 0, v[114:115]
	v_lshl_add_u64 v[108:109], v[108:109], 0, v[138:139]
	global_store_dwordx2 v[108:109], v[116:117], off
	s_waitcnt vmcnt(0) lgkmcnt(0)
	v_lshlrev_b32_e32 v114, 16, v110
	v_and_b32_e32 v115, 0xffff0000, v110
	v_rcp_f32_e32 v116, v105
	s_nop 0
	v_mul_f32_e32 v105, 1.0, v116
	v_rcp_f32_e32 v116, v104
	s_nop 0
	v_mul_f32_e32 v104, 1.0, v116
	v_pk_mul_f32 v[104:105], v[104:105], v[114:115]
	v_rcp_f32_e32 v115, v107
	v_lshlrev_b32_e32 v110, 16, v111
	v_and_b32_e32 v111, 0xffff0000, v111
	v_cvt_pk_bf16_f32 v104, v104, v105
	v_mul_f32_e32 v107, 1.0, v115
	v_rcp_f32_e32 v115, v106
	s_nop 0
	v_mul_f32_e32 v106, 1.0, v115
	v_pk_mul_f32 v[106:107], v[106:107], v[110:111]
	s_nop 0
	v_cvt_pk_bf16_f32 v105, v106, v107
	global_store_dwordx2 v[108:109], v[104:105], off offset:32
	global_load_dwordx2 v[104:105], v[112:113], off offset:256
	s_waitcnt vmcnt(0) lgkmcnt(0)
	v_lshlrev_b32_e32 v106, 16, v104
	v_and_b32_e32 v107, 0xffff0000, v104
	v_rcp_f32_e32 v110, v101
	s_nop 0
	v_mul_f32_e32 v101, 1.0, v110
	v_rcp_f32_e32 v110, v100
	s_nop 0
	v_mul_f32_e32 v100, 1.0, v110
	v_pk_mul_f32 v[100:101], v[100:101], v[106:107]
	v_rcp_f32_e32 v107, v103
	v_lshlrev_b32_e32 v104, 16, v105
	v_and_b32_e32 v105, 0xffff0000, v105
	v_cvt_pk_bf16_f32 v100, v100, v101
	v_mul_f32_e32 v103, 1.0, v107
	v_rcp_f32_e32 v107, v102
	s_nop 0
	v_mul_f32_e32 v102, 1.0, v107
	v_pk_mul_f32 v[102:103], v[102:103], v[104:105]
	s_nop 0
	v_cvt_pk_bf16_f32 v101, v102, v103
	global_store_dwordx2 v[108:109], v[100:101], off offset:256
	global_load_dwordx2 v[100:101], v[112:113], off offset:288
	s_waitcnt vmcnt(0) lgkmcnt(0)
	v_lshlrev_b32_e32 v102, 16, v100
	v_and_b32_e32 v103, 0xffff0000, v100
	v_rcp_f32_e32 v104, v97
	s_nop 0
	v_mul_f32_e32 v97, 1.0, v104
	v_rcp_f32_e32 v104, v96
	s_nop 0
	v_mul_f32_e32 v96, 1.0, v104
	v_pk_mul_f32 v[96:97], v[96:97], v[102:103]
	v_rcp_f32_e32 v103, v99
	v_lshlrev_b32_e32 v100, 16, v101
	v_and_b32_e32 v101, 0xffff0000, v101
	v_cvt_pk_bf16_f32 v96, v96, v97
	v_mul_f32_e32 v99, 1.0, v103
	v_rcp_f32_e32 v103, v98
	s_nop 0
	v_mul_f32_e32 v98, 1.0, v103
	v_pk_mul_f32 v[98:99], v[98:99], v[100:101]
	s_nop 0
	v_cvt_pk_bf16_f32 v97, v98, v99
	global_store_dwordx2 v[108:109], v[96:97], off offset:288
	v_add_u32_e32 v96, 32, v140
	v_ashrrev_i32_e32 v97, 31, v96
	v_lshlrev_b64 v[100:101], 10, v[96:97]
	v_lshlrev_b64 v[98:99], 11, v[96:97]
	v_lshl_add_u64 v[96:97], s[44:45], 0, v[100:101]
	v_lshl_add_u64 v[96:97], v[96:97], 0, v[138:139]
	global_load_dwordx2 v[100:101], v[96:97], off
	s_waitcnt vmcnt(0) lgkmcnt(0)
	v_lshlrev_b32_e32 v102, 16, v100
	v_and_b32_e32 v103, 0xffff0000, v100
	v_rcp_f32_e32 v104, v93
	s_nop 0
	v_mul_f32_e32 v93, 1.0, v104
	v_rcp_f32_e32 v104, v92
	s_nop 0
	v_mul_f32_e32 v92, 1.0, v104
	v_pk_mul_f32 v[92:93], v[92:93], v[102:103]
	v_rcp_f32_e32 v103, v95
	v_lshlrev_b32_e32 v100, 16, v101
	v_and_b32_e32 v101, 0xffff0000, v101
	v_mul_f32_e32 v95, 1.0, v103
	v_rcp_f32_e32 v103, v94
	s_nop 0
	v_mul_f32_e32 v94, 1.0, v103
	v_pk_mul_f32 v[94:95], v[94:95], v[100:101]
	v_cvt_pk_bf16_f32 v100, v92, v93
	v_cvt_pk_bf16_f32 v101, v94, v95
	global_load_dwordx2 v[94:95], v[96:97], off offset:32
	v_lshl_add_u64 v[92:93], s[2:3], 0, v[98:99]
	v_lshl_add_u64 v[92:93], v[92:93], 0, v[138:139]
	global_store_dwordx2 v[92:93], v[100:101], off
	s_waitcnt vmcnt(0) lgkmcnt(0)
	v_lshlrev_b32_e32 v98, 16, v94
	v_and_b32_e32 v99, 0xffff0000, v94
	v_rcp_f32_e32 v100, v89
	s_nop 0
	v_mul_f32_e32 v89, 1.0, v100
	v_rcp_f32_e32 v100, v88
	s_nop 0
	v_mul_f32_e32 v88, 1.0, v100
	v_pk_mul_f32 v[88:89], v[88:89], v[98:99]
	v_rcp_f32_e32 v99, v91
	v_lshlrev_b32_e32 v94, 16, v95
	v_and_b32_e32 v95, 0xffff0000, v95
	v_cvt_pk_bf16_f32 v88, v88, v89
	v_mul_f32_e32 v91, 1.0, v99
	v_rcp_f32_e32 v99, v90
	s_nop 0
	v_mul_f32_e32 v90, 1.0, v99
	v_pk_mul_f32 v[90:91], v[90:91], v[94:95]
	s_nop 0
	v_cvt_pk_bf16_f32 v89, v90, v91
	global_store_dwordx2 v[92:93], v[88:89], off offset:32
	global_load_dwordx2 v[88:89], v[96:97], off offset:256
	s_waitcnt vmcnt(0) lgkmcnt(0)
	v_lshlrev_b32_e32 v90, 16, v88
	v_and_b32_e32 v91, 0xffff0000, v88
	v_rcp_f32_e32 v94, v85
	s_nop 0
	v_mul_f32_e32 v85, 1.0, v94
	v_rcp_f32_e32 v94, v84
	s_nop 0
	v_mul_f32_e32 v84, 1.0, v94
	v_pk_mul_f32 v[84:85], v[84:85], v[90:91]
	v_rcp_f32_e32 v91, v87
	v_lshlrev_b32_e32 v88, 16, v89
	v_and_b32_e32 v89, 0xffff0000, v89
	v_cvt_pk_bf16_f32 v84, v84, v85
	v_mul_f32_e32 v87, 1.0, v91
	v_rcp_f32_e32 v91, v86
	s_nop 0
	v_mul_f32_e32 v86, 1.0, v91
	v_pk_mul_f32 v[86:87], v[86:87], v[88:89]
	s_nop 0
	v_cvt_pk_bf16_f32 v85, v86, v87
	global_store_dwordx2 v[92:93], v[84:85], off offset:256
	global_load_dwordx2 v[84:85], v[96:97], off offset:288
	s_waitcnt vmcnt(0) lgkmcnt(0)
	v_lshlrev_b32_e32 v86, 16, v84
	v_and_b32_e32 v87, 0xffff0000, v84
	v_rcp_f32_e32 v88, v81
	s_nop 0
	v_mul_f32_e32 v81, 1.0, v88
	v_rcp_f32_e32 v88, v80
	s_nop 0
	v_mul_f32_e32 v80, 1.0, v88
	v_pk_mul_f32 v[80:81], v[80:81], v[86:87]
	v_rcp_f32_e32 v87, v83
	v_lshlrev_b32_e32 v84, 16, v85
	v_and_b32_e32 v85, 0xffff0000, v85
	v_cvt_pk_bf16_f32 v80, v80, v81
	v_mul_f32_e32 v83, 1.0, v87
	v_rcp_f32_e32 v87, v82
	s_nop 0
	v_mul_f32_e32 v82, 1.0, v87
	v_pk_mul_f32 v[82:83], v[82:83], v[84:85]
	s_nop 0
	v_cvt_pk_bf16_f32 v81, v82, v83
	global_store_dwordx2 v[92:93], v[80:81], off offset:288
	v_add_u32_e32 v80, 48, v140
	v_ashrrev_i32_e32 v81, 31, v80
	v_lshlrev_b64 v[84:85], 10, v[80:81]
	v_lshlrev_b64 v[82:83], 11, v[80:81]
	v_lshl_add_u64 v[80:81], s[44:45], 0, v[84:85]
	v_lshl_add_u64 v[80:81], v[80:81], 0, v[138:139]
	global_load_dwordx2 v[84:85], v[80:81], off
	s_waitcnt vmcnt(0) lgkmcnt(0)
	v_lshlrev_b32_e32 v86, 16, v84
	v_and_b32_e32 v87, 0xffff0000, v84
	v_rcp_f32_e32 v88, v77
	s_nop 0
	v_mul_f32_e32 v77, 1.0, v88
	v_rcp_f32_e32 v88, v76
	s_nop 0
	v_mul_f32_e32 v76, 1.0, v88
	v_pk_mul_f32 v[76:77], v[76:77], v[86:87]
	v_rcp_f32_e32 v87, v79
	v_lshlrev_b32_e32 v84, 16, v85
	v_and_b32_e32 v85, 0xffff0000, v85
	v_mul_f32_e32 v79, 1.0, v87
	v_rcp_f32_e32 v87, v78
	s_nop 0
	v_mul_f32_e32 v78, 1.0, v87
	v_pk_mul_f32 v[78:79], v[78:79], v[84:85]
	v_cvt_pk_bf16_f32 v84, v76, v77
	v_cvt_pk_bf16_f32 v85, v78, v79
	global_load_dwordx2 v[78:79], v[80:81], off offset:32
	v_lshl_add_u64 v[76:77], s[2:3], 0, v[82:83]
	v_lshl_add_u64 v[76:77], v[76:77], 0, v[138:139]
	global_store_dwordx2 v[76:77], v[84:85], off
	s_waitcnt vmcnt(0) lgkmcnt(0)
	v_lshlrev_b32_e32 v82, 16, v78
	v_and_b32_e32 v83, 0xffff0000, v78
	v_rcp_f32_e32 v84, v73
	s_nop 0
	v_mul_f32_e32 v73, 1.0, v84
	v_rcp_f32_e32 v84, v72
	s_nop 0
	v_mul_f32_e32 v72, 1.0, v84
	v_pk_mul_f32 v[72:73], v[72:73], v[82:83]
	v_rcp_f32_e32 v83, v75
	v_lshlrev_b32_e32 v78, 16, v79
	v_and_b32_e32 v79, 0xffff0000, v79
	v_cvt_pk_bf16_f32 v72, v72, v73
	v_mul_f32_e32 v75, 1.0, v83
	v_rcp_f32_e32 v83, v74
	s_nop 0
	v_mul_f32_e32 v74, 1.0, v83
	v_pk_mul_f32 v[74:75], v[74:75], v[78:79]
	s_nop 0
	v_cvt_pk_bf16_f32 v73, v74, v75
	global_store_dwordx2 v[76:77], v[72:73], off offset:32
	global_load_dwordx2 v[72:73], v[80:81], off offset:256
	s_waitcnt vmcnt(0) lgkmcnt(0)
	v_lshlrev_b32_e32 v74, 16, v72
	v_and_b32_e32 v75, 0xffff0000, v72
	v_rcp_f32_e32 v78, v69
	s_nop 0
	v_mul_f32_e32 v69, 1.0, v78
	v_rcp_f32_e32 v78, v68
	s_nop 0
	v_mul_f32_e32 v68, 1.0, v78
	v_pk_mul_f32 v[68:69], v[68:69], v[74:75]
	v_rcp_f32_e32 v75, v71
	v_lshlrev_b32_e32 v72, 16, v73
	v_and_b32_e32 v73, 0xffff0000, v73
	v_cvt_pk_bf16_f32 v68, v68, v69
	v_mul_f32_e32 v71, 1.0, v75
	v_rcp_f32_e32 v75, v70
	s_nop 0
	v_mul_f32_e32 v70, 1.0, v75
	v_pk_mul_f32 v[70:71], v[70:71], v[72:73]
	s_nop 0
	v_cvt_pk_bf16_f32 v69, v70, v71
	global_store_dwordx2 v[76:77], v[68:69], off offset:256
	global_load_dwordx2 v[68:69], v[80:81], off offset:288
	s_waitcnt vmcnt(0) lgkmcnt(0)
	v_lshlrev_b32_e32 v70, 16, v68
	v_and_b32_e32 v71, 0xffff0000, v68
	v_rcp_f32_e32 v72, v65
	s_nop 0
	v_mul_f32_e32 v65, 1.0, v72
	v_rcp_f32_e32 v72, v64
	s_nop 0
	v_mul_f32_e32 v64, 1.0, v72
	v_pk_mul_f32 v[64:65], v[64:65], v[70:71]
	v_rcp_f32_e32 v71, v67
	v_lshlrev_b32_e32 v68, 16, v69
	v_and_b32_e32 v69, 0xffff0000, v69
	v_cvt_pk_bf16_f32 v64, v64, v65
	v_mul_f32_e32 v67, 1.0, v71
	v_rcp_f32_e32 v71, v66
	s_nop 0
	v_mul_f32_e32 v66, 1.0, v71
	v_pk_mul_f32 v[66:67], v[66:67], v[68:69]
	s_nop 0
	v_cvt_pk_bf16_f32 v65, v66, v67
	global_store_dwordx2 v[76:77], v[64:65], off offset:288
	v_add_u32_e32 v64, 0x80, v140
	v_ashrrev_i32_e32 v65, 31, v64
	v_lshlrev_b64 v[68:69], 10, v[64:65]
	v_lshlrev_b64 v[66:67], 11, v[64:65]
	v_lshl_add_u64 v[64:65], s[44:45], 0, v[68:69]
	v_lshl_add_u64 v[64:65], v[64:65], 0, v[138:139]
	global_load_dwordx2 v[68:69], v[64:65], off
	s_waitcnt vmcnt(0) lgkmcnt(0)
	v_lshlrev_b32_e32 v70, 16, v68
	v_and_b32_e32 v71, 0xffff0000, v68
	v_rcp_f32_e32 v72, v61
	s_nop 0
	v_mul_f32_e32 v61, 1.0, v72
	v_rcp_f32_e32 v72, v60
	s_nop 0
	v_mul_f32_e32 v60, 1.0, v72
	v_pk_mul_f32 v[60:61], v[60:61], v[70:71]
	v_rcp_f32_e32 v71, v63
	v_lshlrev_b32_e32 v68, 16, v69
	v_and_b32_e32 v69, 0xffff0000, v69
	v_mul_f32_e32 v63, 1.0, v71
	v_rcp_f32_e32 v71, v62
	s_nop 0
	v_mul_f32_e32 v62, 1.0, v71
	v_pk_mul_f32 v[62:63], v[62:63], v[68:69]
	v_cvt_pk_bf16_f32 v68, v60, v61
	v_cvt_pk_bf16_f32 v69, v62, v63
	global_load_dwordx2 v[62:63], v[64:65], off offset:32
	v_lshl_add_u64 v[60:61], s[2:3], 0, v[66:67]
	v_lshl_add_u64 v[60:61], v[60:61], 0, v[138:139]
	global_store_dwordx2 v[60:61], v[68:69], off
	s_waitcnt vmcnt(0) lgkmcnt(0)
	v_lshlrev_b32_e32 v66, 16, v62
	v_and_b32_e32 v67, 0xffff0000, v62
	v_rcp_f32_e32 v68, v57
	s_nop 0
	v_mul_f32_e32 v57, 1.0, v68
	v_rcp_f32_e32 v68, v56
	s_nop 0
	v_mul_f32_e32 v56, 1.0, v68
	v_pk_mul_f32 v[56:57], v[56:57], v[66:67]
	v_rcp_f32_e32 v67, v59
	v_lshlrev_b32_e32 v62, 16, v63
	v_and_b32_e32 v63, 0xffff0000, v63
	v_cvt_pk_bf16_f32 v56, v56, v57
	v_mul_f32_e32 v59, 1.0, v67
	v_rcp_f32_e32 v67, v58
	s_nop 0
	v_mul_f32_e32 v58, 1.0, v67
	v_pk_mul_f32 v[58:59], v[58:59], v[62:63]
	s_nop 0
	v_cvt_pk_bf16_f32 v57, v58, v59
	global_store_dwordx2 v[60:61], v[56:57], off offset:32
	global_load_dwordx2 v[56:57], v[64:65], off offset:256
	s_waitcnt vmcnt(0) lgkmcnt(0)
	v_lshlrev_b32_e32 v58, 16, v56
	v_and_b32_e32 v59, 0xffff0000, v56
	v_rcp_f32_e32 v62, v53
	s_nop 0
	v_mul_f32_e32 v53, 1.0, v62
	v_rcp_f32_e32 v62, v52
	s_nop 0
	v_mul_f32_e32 v52, 1.0, v62
	v_pk_mul_f32 v[52:53], v[52:53], v[58:59]
	v_rcp_f32_e32 v59, v55
	v_lshlrev_b32_e32 v56, 16, v57
	v_and_b32_e32 v57, 0xffff0000, v57
	v_cvt_pk_bf16_f32 v52, v52, v53
	v_mul_f32_e32 v55, 1.0, v59
	v_rcp_f32_e32 v59, v54
	s_nop 0
	v_mul_f32_e32 v54, 1.0, v59
	v_pk_mul_f32 v[54:55], v[54:55], v[56:57]
	s_nop 0
	v_cvt_pk_bf16_f32 v53, v54, v55
	global_store_dwordx2 v[60:61], v[52:53], off offset:256
	global_load_dwordx2 v[52:53], v[64:65], off offset:288
	s_waitcnt vmcnt(0) lgkmcnt(0)
	v_lshlrev_b32_e32 v54, 16, v52
	v_and_b32_e32 v55, 0xffff0000, v52
	v_rcp_f32_e32 v56, v49
	s_nop 0
	v_mul_f32_e32 v49, 1.0, v56
	v_rcp_f32_e32 v56, v48
	s_nop 0
	v_mul_f32_e32 v48, 1.0, v56
	v_pk_mul_f32 v[48:49], v[48:49], v[54:55]
	v_rcp_f32_e32 v55, v51
	v_lshlrev_b32_e32 v52, 16, v53
	v_and_b32_e32 v53, 0xffff0000, v53
	v_cvt_pk_bf16_f32 v48, v48, v49
	v_mul_f32_e32 v51, 1.0, v55
	v_rcp_f32_e32 v55, v50
	s_nop 0
	v_mul_f32_e32 v50, 1.0, v55
	v_pk_mul_f32 v[50:51], v[50:51], v[52:53]
	s_nop 0
	v_cvt_pk_bf16_f32 v49, v50, v51
	global_store_dwordx2 v[60:61], v[48:49], off offset:288
	v_add_u32_e32 v48, 0x90, v140
	v_ashrrev_i32_e32 v49, 31, v48
	v_lshlrev_b64 v[52:53], 10, v[48:49]
	v_lshlrev_b64 v[50:51], 11, v[48:49]
	v_lshl_add_u64 v[48:49], s[44:45], 0, v[52:53]
	v_lshl_add_u64 v[48:49], v[48:49], 0, v[138:139]
	global_load_dwordx2 v[52:53], v[48:49], off
	s_waitcnt vmcnt(0) lgkmcnt(0)
	v_lshlrev_b32_e32 v54, 16, v52
	v_and_b32_e32 v55, 0xffff0000, v52
	v_rcp_f32_e32 v56, v45
	s_nop 0
	v_mul_f32_e32 v45, 1.0, v56
	v_rcp_f32_e32 v56, v44
	s_nop 0
	v_mul_f32_e32 v44, 1.0, v56
	v_pk_mul_f32 v[44:45], v[44:45], v[54:55]
	v_rcp_f32_e32 v55, v47
	v_lshlrev_b32_e32 v52, 16, v53
	v_and_b32_e32 v53, 0xffff0000, v53
	v_mul_f32_e32 v47, 1.0, v55
	v_rcp_f32_e32 v55, v46
	s_nop 0
	v_mul_f32_e32 v46, 1.0, v55
	v_pk_mul_f32 v[46:47], v[46:47], v[52:53]
	v_cvt_pk_bf16_f32 v52, v44, v45
	v_cvt_pk_bf16_f32 v53, v46, v47
	global_load_dwordx2 v[46:47], v[48:49], off offset:32
	v_lshl_add_u64 v[44:45], s[2:3], 0, v[50:51]
	v_lshl_add_u64 v[44:45], v[44:45], 0, v[138:139]
	global_store_dwordx2 v[44:45], v[52:53], off
	s_waitcnt vmcnt(0) lgkmcnt(0)
	v_lshlrev_b32_e32 v50, 16, v46
	v_and_b32_e32 v51, 0xffff0000, v46
	v_rcp_f32_e32 v52, v41
	s_nop 0
	v_mul_f32_e32 v41, 1.0, v52
	v_rcp_f32_e32 v52, v40
	s_nop 0
	v_mul_f32_e32 v40, 1.0, v52
	v_pk_mul_f32 v[40:41], v[40:41], v[50:51]
	v_rcp_f32_e32 v51, v43
	v_lshlrev_b32_e32 v46, 16, v47
	v_and_b32_e32 v47, 0xffff0000, v47
	v_cvt_pk_bf16_f32 v40, v40, v41
	v_mul_f32_e32 v43, 1.0, v51
	v_rcp_f32_e32 v51, v42
	s_nop 0
	v_mul_f32_e32 v42, 1.0, v51
	v_pk_mul_f32 v[42:43], v[42:43], v[46:47]
	s_nop 0
	v_cvt_pk_bf16_f32 v41, v42, v43
	global_store_dwordx2 v[44:45], v[40:41], off offset:32
	global_load_dwordx2 v[40:41], v[48:49], off offset:256
	s_waitcnt vmcnt(0) lgkmcnt(0)
	v_lshlrev_b32_e32 v42, 16, v40
	v_and_b32_e32 v43, 0xffff0000, v40
	v_rcp_f32_e32 v46, v37
	s_nop 0
	v_mul_f32_e32 v37, 1.0, v46
	v_rcp_f32_e32 v46, v36
	s_nop 0
	v_mul_f32_e32 v36, 1.0, v46
	v_pk_mul_f32 v[36:37], v[36:37], v[42:43]
	v_rcp_f32_e32 v43, v39
	v_lshlrev_b32_e32 v40, 16, v41
	v_and_b32_e32 v41, 0xffff0000, v41
	v_cvt_pk_bf16_f32 v36, v36, v37
	v_mul_f32_e32 v39, 1.0, v43
	v_rcp_f32_e32 v43, v38
	s_nop 0
	v_mul_f32_e32 v38, 1.0, v43
	v_pk_mul_f32 v[38:39], v[38:39], v[40:41]
	s_nop 0
	v_cvt_pk_bf16_f32 v37, v38, v39
	global_store_dwordx2 v[44:45], v[36:37], off offset:256
	global_load_dwordx2 v[36:37], v[48:49], off offset:288
	s_waitcnt vmcnt(0) lgkmcnt(0)
	v_lshlrev_b32_e32 v38, 16, v36
	v_and_b32_e32 v39, 0xffff0000, v36
	v_rcp_f32_e32 v40, v33
	s_nop 0
	v_mul_f32_e32 v33, 1.0, v40
	v_rcp_f32_e32 v40, v32
	s_nop 0
	v_mul_f32_e32 v32, 1.0, v40
	v_pk_mul_f32 v[32:33], v[32:33], v[38:39]
	v_rcp_f32_e32 v39, v35
	v_lshlrev_b32_e32 v36, 16, v37
	v_and_b32_e32 v37, 0xffff0000, v37
	v_cvt_pk_bf16_f32 v32, v32, v33
	v_mul_f32_e32 v35, 1.0, v39
	v_rcp_f32_e32 v39, v34
	s_nop 0
	v_mul_f32_e32 v34, 1.0, v39
	v_pk_mul_f32 v[34:35], v[34:35], v[36:37]
	s_nop 0
	v_cvt_pk_bf16_f32 v33, v34, v35
	global_store_dwordx2 v[44:45], v[32:33], off offset:288
	v_add_u32_e32 v32, 0xa0, v140
	v_ashrrev_i32_e32 v33, 31, v32
	v_lshlrev_b64 v[36:37], 10, v[32:33]
	v_lshlrev_b64 v[34:35], 11, v[32:33]
	v_lshl_add_u64 v[32:33], s[44:45], 0, v[36:37]
	v_lshl_add_u64 v[32:33], v[32:33], 0, v[138:139]
	global_load_dwordx2 v[36:37], v[32:33], off
	s_waitcnt vmcnt(0) lgkmcnt(0)
	v_lshlrev_b32_e32 v38, 16, v36
	v_and_b32_e32 v39, 0xffff0000, v36
	v_rcp_f32_e32 v40, v29
	s_nop 0
	v_mul_f32_e32 v29, 1.0, v40
	v_rcp_f32_e32 v40, v28
	s_nop 0
	v_mul_f32_e32 v28, 1.0, v40
	v_pk_mul_f32 v[28:29], v[28:29], v[38:39]
	v_rcp_f32_e32 v39, v31
	v_lshlrev_b32_e32 v36, 16, v37
	v_and_b32_e32 v37, 0xffff0000, v37
	v_mul_f32_e32 v31, 1.0, v39
	v_rcp_f32_e32 v39, v30
	s_nop 0
	v_mul_f32_e32 v30, 1.0, v39
	v_pk_mul_f32 v[30:31], v[30:31], v[36:37]
	v_cvt_pk_bf16_f32 v36, v28, v29
	v_cvt_pk_bf16_f32 v37, v30, v31
	global_load_dwordx2 v[30:31], v[32:33], off offset:32
	v_lshl_add_u64 v[28:29], s[2:3], 0, v[34:35]
	v_lshl_add_u64 v[28:29], v[28:29], 0, v[138:139]
	global_store_dwordx2 v[28:29], v[36:37], off
	s_waitcnt vmcnt(0) lgkmcnt(0)
	v_lshlrev_b32_e32 v34, 16, v30
	v_and_b32_e32 v35, 0xffff0000, v30
	v_rcp_f32_e32 v36, v25
	s_nop 0
	v_mul_f32_e32 v25, 1.0, v36
	v_rcp_f32_e32 v36, v24
	s_nop 0
	v_mul_f32_e32 v24, 1.0, v36
	v_pk_mul_f32 v[24:25], v[24:25], v[34:35]
	v_rcp_f32_e32 v35, v27
	v_lshlrev_b32_e32 v30, 16, v31
	v_and_b32_e32 v31, 0xffff0000, v31
	v_cvt_pk_bf16_f32 v24, v24, v25
	v_mul_f32_e32 v27, 1.0, v35
	v_rcp_f32_e32 v35, v26
	s_nop 0
	v_mul_f32_e32 v26, 1.0, v35
	v_pk_mul_f32 v[26:27], v[26:27], v[30:31]
	s_nop 0
	v_cvt_pk_bf16_f32 v25, v26, v27
	global_store_dwordx2 v[28:29], v[24:25], off offset:32
	global_load_dwordx2 v[24:25], v[32:33], off offset:256
	s_waitcnt vmcnt(0) lgkmcnt(0)
	v_lshlrev_b32_e32 v26, 16, v24
	v_and_b32_e32 v27, 0xffff0000, v24
	v_rcp_f32_e32 v30, v21
	s_nop 0
	v_mul_f32_e32 v21, 1.0, v30
	v_rcp_f32_e32 v30, v20
	s_nop 0
	v_mul_f32_e32 v20, 1.0, v30
	v_pk_mul_f32 v[20:21], v[20:21], v[26:27]
	v_rcp_f32_e32 v27, v23
	v_lshlrev_b32_e32 v24, 16, v25
	v_and_b32_e32 v25, 0xffff0000, v25
	v_cvt_pk_bf16_f32 v20, v20, v21
	v_mul_f32_e32 v23, 1.0, v27
	v_rcp_f32_e32 v27, v22
	s_nop 0
	v_mul_f32_e32 v22, 1.0, v27
	v_pk_mul_f32 v[22:23], v[22:23], v[24:25]
	s_nop 0
	v_cvt_pk_bf16_f32 v21, v22, v23
	global_store_dwordx2 v[28:29], v[20:21], off offset:256
	global_load_dwordx2 v[20:21], v[32:33], off offset:288
	s_waitcnt vmcnt(0) lgkmcnt(0)
	v_lshlrev_b32_e32 v22, 16, v20
	v_and_b32_e32 v23, 0xffff0000, v20
	v_rcp_f32_e32 v24, v17
	s_nop 0
	v_mul_f32_e32 v17, 1.0, v24
	v_rcp_f32_e32 v24, v16
	s_nop 0
	v_mul_f32_e32 v16, 1.0, v24
	v_pk_mul_f32 v[16:17], v[16:17], v[22:23]
	v_rcp_f32_e32 v23, v19
	v_lshlrev_b32_e32 v20, 16, v21
	v_and_b32_e32 v21, 0xffff0000, v21
	v_cvt_pk_bf16_f32 v16, v16, v17
	v_mul_f32_e32 v19, 1.0, v23
	v_rcp_f32_e32 v23, v18
	s_nop 0
	v_mul_f32_e32 v18, 1.0, v23
	v_pk_mul_f32 v[18:19], v[18:19], v[20:21]
	s_nop 0
	v_cvt_pk_bf16_f32 v17, v18, v19
	global_store_dwordx2 v[28:29], v[16:17], off offset:288
	v_add_u32_e32 v16, 0xb0, v140
	v_ashrrev_i32_e32 v17, 31, v16
	v_lshlrev_b64 v[20:21], 10, v[16:17]
	v_lshlrev_b64 v[18:19], 11, v[16:17]
	v_lshl_add_u64 v[16:17], s[44:45], 0, v[20:21]
	v_lshl_add_u64 v[16:17], v[16:17], 0, v[138:139]
	global_load_dwordx2 v[20:21], v[16:17], off
	s_waitcnt vmcnt(0) lgkmcnt(0)
	v_lshlrev_b32_e32 v22, 16, v20
	v_and_b32_e32 v23, 0xffff0000, v20
	v_rcp_f32_e32 v24, v13
	s_nop 0
	v_mul_f32_e32 v13, 1.0, v24
	v_rcp_f32_e32 v24, v12
	s_nop 0
	v_mul_f32_e32 v12, 1.0, v24
	v_pk_mul_f32 v[12:13], v[12:13], v[22:23]
	v_rcp_f32_e32 v23, v15
	v_lshlrev_b32_e32 v20, 16, v21
	v_and_b32_e32 v21, 0xffff0000, v21
	v_mul_f32_e32 v15, 1.0, v23
	v_rcp_f32_e32 v23, v14
	s_nop 0
	v_mul_f32_e32 v14, 1.0, v23
	v_pk_mul_f32 v[14:15], v[14:15], v[20:21]
	v_cvt_pk_bf16_f32 v20, v12, v13
	v_cvt_pk_bf16_f32 v21, v14, v15
	global_load_dwordx2 v[14:15], v[16:17], off offset:32
	v_lshl_add_u64 v[12:13], s[2:3], 0, v[18:19]
	v_lshl_add_u64 v[12:13], v[12:13], 0, v[138:139]
	global_store_dwordx2 v[12:13], v[20:21], off
	s_mov_b64 s[2:3], s[54:55]
	s_waitcnt vmcnt(0) lgkmcnt(0)
	v_lshlrev_b32_e32 v18, 16, v14
	v_and_b32_e32 v19, 0xffff0000, v14
	v_rcp_f32_e32 v20, v9
	s_nop 0
	v_mul_f32_e32 v9, 1.0, v20
	v_rcp_f32_e32 v20, v8
	s_nop 0
	v_mul_f32_e32 v8, 1.0, v20
	v_pk_mul_f32 v[8:9], v[8:9], v[18:19]
	v_rcp_f32_e32 v19, v11
	v_lshlrev_b32_e32 v14, 16, v15
	v_and_b32_e32 v15, 0xffff0000, v15
	v_cvt_pk_bf16_f32 v8, v8, v9
	v_mul_f32_e32 v11, 1.0, v19
	v_rcp_f32_e32 v19, v10
	s_nop 0
	v_mul_f32_e32 v10, 1.0, v19
	v_pk_mul_f32 v[10:11], v[10:11], v[14:15]
	s_nop 0
	v_cvt_pk_bf16_f32 v9, v10, v11
	global_store_dwordx2 v[12:13], v[8:9], off offset:32
	global_load_dwordx2 v[8:9], v[16:17], off offset:256
	s_waitcnt vmcnt(0) lgkmcnt(0)
	v_lshlrev_b32_e32 v10, 16, v8
	v_and_b32_e32 v11, 0xffff0000, v8
	v_rcp_f32_e32 v14, v5
	s_nop 0
	v_mul_f32_e32 v5, 1.0, v14
	v_rcp_f32_e32 v14, v4
	s_nop 0
	v_mul_f32_e32 v4, 1.0, v14
	v_pk_mul_f32 v[4:5], v[4:5], v[10:11]
	v_rcp_f32_e32 v11, v7
	v_lshlrev_b32_e32 v8, 16, v9
	v_and_b32_e32 v9, 0xffff0000, v9
	v_cvt_pk_bf16_f32 v4, v4, v5
	v_mul_f32_e32 v7, 1.0, v11
	v_rcp_f32_e32 v11, v6
	s_nop 0
	v_mul_f32_e32 v6, 1.0, v11
	v_pk_mul_f32 v[6:7], v[6:7], v[8:9]
	s_nop 0
	v_cvt_pk_bf16_f32 v5, v6, v7
	global_store_dwordx2 v[12:13], v[4:5], off offset:256
	global_load_dwordx2 v[4:5], v[16:17], off offset:288
	s_waitcnt vmcnt(0) lgkmcnt(0)
	v_lshlrev_b32_e32 v6, 16, v4
	v_and_b32_e32 v7, 0xffff0000, v4
	v_rcp_f32_e32 v8, v1
	s_nop 0
	v_mul_f32_e32 v1, 1.0, v8
	v_rcp_f32_e32 v8, v0
	s_nop 0
	v_mul_f32_e32 v0, 1.0, v8
	v_pk_mul_f32 v[0:1], v[0:1], v[6:7]
	v_rcp_f32_e32 v7, v3
	v_lshlrev_b32_e32 v4, 16, v5
	v_and_b32_e32 v5, 0xffff0000, v5
	v_cvt_pk_bf16_f32 v0, v0, v1
	v_mul_f32_e32 v3, 1.0, v7
	s_nop 0
	v_rcp_f32_e32 v7, v2
	s_nop 8
	v_mul_f32_e32 v2, 1.0, v7
	v_pk_mul_f32 v[2:3], v[2:3], v[4:5]
	s_and_b64 vcc, exec, s[42:43]
	v_cvt_pk_bf16_f32 v1, v2, v3
	global_store_dwordx2 v[12:13], v[0:1], off offset:288
	s_cbranch_vccnz .LBB0_1978

.Lconv_store_3:
	ds_read2_b32 v[18:19], v13 offset1:8
	v_add_u32_e32 v16, s6, v15
	s_ashr_i32 s3, s2, 31
	v_ashrrev_i32_e32 v17, 31, v16
	v_lshl_add_u64 v[2:3], s[2:3], 1, v[0:1]
	v_lshlrev_b64 v[20:21], 11, v[16:17]
	s_waitcnt lgkmcnt(0)
	v_cvt_pk_bf16_f32 v18, v18, s0
	v_lshl_add_u64 v[20:21], v[2:3], 0, v[20:21]
	global_store_short v[20:21], v18, off
	v_add_u32_e32 v18, 8, v16
	v_cvt_pk_bf16_f32 v17, v19, s0
	v_ashrrev_i32_e32 v19, 31, v18
	v_lshlrev_b64 v[18:19], 11, v[18:19]
	ds_read2_b32 v[20:21], v13 offset0:16 offset1:24
	v_lshl_add_u64 v[18:19], v[2:3], 0, v[18:19]
	global_store_short v[18:19], v17, off
	v_add_u32_e32 v18, 16, v16
	v_ashrrev_i32_e32 v19, 31, v18
	v_lshlrev_b64 v[18:19], 11, v[18:19]
	s_waitcnt lgkmcnt(0)
	v_cvt_pk_bf16_f32 v17, v20, s0
	v_lshl_add_u64 v[18:19], v[2:3], 0, v[18:19]
	global_store_short v[18:19], v17, off
	v_add_u32_e32 v18, 24, v16
	v_ashrrev_i32_e32 v19, 31, v18
	v_cvt_pk_bf16_f32 v17, v21, s0
	v_lshlrev_b64 v[18:19], 11, v[18:19]
	ds_read2_b32 v[20:21], v13 offset0:32 offset1:40
	v_lshl_add_u64 v[18:19], v[2:3], 0, v[18:19]
	global_store_short v[18:19], v17, off
	v_add_u32_e32 v18, 32, v16
	v_ashrrev_i32_e32 v19, 31, v18
	v_lshlrev_b64 v[18:19], 11, v[18:19]
	s_waitcnt lgkmcnt(0)
	v_cvt_pk_bf16_f32 v17, v20, s0
	v_lshl_add_u64 v[18:19], v[2:3], 0, v[18:19]
	global_store_short v[18:19], v17, off
	v_add_u32_e32 v18, 40, v16
	v_ashrrev_i32_e32 v19, 31, v18
	v_cvt_pk_bf16_f32 v17, v21, s0
	v_lshlrev_b64 v[18:19], 11, v[18:19]
	ds_read2_b32 v[20:21], v13 offset0:48 offset1:56
	v_lshl_add_u64 v[18:19], v[2:3], 0, v[18:19]
	global_store_short v[18:19], v17, off
	v_add_u32_e32 v18, 48, v16
	v_ashrrev_i32_e32 v19, 31, v18
	v_lshlrev_b64 v[18:19], 11, v[18:19]
	s_waitcnt lgkmcnt(0)
	v_cvt_pk_bf16_f32 v17, v20, s0
	v_lshl_add_u64 v[18:19], v[2:3], 0, v[18:19]
	v_add_u32_e32 v16, 56, v16
	global_store_short v[18:19], v17, off
	v_ashrrev_i32_e32 v17, 31, v16
	v_readlane_b32 s2, v251, 1
	v_lshlrev_b64 v[16:17], 11, v[16:17]
	s_add_i32 s5, s5, s2
	v_readlane_b32 s2, v254, 58
	v_cvt_pk_bf16_f32 v18, v21, s0
	v_lshl_add_u64 v[2:3], v[2:3], 0, v[16:17]
	v_add_u32_e32 v15, s2, v15
	v_add_u32_e32 v5, s2, v5
	s_cmpk_lt_i32 s5, 0x480
	global_store_short v[2:3], v18, off
	s_waitcnt lgkmcnt(0)
	s_barrier
	v_readlane_b32 s3, v251, 2
	s_cbranch_scc0 .LBB0_2296
.LBB0_2288:
	s_mul_hi_i32 s2, s5, 0x38e38e39
	s_lshr_b32 s3, s2, 31
	s_ashr_i32 s7, s2, 4
	s_add_i32 s7, s7, s3
	s_mul_i32 s6, s7, 0xffffee00
	s_add_i32 s6, s6, s10
	v_add_u32_e32 v2, s6, v5
	s_movk_i32 s2, 0x11ff
	v_cmp_lt_i32_e32 vcc, s2, v2
	v_ashrrev_i32_e32 v3, 31, v2
	s_lshl_b32 s2, s7, 6
	v_lshl_add_u64 v[2:3], v[2:3], 2, s[18:19]
	s_movk_i32 s3, 0x4800
	v_mov_b32_e32 v100, 0
	v_mov_b32_e32 v101, 0
	v_mov_b32_e32 v102, 0
	v_mov_b32_e32 v103, 0
	v_mov_b32_e32 v104, 0
	v_mov_b32_e32 v105, 0
	v_mov_b32_e32 v106, 0
	v_mov_b32_e32 v107, 0
	s_mov_b64 s[42:43], exec
	s_andn2_b64 exec, exec, vcc
	s_cbranch_execz .Lconv_merge_3
	v_add_u32_e32 v124, s2, v4
	v_mad_i64_i32 v[108:109], s[8:9], v124, s3, v[2:3]
	v_add_u32_e32 v124, s2, v6
	v_mad_i64_i32 v[110:111], s[8:9], v124, s3, v[2:3]
	v_add_u32_e32 v124, s2, v7
	v_mad_i64_i32 v[112:113], s[8:9], v124, s3, v[2:3]
	v_add_u32_e32 v124, s2, v8
	v_mad_i64_i32 v[114:115], s[8:9], v124, s3, v[2:3]
	v_add_u32_e32 v124, s2, v9
	v_mad_i64_i32 v[116:117], s[8:9], v124, s3, v[2:3]
	v_add_u32_e32 v124, s2, v10
	v_mad_i64_i32 v[118:119], s[8:9], v124, s3, v[2:3]
	v_add_u32_e32 v124, s2, v11
	v_mad_i64_i32 v[120:121], s[8:9], v124, s3, v[2:3]
	v_add_u32_e32 v124, s2, v12
	v_mad_i64_i32 v[122:123], s[8:9], v124, s3, v[2:3]
	global_load_dword v100, v[108:109], off
	global_load_dword v101, v[110:111], off
	global_load_dword v102, v[112:113], off
	global_load_dword v103, v[114:115], off
	global_load_dword v104, v[116:117], off
	global_load_dword v105, v[118:119], off
	global_load_dword v106, v[120:121], off
	global_load_dword v107, v[122:123], off
	s_waitcnt vmcnt(0)
.Lconv_merge_3:
	s_mov_b64 exec, s[42:43]
	ds_write_b32 v14, v100
	ds_write_b32 v14, v101 offset:2080
	ds_write_b32 v14, v102 offset:4160
	ds_write_b32 v14, v103 offset:6240
	ds_write_b32 v14, v104 offset:8320
	ds_write_b32 v14, v105 offset:10400
	ds_write_b32 v14, v106 offset:12480
	ds_write_b32 v14, v107 offset:14560
	s_waitcnt lgkmcnt(0)
	s_barrier
	s_branch .Lconv_store_3

.Lconv_store_4:
	ds_read2_b32 v[18:19], v13 offset1:8
	s_add_i32 s6, s6, s10
	v_add_u32_e32 v16, s6, v15
	s_ashr_i32 s3, s2, 31
	v_ashrrev_i32_e32 v17, 31, v16
	v_lshl_add_u64 v[2:3], s[2:3], 1, v[0:1]
	v_lshlrev_b64 v[20:21], 11, v[16:17]
	s_waitcnt lgkmcnt(0)
	v_cvt_pk_bf16_f32 v18, v18, s0
	v_lshl_add_u64 v[20:21], v[2:3], 0, v[20:21]
	global_store_short v[20:21], v18, off
	v_add_u32_e32 v18, 8, v16
	v_cvt_pk_bf16_f32 v17, v19, s0
	v_ashrrev_i32_e32 v19, 31, v18
	v_lshlrev_b64 v[18:19], 11, v[18:19]
	ds_read2_b32 v[20:21], v13 offset0:16 offset1:24
	v_lshl_add_u64 v[18:19], v[2:3], 0, v[18:19]
	global_store_short v[18:19], v17, off
	v_add_u32_e32 v18, 16, v16
	v_ashrrev_i32_e32 v19, 31, v18
	v_lshlrev_b64 v[18:19], 11, v[18:19]
	s_waitcnt lgkmcnt(0)
	v_cvt_pk_bf16_f32 v17, v20, s0
	v_lshl_add_u64 v[18:19], v[2:3], 0, v[18:19]
	global_store_short v[18:19], v17, off
	v_add_u32_e32 v18, 24, v16
	v_ashrrev_i32_e32 v19, 31, v18
	v_cvt_pk_bf16_f32 v17, v21, s0
	v_lshlrev_b64 v[18:19], 11, v[18:19]
	ds_read2_b32 v[20:21], v13 offset0:32 offset1:40
	v_lshl_add_u64 v[18:19], v[2:3], 0, v[18:19]
	global_store_short v[18:19], v17, off
	v_add_u32_e32 v18, 32, v16
	v_ashrrev_i32_e32 v19, 31, v18
	v_lshlrev_b64 v[18:19], 11, v[18:19]
	s_waitcnt lgkmcnt(0)
	v_cvt_pk_bf16_f32 v17, v20, s0
	v_lshl_add_u64 v[18:19], v[2:3], 0, v[18:19]
	global_store_short v[18:19], v17, off
	v_add_u32_e32 v18, 40, v16
	v_ashrrev_i32_e32 v19, 31, v18
	v_cvt_pk_bf16_f32 v17, v21, s0
	v_lshlrev_b64 v[18:19], 11, v[18:19]
	ds_read2_b32 v[20:21], v13 offset0:48 offset1:56
	v_lshl_add_u64 v[18:19], v[2:3], 0, v[18:19]
	global_store_short v[18:19], v17, off
	v_add_u32_e32 v18, 48, v16
	v_ashrrev_i32_e32 v19, 31, v18
	v_lshlrev_b64 v[18:19], 11, v[18:19]
	s_waitcnt lgkmcnt(0)
	v_cvt_pk_bf16_f32 v17, v20, s0
	v_lshl_add_u64 v[18:19], v[2:3], 0, v[18:19]
	v_add_u32_e32 v16, 56, v16
	global_store_short v[18:19], v17, off
	v_ashrrev_i32_e32 v17, 31, v16
	v_readlane_b32 s2, v251, 1
	v_lshlrev_b64 v[16:17], 11, v[16:17]
	s_add_i32 s5, s5, s2
	v_readlane_b32 s2, v254, 58
	v_cvt_pk_bf16_f32 v18, v21, s0
	v_lshl_add_u64 v[2:3], v[2:3], 0, v[16:17]
	v_add_u32_e32 v15, s2, v15
	v_add_u32_e32 v5, s2, v5
	s_cmpk_gt_i32 s5, 0xff
	global_store_short v[2:3], v18, off
	s_waitcnt lgkmcnt(0)
	s_barrier
	v_readlane_b32 s3, v251, 2
	s_cbranch_scc1 .LBB0_2307
.LBB0_2299:
	s_ashr_i32 s2, s5, 31
	s_lshr_b32 s2, s2, 28
	s_add_i32 s2, s5, s2
	s_ashr_i32 s7, s2, 4
	s_lshl_b32 s6, s7, 10
	s_sub_i32 s2, s10, s6
	v_add_u32_e32 v2, s2, v5
	s_movk_i32 s2, 0x3ff
	v_cmp_lt_i32_e32 vcc, s2, v2
	v_ashrrev_i32_e32 v3, 31, v2
	s_lshl_b32 s2, s7, 6
	v_lshl_add_u64 v[2:3], v[2:3], 2, s[0:1]
	s_movk_i32 s3, 0x1000
	v_mov_b32_e32 v100, 0
	v_mov_b32_e32 v101, 0
	v_mov_b32_e32 v102, 0
	v_mov_b32_e32 v103, 0
	v_mov_b32_e32 v104, 0
	v_mov_b32_e32 v105, 0
	v_mov_b32_e32 v106, 0
	v_mov_b32_e32 v107, 0
	s_mov_b64 s[18:19], exec
	s_andn2_b64 exec, exec, vcc
	s_cbranch_execz .Lconv_merge_4
	v_add_u32_e32 v124, s2, v4
	v_mad_i64_i32 v[108:109], s[8:9], v124, s3, v[2:3]
	v_add_u32_e32 v124, s2, v6
	v_mad_i64_i32 v[110:111], s[8:9], v124, s3, v[2:3]
	v_add_u32_e32 v124, s2, v7
	v_mad_i64_i32 v[112:113], s[8:9], v124, s3, v[2:3]
	v_add_u32_e32 v124, s2, v8
	v_mad_i64_i32 v[114:115], s[8:9], v124, s3, v[2:3]
	v_add_u32_e32 v124, s2, v9
	v_mad_i64_i32 v[116:117], s[8:9], v124, s3, v[2:3]
	v_add_u32_e32 v124, s2, v10
	v_mad_i64_i32 v[118:119], s[8:9], v124, s3, v[2:3]
	v_add_u32_e32 v124, s2, v11
	v_mad_i64_i32 v[120:121], s[8:9], v124, s3, v[2:3]
	v_add_u32_e32 v124, s2, v12
	v_mad_i64_i32 v[122:123], s[8:9], v124, s3, v[2:3]
	global_load_dword v100, v[108:109], off
	global_load_dword v101, v[110:111], off
	global_load_dword v102, v[112:113], off
	global_load_dword v103, v[114:115], off
	global_load_dword v104, v[116:117], off
	global_load_dword v105, v[118:119], off
	global_load_dword v106, v[120:121], off
	global_load_dword v107, v[122:123], off
	s_waitcnt vmcnt(0)
.Lconv_merge_4:
	s_mov_b64 exec, s[18:19]
	ds_write_b32 v14, v100
	ds_write_b32 v14, v101 offset:2080
	ds_write_b32 v14, v102 offset:4160
	ds_write_b32 v14, v103 offset:6240
	ds_write_b32 v14, v104 offset:8320
	ds_write_b32 v14, v105 offset:10400
	ds_write_b32 v14, v106 offset:12480
	ds_write_b32 v14, v107 offset:14560
	s_sub_i32 s6, 0, s6
	s_waitcnt lgkmcnt(0)
	s_barrier
	s_branch .Lconv_store_4

.LBB0_2364:
	v_mov_b32_e32 v138, v128
	v_mov_b32_e32 v139, v140
	s_lshl_b32 s0, s59, 8
	s_add_i32 s0, s0, s22
	v_add_u32_e32 v143, s0, v138
	v_lshlrev_b32_e32 v138, 2, v139
	v_mul_f32_e32 v139, 0xbfb8aa3b, v124
	v_exp_f32_e32 v146, v139
	v_mul_f32_e32 v139, 0xbfb8aa3b, v125
	v_exp_f32_e32 v147, v139
	s_lshl_b32 s0, s58, 8
	s_or_b32 s0, s0, s23
	s_ashr_i32 s0, s0, 1
	v_pk_add_f32 v[146:147], v[146:147], 1.0 op_sel_hi:[1,0]
	v_add_u32_e32 v144, s0, v138
	v_rcp_f32_e32 v145, v147
	s_movk_i32 s49, 0x1600
	s_ashr_i32 s1, s0, 31
	s_mov_b32 s58, s48
	v_mul_f32_e32 v125, v125, v145
	v_rcp_f32_e32 v145, v146
	s_mov_b32 s59, s50
	s_mov_b64 s[54:55], s[2:3]
	v_mul_f32_e32 v124, v124, v145
	v_pk_mul_f32 v[120:121], v[120:121], v[124:125]
	v_mul_f32_e32 v124, 0xbfb8aa3b, v126
	v_mul_f32_e32 v125, 0xbfb8aa3b, v127
	v_exp_f32_e32 v124, v124
	v_exp_f32_e32 v125, v125
	s_nop 0
	v_pk_add_f32 v[124:125], v[124:125], 1.0 op_sel_hi:[1,0]
	s_nop 0
	v_rcp_f32_e32 v145, v125
	s_nop 0
	v_mul_f32_e32 v125, v127, v145
	v_rcp_f32_e32 v139, v124
	s_nop 0
	v_mul_f32_e32 v124, v126, v139
	v_pk_mul_f32 v[122:123], v[122:123], v[124:125]
	v_cvt_pk_bf16_f32 v124, v120, v121
	v_mov_b64_e32 v[120:121], s[36:37]
	v_ashrrev_i32_e32 v145, 31, v144
	v_cvt_pk_bf16_f32 v125, v122, v123
	v_mad_i64_i32 v[126:127], s[18:19], v143, s49, v[120:121]
	v_lshlrev_b64 v[122:123], 1, v[144:145]
	v_lshl_add_u64 v[144:145], v[126:127], 0, v[122:123]
	global_store_dwordx2 v[144:145], v[124:125], off
	v_mul_f32_e32 v124, 0xbfb8aa3b, v116
	v_mul_f32_e32 v125, 0xbfb8aa3b, v117
	v_exp_f32_e32 v124, v124
	v_exp_f32_e32 v125, v125
	s_nop 0
	v_pk_add_f32 v[124:125], v[124:125], 1.0 op_sel_hi:[1,0]
	s_nop 0
	v_rcp_f32_e32 v144, v125
	s_nop 0
	v_mul_f32_e32 v117, v117, v144
	v_rcp_f32_e32 v139, v124
	s_nop 0
	v_mul_f32_e32 v116, v116, v139
	v_pk_mul_f32 v[112:113], v[112:113], v[116:117]
	v_mul_f32_e32 v116, 0xbfb8aa3b, v118
	v_mul_f32_e32 v117, 0xbfb8aa3b, v119
	v_exp_f32_e32 v116, v116
	v_exp_f32_e32 v117, v117
	s_nop 0
	v_pk_add_f32 v[116:117], v[116:117], 1.0 op_sel_hi:[1,0]
	s_nop 0
	v_rcp_f32_e32 v125, v117
	s_nop 0
	v_mul_f32_e32 v117, v119, v125
	v_rcp_f32_e32 v124, v116
	s_mov_b64 s[18:19], s[52:53]
	v_mul_f32_e32 v116, v118, v124
	v_ashrrev_i32_e32 v139, 31, v138
	v_pk_mul_f32 v[114:115], v[114:115], v[116:117]
	v_cvt_pk_bf16_f32 v116, v112, v113
	v_lshl_add_u64 v[112:113], s[0:1], 0, v[138:139]
	v_lshlrev_b64 v[112:113], 1, v[112:113]
	v_cvt_pk_bf16_f32 v117, v114, v115
	v_lshl_add_u64 v[114:115], v[126:127], 0, v[112:113]
	global_store_dwordx2 v[114:115], v[116:117], off offset:128
	v_mul_f32_e32 v114, 0xbfb8aa3b, v108
	v_mul_f32_e32 v115, 0xbfb8aa3b, v109
	v_exp_f32_e32 v114, v114
	v_exp_f32_e32 v115, v115
	v_add_u32_e32 v116, 16, v143
	v_pk_add_f32 v[114:115], v[114:115], 1.0 op_sel_hi:[1,0]
	s_nop 0
	v_rcp_f32_e32 v118, v115
	s_nop 0
	v_mul_f32_e32 v109, v109, v118
	v_rcp_f32_e32 v117, v114
	s_nop 0
	v_mul_f32_e32 v108, v108, v117
	v_pk_mul_f32 v[104:105], v[104:105], v[108:109]
	v_mul_f32_e32 v108, 0xbfb8aa3b, v110
	v_mul_f32_e32 v109, 0xbfb8aa3b, v111
	v_exp_f32_e32 v108, v108
	v_exp_f32_e32 v109, v109
	v_cvt_pk_bf16_f32 v104, v104, v105
	v_pk_add_f32 v[108:109], v[108:109], 1.0 op_sel_hi:[1,0]
	s_nop 0
	v_rcp_f32_e32 v115, v109
	s_nop 0
	v_mul_f32_e32 v109, v111, v115
	v_rcp_f32_e32 v114, v108
	s_nop 0
	v_mul_f32_e32 v108, v110, v114
	v_pk_mul_f32 v[106:107], v[106:107], v[108:109]
	s_nop 0
	v_cvt_pk_bf16_f32 v105, v106, v107
	v_mad_i64_i32 v[106:107], s[0:1], v116, s49, v[120:121]
	v_lshl_add_u64 v[108:109], v[106:107], 0, v[122:123]
	global_store_dwordx2 v[108:109], v[104:105], off
	v_mul_f32_e32 v104, 0xbfb8aa3b, v100
	v_mul_f32_e32 v105, 0xbfb8aa3b, v101
	v_exp_f32_e32 v104, v104
	v_exp_f32_e32 v105, v105
	s_nop 0
	v_pk_add_f32 v[104:105], v[104:105], 1.0 op_sel_hi:[1,0]
	s_nop 0
	v_rcp_f32_e32 v109, v105
	s_nop 0
	v_mul_f32_e32 v101, v101, v109
	v_rcp_f32_e32 v108, v104
	s_nop 0
	v_mul_f32_e32 v100, v100, v108
	v_pk_mul_f32 v[96:97], v[96:97], v[100:101]
	v_mul_f32_e32 v100, 0xbfb8aa3b, v102
	v_mul_f32_e32 v101, 0xbfb8aa3b, v103
	v_exp_f32_e32 v100, v100
	v_exp_f32_e32 v101, v101
	v_cvt_pk_bf16_f32 v96, v96, v97
	v_pk_add_f32 v[100:101], v[100:101], 1.0 op_sel_hi:[1,0]
	s_nop 0
	v_rcp_f32_e32 v105, v101
	s_nop 0
	v_mul_f32_e32 v101, v103, v105
	v_rcp_f32_e32 v104, v100
	s_nop 0
	v_mul_f32_e32 v100, v102, v104
	v_pk_mul_f32 v[98:99], v[98:99], v[100:101]
	s_nop 0
	v_cvt_pk_bf16_f32 v97, v98, v99
	v_lshl_add_u64 v[98:99], v[106:107], 0, v[112:113]
	global_store_dwordx2 v[98:99], v[96:97], off offset:128
	v_mul_f32_e32 v96, 0xbfb8aa3b, v92
	v_mul_f32_e32 v97, 0xbfb8aa3b, v93
	v_exp_f32_e32 v96, v96
	v_exp_f32_e32 v97, v97
	v_add_u32_e32 v98, 32, v143
	v_pk_add_f32 v[96:97], v[96:97], 1.0 op_sel_hi:[1,0]
	s_nop 0
	v_rcp_f32_e32 v100, v97
	s_nop 0
	v_mul_f32_e32 v93, v93, v100
	v_rcp_f32_e32 v99, v96
	s_nop 0
	v_mul_f32_e32 v92, v92, v99
	v_pk_mul_f32 v[88:89], v[88:89], v[92:93]
	v_mul_f32_e32 v92, 0xbfb8aa3b, v94
	v_mul_f32_e32 v93, 0xbfb8aa3b, v95
	v_exp_f32_e32 v92, v92
	v_exp_f32_e32 v93, v93
	v_cvt_pk_bf16_f32 v88, v88, v89
	v_pk_add_f32 v[92:93], v[92:93], 1.0 op_sel_hi:[1,0]
	s_nop 0
	v_rcp_f32_e32 v97, v93
	s_nop 0
	v_mul_f32_e32 v93, v95, v97
	v_rcp_f32_e32 v96, v92
	s_nop 0
	v_mul_f32_e32 v92, v94, v96
	v_pk_mul_f32 v[90:91], v[90:91], v[92:93]
	s_nop 0
	v_cvt_pk_bf16_f32 v89, v90, v91
	v_mad_i64_i32 v[90:91], s[0:1], v98, s49, v[120:121]
	v_lshl_add_u64 v[92:93], v[90:91], 0, v[122:123]
	global_store_dwordx2 v[92:93], v[88:89], off
	v_mul_f32_e32 v88, 0xbfb8aa3b, v84
	v_mul_f32_e32 v89, 0xbfb8aa3b, v85
	v_exp_f32_e32 v88, v88
	v_exp_f32_e32 v89, v89
	s_nop 0
	v_pk_add_f32 v[88:89], v[88:89], 1.0 op_sel_hi:[1,0]
	s_nop 0
	v_rcp_f32_e32 v93, v89
	s_nop 0
	v_mul_f32_e32 v85, v85, v93
	v_rcp_f32_e32 v92, v88
	s_nop 0
	v_mul_f32_e32 v84, v84, v92
	v_pk_mul_f32 v[80:81], v[80:81], v[84:85]
	v_mul_f32_e32 v84, 0xbfb8aa3b, v86
	v_mul_f32_e32 v85, 0xbfb8aa3b, v87
	v_exp_f32_e32 v84, v84
	v_exp_f32_e32 v85, v85
	v_cvt_pk_bf16_f32 v80, v80, v81
	v_pk_add_f32 v[84:85], v[84:85], 1.0 op_sel_hi:[1,0]
	s_nop 0
	v_rcp_f32_e32 v89, v85
	s_nop 0
	v_mul_f32_e32 v85, v87, v89
	v_rcp_f32_e32 v88, v84
	s_nop 0
	v_mul_f32_e32 v84, v86, v88
	v_pk_mul_f32 v[82:83], v[82:83], v[84:85]
	s_nop 0
	v_cvt_pk_bf16_f32 v81, v82, v83
	v_lshl_add_u64 v[82:83], v[90:91], 0, v[112:113]
	global_store_dwordx2 v[82:83], v[80:81], off offset:128
	v_mul_f32_e32 v80, 0xbfb8aa3b, v76
	v_mul_f32_e32 v81, 0xbfb8aa3b, v77
	v_exp_f32_e32 v80, v80
	v_exp_f32_e32 v81, v81
	v_add_u32_e32 v82, 48, v143
	v_pk_add_f32 v[80:81], v[80:81], 1.0 op_sel_hi:[1,0]
	s_nop 0
	v_rcp_f32_e32 v84, v81
	s_nop 0
	v_mul_f32_e32 v77, v77, v84
	v_rcp_f32_e32 v83, v80
	s_nop 0
	v_mul_f32_e32 v76, v76, v83
	v_pk_mul_f32 v[72:73], v[72:73], v[76:77]
	v_mul_f32_e32 v76, 0xbfb8aa3b, v78
	v_mul_f32_e32 v77, 0xbfb8aa3b, v79
	v_exp_f32_e32 v76, v76
	v_exp_f32_e32 v77, v77
	v_cvt_pk_bf16_f32 v72, v72, v73
	v_pk_add_f32 v[76:77], v[76:77], 1.0 op_sel_hi:[1,0]
	s_nop 0
	v_rcp_f32_e32 v81, v77
	s_nop 0
	v_mul_f32_e32 v77, v79, v81
	v_rcp_f32_e32 v80, v76
	s_nop 0
	v_mul_f32_e32 v76, v78, v80
	v_pk_mul_f32 v[74:75], v[74:75], v[76:77]
	s_nop 0
	v_cvt_pk_bf16_f32 v73, v74, v75
	v_mad_i64_i32 v[74:75], s[0:1], v82, s49, v[120:121]
	v_lshl_add_u64 v[76:77], v[74:75], 0, v[122:123]
	global_store_dwordx2 v[76:77], v[72:73], off
	v_mul_f32_e32 v72, 0xbfb8aa3b, v68
	v_mul_f32_e32 v73, 0xbfb8aa3b, v69
	v_exp_f32_e32 v72, v72
	v_exp_f32_e32 v73, v73
	s_nop 0
	v_pk_add_f32 v[72:73], v[72:73], 1.0 op_sel_hi:[1,0]
	s_nop 0
	v_rcp_f32_e32 v77, v73
	s_nop 0
	v_mul_f32_e32 v69, v69, v77
	v_rcp_f32_e32 v76, v72
	s_nop 0
	v_mul_f32_e32 v68, v68, v76
	v_pk_mul_f32 v[64:65], v[64:65], v[68:69]
	v_mul_f32_e32 v68, 0xbfb8aa3b, v70
	v_mul_f32_e32 v69, 0xbfb8aa3b, v71
	v_exp_f32_e32 v68, v68
	v_exp_f32_e32 v69, v69
	v_cvt_pk_bf16_f32 v64, v64, v65
	v_pk_add_f32 v[68:69], v[68:69], 1.0 op_sel_hi:[1,0]
	s_nop 0
	v_rcp_f32_e32 v73, v69
	s_nop 0
	v_mul_f32_e32 v69, v71, v73
	v_rcp_f32_e32 v72, v68
	s_nop 0
	v_mul_f32_e32 v68, v70, v72
	v_pk_mul_f32 v[66:67], v[66:67], v[68:69]
	s_nop 0
	v_cvt_pk_bf16_f32 v65, v66, v67
	v_lshl_add_u64 v[66:67], v[74:75], 0, v[112:113]
	global_store_dwordx2 v[66:67], v[64:65], off offset:128
	v_mul_f32_e32 v64, 0xbfb8aa3b, v60
	v_mul_f32_e32 v65, 0xbfb8aa3b, v61
	v_exp_f32_e32 v64, v64
	v_exp_f32_e32 v65, v65
	v_add_u32_e32 v66, 0x80, v143
	v_pk_add_f32 v[64:65], v[64:65], 1.0 op_sel_hi:[1,0]
	s_nop 0
	v_rcp_f32_e32 v68, v65
	s_nop 0
	v_mul_f32_e32 v61, v61, v68
	v_rcp_f32_e32 v67, v64
	s_nop 0
	v_mul_f32_e32 v60, v60, v67
	v_pk_mul_f32 v[56:57], v[56:57], v[60:61]
	v_mul_f32_e32 v60, 0xbfb8aa3b, v62
	v_mul_f32_e32 v61, 0xbfb8aa3b, v63
	v_exp_f32_e32 v60, v60
	v_exp_f32_e32 v61, v61
	v_cvt_pk_bf16_f32 v56, v56, v57
	v_pk_add_f32 v[60:61], v[60:61], 1.0 op_sel_hi:[1,0]
	s_nop 0
	v_rcp_f32_e32 v65, v61
	s_nop 0
	v_mul_f32_e32 v61, v63, v65
	v_rcp_f32_e32 v64, v60
	s_nop 0
	v_mul_f32_e32 v60, v62, v64
	v_pk_mul_f32 v[58:59], v[58:59], v[60:61]
	s_nop 0
	v_cvt_pk_bf16_f32 v57, v58, v59
	v_mad_i64_i32 v[58:59], s[0:1], v66, s49, v[120:121]
	v_lshl_add_u64 v[60:61], v[58:59], 0, v[122:123]
	global_store_dwordx2 v[60:61], v[56:57], off
	v_mul_f32_e32 v56, 0xbfb8aa3b, v52
	v_mul_f32_e32 v57, 0xbfb8aa3b, v53
	v_exp_f32_e32 v56, v56
	v_exp_f32_e32 v57, v57
	s_nop 0
	v_pk_add_f32 v[56:57], v[56:57], 1.0 op_sel_hi:[1,0]
	s_nop 0
	v_rcp_f32_e32 v61, v57
	s_nop 0
	v_mul_f32_e32 v53, v53, v61
	v_rcp_f32_e32 v60, v56
	s_nop 0
	v_mul_f32_e32 v52, v52, v60
	v_pk_mul_f32 v[48:49], v[48:49], v[52:53]
	v_mul_f32_e32 v52, 0xbfb8aa3b, v54
	v_mul_f32_e32 v53, 0xbfb8aa3b, v55
	v_exp_f32_e32 v52, v52
	v_exp_f32_e32 v53, v53
	v_cvt_pk_bf16_f32 v48, v48, v49
	v_pk_add_f32 v[52:53], v[52:53], 1.0 op_sel_hi:[1,0]
	s_nop 0
	v_rcp_f32_e32 v57, v53
	s_nop 0
	v_mul_f32_e32 v53, v55, v57
	v_rcp_f32_e32 v56, v52
	s_nop 0
	v_mul_f32_e32 v52, v54, v56
	v_pk_mul_f32 v[50:51], v[50:51], v[52:53]
	s_nop 0
	v_cvt_pk_bf16_f32 v49, v50, v51
	v_lshl_add_u64 v[50:51], v[58:59], 0, v[112:113]
	global_store_dwordx2 v[50:51], v[48:49], off offset:128
	v_mul_f32_e32 v48, 0xbfb8aa3b, v44
	v_mul_f32_e32 v49, 0xbfb8aa3b, v45
	v_exp_f32_e32 v48, v48
	v_exp_f32_e32 v49, v49
	v_add_u32_e32 v50, 0x90, v143
	v_pk_add_f32 v[48:49], v[48:49], 1.0 op_sel_hi:[1,0]
	s_nop 0
	v_rcp_f32_e32 v52, v49
	s_nop 0
	v_mul_f32_e32 v45, v45, v52
	v_rcp_f32_e32 v51, v48
	s_nop 0
	v_mul_f32_e32 v44, v44, v51
	v_pk_mul_f32 v[40:41], v[40:41], v[44:45]
	v_mul_f32_e32 v44, 0xbfb8aa3b, v46
	v_mul_f32_e32 v45, 0xbfb8aa3b, v47
	v_exp_f32_e32 v44, v44
	v_exp_f32_e32 v45, v45
	v_cvt_pk_bf16_f32 v40, v40, v41
	v_pk_add_f32 v[44:45], v[44:45], 1.0 op_sel_hi:[1,0]
	s_nop 0
	v_rcp_f32_e32 v49, v45
	s_nop 0
	v_mul_f32_e32 v45, v47, v49
	v_rcp_f32_e32 v48, v44
	s_nop 0
	v_mul_f32_e32 v44, v46, v48
	v_pk_mul_f32 v[42:43], v[42:43], v[44:45]
	s_nop 0
	v_cvt_pk_bf16_f32 v41, v42, v43
	v_mad_i64_i32 v[42:43], s[0:1], v50, s49, v[120:121]
	v_lshl_add_u64 v[44:45], v[42:43], 0, v[122:123]
	global_store_dwordx2 v[44:45], v[40:41], off
	v_mul_f32_e32 v40, 0xbfb8aa3b, v36
	v_mul_f32_e32 v41, 0xbfb8aa3b, v37
	v_exp_f32_e32 v40, v40
	v_exp_f32_e32 v41, v41
	s_nop 0
	v_pk_add_f32 v[40:41], v[40:41], 1.0 op_sel_hi:[1,0]
	s_nop 0
	v_rcp_f32_e32 v45, v41
	s_nop 0
	v_mul_f32_e32 v37, v37, v45
	v_rcp_f32_e32 v44, v40
	s_nop 0
	v_mul_f32_e32 v36, v36, v44
	v_pk_mul_f32 v[32:33], v[32:33], v[36:37]
	v_mul_f32_e32 v36, 0xbfb8aa3b, v38
	v_mul_f32_e32 v37, 0xbfb8aa3b, v39
	v_exp_f32_e32 v36, v36
	v_exp_f32_e32 v37, v37
	v_cvt_pk_bf16_f32 v32, v32, v33
	v_pk_add_f32 v[36:37], v[36:37], 1.0 op_sel_hi:[1,0]
	s_nop 0
	v_rcp_f32_e32 v41, v37
	s_nop 0
	v_mul_f32_e32 v37, v39, v41
	v_rcp_f32_e32 v40, v36
	s_nop 0
	v_mul_f32_e32 v36, v38, v40
	v_pk_mul_f32 v[34:35], v[34:35], v[36:37]
	s_nop 0
	v_cvt_pk_bf16_f32 v33, v34, v35
	v_lshl_add_u64 v[34:35], v[42:43], 0, v[112:113]
	global_store_dwordx2 v[34:35], v[32:33], off offset:128
	v_mul_f32_e32 v32, 0xbfb8aa3b, v28
	v_mul_f32_e32 v33, 0xbfb8aa3b, v29
	v_exp_f32_e32 v32, v32
	v_exp_f32_e32 v33, v33
	v_add_u32_e32 v34, 0xa0, v143
	v_pk_add_f32 v[32:33], v[32:33], 1.0 op_sel_hi:[1,0]
	s_nop 0
	v_rcp_f32_e32 v36, v33
	s_nop 0
	v_mul_f32_e32 v29, v29, v36
	v_rcp_f32_e32 v35, v32
	s_nop 0
	v_mul_f32_e32 v28, v28, v35
	v_pk_mul_f32 v[24:25], v[24:25], v[28:29]
	v_mul_f32_e32 v28, 0xbfb8aa3b, v30
	v_mul_f32_e32 v29, 0xbfb8aa3b, v31
	v_exp_f32_e32 v28, v28
	v_exp_f32_e32 v29, v29
	v_cvt_pk_bf16_f32 v24, v24, v25
	v_pk_add_f32 v[28:29], v[28:29], 1.0 op_sel_hi:[1,0]
	s_nop 0
	v_rcp_f32_e32 v33, v29
	s_nop 0
	v_mul_f32_e32 v29, v31, v33
	v_rcp_f32_e32 v32, v28
	s_nop 0
	v_mul_f32_e32 v28, v30, v32
	v_pk_mul_f32 v[26:27], v[26:27], v[28:29]
	s_nop 0
	v_cvt_pk_bf16_f32 v25, v26, v27
	v_mad_i64_i32 v[26:27], s[0:1], v34, s49, v[120:121]
	v_lshl_add_u64 v[28:29], v[26:27], 0, v[122:123]
	global_store_dwordx2 v[28:29], v[24:25], off
	v_mul_f32_e32 v24, 0xbfb8aa3b, v20
	v_mul_f32_e32 v25, 0xbfb8aa3b, v21
	v_exp_f32_e32 v24, v24
	v_exp_f32_e32 v25, v25
	s_nop 0
	v_pk_add_f32 v[24:25], v[24:25], 1.0 op_sel_hi:[1,0]
	s_nop 0
	v_rcp_f32_e32 v29, v25
	s_nop 0
	v_mul_f32_e32 v21, v21, v29
	v_rcp_f32_e32 v28, v24
	s_nop 0
	v_mul_f32_e32 v20, v20, v28
	v_pk_mul_f32 v[16:17], v[16:17], v[20:21]
	v_mul_f32_e32 v20, 0xbfb8aa3b, v22
	v_mul_f32_e32 v21, 0xbfb8aa3b, v23
	v_exp_f32_e32 v20, v20
	v_exp_f32_e32 v21, v21
	v_cvt_pk_bf16_f32 v16, v16, v17
	v_pk_add_f32 v[20:21], v[20:21], 1.0 op_sel_hi:[1,0]
	s_nop 0
	v_rcp_f32_e32 v25, v21
	s_nop 0
	v_mul_f32_e32 v21, v23, v25
	v_rcp_f32_e32 v24, v20
	s_nop 0
	v_mul_f32_e32 v20, v22, v24
	v_pk_mul_f32 v[18:19], v[18:19], v[20:21]
	s_nop 0
	v_cvt_pk_bf16_f32 v17, v18, v19
	v_lshl_add_u64 v[18:19], v[26:27], 0, v[112:113]
	global_store_dwordx2 v[18:19], v[16:17], off offset:128
	v_mul_f32_e32 v16, 0xbfb8aa3b, v12
	v_mul_f32_e32 v17, 0xbfb8aa3b, v13
	v_exp_f32_e32 v16, v16
	v_exp_f32_e32 v17, v17
	v_add_u32_e32 v18, 0xb0, v143
	v_pk_add_f32 v[16:17], v[16:17], 1.0 op_sel_hi:[1,0]
	s_nop 0
	v_rcp_f32_e32 v20, v17
	s_nop 0
	v_mul_f32_e32 v13, v13, v20
	v_rcp_f32_e32 v19, v16
	s_nop 0
	v_mul_f32_e32 v12, v12, v19
	v_pk_mul_f32 v[8:9], v[8:9], v[12:13]
	v_mul_f32_e32 v12, 0xbfb8aa3b, v14
	v_mul_f32_e32 v13, 0xbfb8aa3b, v15
	v_exp_f32_e32 v12, v12
	v_exp_f32_e32 v13, v13
	v_cvt_pk_bf16_f32 v8, v8, v9
	v_pk_add_f32 v[12:13], v[12:13], 1.0 op_sel_hi:[1,0]
	s_nop 0
	v_rcp_f32_e32 v17, v13
	s_nop 0
	v_mul_f32_e32 v13, v15, v17
	v_rcp_f32_e32 v16, v12
	s_nop 0
	v_mul_f32_e32 v12, v14, v16
	v_pk_mul_f32 v[10:11], v[10:11], v[12:13]
	s_nop 0
	v_cvt_pk_bf16_f32 v9, v10, v11
	v_mad_i64_i32 v[10:11], s[0:1], v18, s49, v[120:121]
	v_lshl_add_u64 v[12:13], v[10:11], 0, v[122:123]
	global_store_dwordx2 v[12:13], v[8:9], off
	v_mul_f32_e32 v8, 0xbfb8aa3b, v4
	v_mul_f32_e32 v9, 0xbfb8aa3b, v5
	v_exp_f32_e32 v8, v8
	v_exp_f32_e32 v9, v9
	s_nop 0
	v_pk_add_f32 v[8:9], v[8:9], 1.0 op_sel_hi:[1,0]
	s_nop 0
	v_rcp_f32_e32 v13, v9
	s_nop 0
	v_mul_f32_e32 v5, v5, v13
	v_rcp_f32_e32 v12, v8
	s_nop 0
	v_mul_f32_e32 v4, v4, v12
	v_pk_mul_f32 v[0:1], v[0:1], v[4:5]
	v_mul_f32_e32 v4, 0xbfb8aa3b, v6
	v_mul_f32_e32 v5, 0xbfb8aa3b, v7
	v_exp_f32_e32 v4, v4
	v_exp_f32_e32 v5, v5
	v_cvt_pk_bf16_f32 v0, v0, v1
	v_pk_add_f32 v[4:5], v[4:5], 1.0 op_sel_hi:[1,0]
	s_nop 0
	v_rcp_f32_e32 v9, v5
	s_nop 0
	v_mul_f32_e32 v5, v7, v9
	s_nop 0
	v_rcp_f32_e32 v8, v4
	s_nop 8
	v_mul_f32_e32 v4, v6, v8
	v_pk_mul_f32 v[2:3], v[2:3], v[4:5]
	s_and_b64 vcc, exec, s[42:43]
	v_cvt_pk_bf16_f32 v1, v2, v3
	v_lshl_add_u64 v[2:3], v[10:11], 0, v[112:113]
	global_store_dwordx2 v[2:3], v[0:1], off offset:128
	s_cbranch_vccnz .LBB0_2375

.LBB0_2384:
	v_mov_b32_e32 v138, v128
	v_mov_b32_e32 v139, v140
	s_lshl_b32 s18, s59, 8
	s_add_i32 s18, s18, s22
	v_add_u32_e32 v143, s18, v138
	v_lshlrev_b32_e32 v138, 2, v139
	v_mul_f32_e32 v139, 0xbfb8aa3b, v124
	v_exp_f32_e32 v146, v139
	v_mul_f32_e32 v139, 0xbfb8aa3b, v125
	v_exp_f32_e32 v147, v139
	s_lshl_b32 s18, s58, 8
	s_or_b32 s18, s18, s23
	s_ashr_i32 s18, s18, 1
	v_pk_add_f32 v[146:147], v[146:147], 1.0 op_sel_hi:[1,0]
	v_add_u32_e32 v144, s18, v138
	v_rcp_f32_e32 v145, v147
	s_movk_i32 s47, 0x1600
	s_ashr_i32 s19, s18, 31
	s_mov_b32 s58, s46
	v_mul_f32_e32 v125, v125, v145
	v_rcp_f32_e32 v145, v146
	s_mov_b32 s59, s48
	v_mul_f32_e32 v124, v124, v145
	v_pk_mul_f32 v[120:121], v[120:121], v[124:125]
	v_mul_f32_e32 v124, 0xbfb8aa3b, v126
	v_mul_f32_e32 v125, 0xbfb8aa3b, v127
	v_exp_f32_e32 v124, v124
	v_exp_f32_e32 v125, v125
	s_nop 0
	v_pk_add_f32 v[124:125], v[124:125], 1.0 op_sel_hi:[1,0]
	s_nop 0
	v_rcp_f32_e32 v145, v125
	s_nop 0
	v_mul_f32_e32 v125, v127, v145
	v_rcp_f32_e32 v139, v124
	s_nop 0
	v_mul_f32_e32 v124, v126, v139
	v_pk_mul_f32 v[122:123], v[122:123], v[124:125]
	v_cvt_pk_bf16_f32 v124, v120, v121
	v_mov_b64_e32 v[120:121], s[36:37]
	v_ashrrev_i32_e32 v145, 31, v144
	v_cvt_pk_bf16_f32 v125, v122, v123
	v_mad_i64_i32 v[126:127], s[52:53], v143, s47, v[120:121]
	v_lshlrev_b64 v[122:123], 1, v[144:145]
	v_lshl_add_u64 v[144:145], v[126:127], 0, v[122:123]
	global_store_dwordx2 v[144:145], v[124:125], off
	v_mul_f32_e32 v124, 0xbfb8aa3b, v116
	v_mul_f32_e32 v125, 0xbfb8aa3b, v117
	v_exp_f32_e32 v124, v124
	v_exp_f32_e32 v125, v125
	s_nop 0
	v_pk_add_f32 v[124:125], v[124:125], 1.0 op_sel_hi:[1,0]
	s_nop 0
	v_rcp_f32_e32 v144, v125
	s_nop 0
	v_mul_f32_e32 v117, v117, v144
	v_rcp_f32_e32 v139, v124
	s_nop 0
	v_mul_f32_e32 v116, v116, v139
	v_pk_mul_f32 v[112:113], v[112:113], v[116:117]
	v_mul_f32_e32 v116, 0xbfb8aa3b, v118
	v_mul_f32_e32 v117, 0xbfb8aa3b, v119
	v_exp_f32_e32 v116, v116
	v_exp_f32_e32 v117, v117
	s_nop 0
	v_pk_add_f32 v[116:117], v[116:117], 1.0 op_sel_hi:[1,0]
	s_nop 0
	v_rcp_f32_e32 v125, v117
	s_nop 0
	v_mul_f32_e32 v117, v119, v125
	v_rcp_f32_e32 v124, v116
	s_mov_b64 s[52:53], s[2:3]
	v_mul_f32_e32 v116, v118, v124
	v_ashrrev_i32_e32 v139, 31, v138
	v_pk_mul_f32 v[114:115], v[114:115], v[116:117]
	v_cvt_pk_bf16_f32 v116, v112, v113
	v_lshl_add_u64 v[112:113], s[18:19], 0, v[138:139]
	v_lshlrev_b64 v[112:113], 1, v[112:113]
	v_cvt_pk_bf16_f32 v117, v114, v115
	v_lshl_add_u64 v[114:115], v[126:127], 0, v[112:113]
	global_store_dwordx2 v[114:115], v[116:117], off offset:128
	v_mul_f32_e32 v114, 0xbfb8aa3b, v108
	v_mul_f32_e32 v115, 0xbfb8aa3b, v109
	v_exp_f32_e32 v114, v114
	v_exp_f32_e32 v115, v115
	v_add_u32_e32 v116, 16, v143
	v_pk_add_f32 v[114:115], v[114:115], 1.0 op_sel_hi:[1,0]
	s_nop 0
	v_rcp_f32_e32 v118, v115
	s_nop 0
	v_mul_f32_e32 v109, v109, v118
	v_rcp_f32_e32 v117, v114
	s_nop 0
	v_mul_f32_e32 v108, v108, v117
	v_pk_mul_f32 v[104:105], v[104:105], v[108:109]
	v_mul_f32_e32 v108, 0xbfb8aa3b, v110
	v_mul_f32_e32 v109, 0xbfb8aa3b, v111
	v_exp_f32_e32 v108, v108
	v_exp_f32_e32 v109, v109
	v_cvt_pk_bf16_f32 v104, v104, v105
	v_pk_add_f32 v[108:109], v[108:109], 1.0 op_sel_hi:[1,0]
	s_nop 0
	v_rcp_f32_e32 v115, v109
	s_nop 0
	v_mul_f32_e32 v109, v111, v115
	v_rcp_f32_e32 v114, v108
	s_nop 0
	v_mul_f32_e32 v108, v110, v114
	v_pk_mul_f32 v[106:107], v[106:107], v[108:109]
	s_nop 0
	v_cvt_pk_bf16_f32 v105, v106, v107
	v_mad_i64_i32 v[106:107], s[18:19], v116, s47, v[120:121]
	v_lshl_add_u64 v[108:109], v[106:107], 0, v[122:123]
	global_store_dwordx2 v[108:109], v[104:105], off
	v_mul_f32_e32 v104, 0xbfb8aa3b, v100
	v_mul_f32_e32 v105, 0xbfb8aa3b, v101
	v_exp_f32_e32 v104, v104
	v_exp_f32_e32 v105, v105
	s_nop 0
	v_pk_add_f32 v[104:105], v[104:105], 1.0 op_sel_hi:[1,0]
	s_nop 0
	v_rcp_f32_e32 v109, v105
	s_nop 0
	v_mul_f32_e32 v101, v101, v109
	v_rcp_f32_e32 v108, v104
	s_nop 0
	v_mul_f32_e32 v100, v100, v108
	v_pk_mul_f32 v[96:97], v[96:97], v[100:101]
	v_mul_f32_e32 v100, 0xbfb8aa3b, v102
	v_mul_f32_e32 v101, 0xbfb8aa3b, v103
	v_exp_f32_e32 v100, v100
	v_exp_f32_e32 v101, v101
	v_cvt_pk_bf16_f32 v96, v96, v97
	v_pk_add_f32 v[100:101], v[100:101], 1.0 op_sel_hi:[1,0]
	s_nop 0
	v_rcp_f32_e32 v105, v101
	s_nop 0
	v_mul_f32_e32 v101, v103, v105
	v_rcp_f32_e32 v104, v100
	s_nop 0
	v_mul_f32_e32 v100, v102, v104
	v_pk_mul_f32 v[98:99], v[98:99], v[100:101]
	s_nop 0
	v_cvt_pk_bf16_f32 v97, v98, v99
	v_lshl_add_u64 v[98:99], v[106:107], 0, v[112:113]
	global_store_dwordx2 v[98:99], v[96:97], off offset:128
	v_mul_f32_e32 v96, 0xbfb8aa3b, v92
	v_mul_f32_e32 v97, 0xbfb8aa3b, v93
	v_exp_f32_e32 v96, v96
	v_exp_f32_e32 v97, v97
	v_add_u32_e32 v98, 32, v143
	v_pk_add_f32 v[96:97], v[96:97], 1.0 op_sel_hi:[1,0]
	s_nop 0
	v_rcp_f32_e32 v100, v97
	s_nop 0
	v_mul_f32_e32 v93, v93, v100
	v_rcp_f32_e32 v99, v96
	s_nop 0
	v_mul_f32_e32 v92, v92, v99
	v_pk_mul_f32 v[88:89], v[88:89], v[92:93]
	v_mul_f32_e32 v92, 0xbfb8aa3b, v94
	v_mul_f32_e32 v93, 0xbfb8aa3b, v95
	v_exp_f32_e32 v92, v92
	v_exp_f32_e32 v93, v93
	v_cvt_pk_bf16_f32 v88, v88, v89
	v_pk_add_f32 v[92:93], v[92:93], 1.0 op_sel_hi:[1,0]
	s_nop 0
	v_rcp_f32_e32 v97, v93
	s_nop 0
	v_mul_f32_e32 v93, v95, v97
	v_rcp_f32_e32 v96, v92
	s_nop 0
	v_mul_f32_e32 v92, v94, v96
	v_pk_mul_f32 v[90:91], v[90:91], v[92:93]
	s_nop 0
	v_cvt_pk_bf16_f32 v89, v90, v91
	v_mad_i64_i32 v[90:91], s[18:19], v98, s47, v[120:121]
	v_lshl_add_u64 v[92:93], v[90:91], 0, v[122:123]
	global_store_dwordx2 v[92:93], v[88:89], off
	v_mul_f32_e32 v88, 0xbfb8aa3b, v84
	v_mul_f32_e32 v89, 0xbfb8aa3b, v85
	v_exp_f32_e32 v88, v88
	v_exp_f32_e32 v89, v89
	s_nop 0
	v_pk_add_f32 v[88:89], v[88:89], 1.0 op_sel_hi:[1,0]
	s_nop 0
	v_rcp_f32_e32 v93, v89
	s_nop 0
	v_mul_f32_e32 v85, v85, v93
	v_rcp_f32_e32 v92, v88
	s_nop 0
	v_mul_f32_e32 v84, v84, v92
	v_pk_mul_f32 v[80:81], v[80:81], v[84:85]
	v_mul_f32_e32 v84, 0xbfb8aa3b, v86
	v_mul_f32_e32 v85, 0xbfb8aa3b, v87
	v_exp_f32_e32 v84, v84
	v_exp_f32_e32 v85, v85
	v_cvt_pk_bf16_f32 v80, v80, v81
	v_pk_add_f32 v[84:85], v[84:85], 1.0 op_sel_hi:[1,0]
	s_nop 0
	v_rcp_f32_e32 v89, v85
	s_nop 0
	v_mul_f32_e32 v85, v87, v89
	v_rcp_f32_e32 v88, v84
	s_nop 0
	v_mul_f32_e32 v84, v86, v88
	v_pk_mul_f32 v[82:83], v[82:83], v[84:85]
	s_nop 0
	v_cvt_pk_bf16_f32 v81, v82, v83
	v_lshl_add_u64 v[82:83], v[90:91], 0, v[112:113]
	global_store_dwordx2 v[82:83], v[80:81], off offset:128
	v_mul_f32_e32 v80, 0xbfb8aa3b, v76
	v_mul_f32_e32 v81, 0xbfb8aa3b, v77
	v_exp_f32_e32 v80, v80
	v_exp_f32_e32 v81, v81
	v_add_u32_e32 v82, 48, v143
	v_pk_add_f32 v[80:81], v[80:81], 1.0 op_sel_hi:[1,0]
	s_nop 0
	v_rcp_f32_e32 v84, v81
	s_nop 0
	v_mul_f32_e32 v77, v77, v84
	v_rcp_f32_e32 v83, v80
	s_nop 0
	v_mul_f32_e32 v76, v76, v83
	v_pk_mul_f32 v[72:73], v[72:73], v[76:77]
	v_mul_f32_e32 v76, 0xbfb8aa3b, v78
	v_mul_f32_e32 v77, 0xbfb8aa3b, v79
	v_exp_f32_e32 v76, v76
	v_exp_f32_e32 v77, v77
	v_cvt_pk_bf16_f32 v72, v72, v73
	v_pk_add_f32 v[76:77], v[76:77], 1.0 op_sel_hi:[1,0]
	s_nop 0
	v_rcp_f32_e32 v81, v77
	s_nop 0
	v_mul_f32_e32 v77, v79, v81
	v_rcp_f32_e32 v80, v76
	s_nop 0
	v_mul_f32_e32 v76, v78, v80
	v_pk_mul_f32 v[74:75], v[74:75], v[76:77]
	s_nop 0
	v_cvt_pk_bf16_f32 v73, v74, v75
	v_mad_i64_i32 v[74:75], s[18:19], v82, s47, v[120:121]
	v_lshl_add_u64 v[76:77], v[74:75], 0, v[122:123]
	global_store_dwordx2 v[76:77], v[72:73], off
	v_mul_f32_e32 v72, 0xbfb8aa3b, v68
	v_mul_f32_e32 v73, 0xbfb8aa3b, v69
	v_exp_f32_e32 v72, v72
	v_exp_f32_e32 v73, v73
	s_nop 0
	v_pk_add_f32 v[72:73], v[72:73], 1.0 op_sel_hi:[1,0]
	s_nop 0
	v_rcp_f32_e32 v77, v73
	s_nop 0
	v_mul_f32_e32 v69, v69, v77
	v_rcp_f32_e32 v76, v72
	s_nop 0
	v_mul_f32_e32 v68, v68, v76
	v_pk_mul_f32 v[64:65], v[64:65], v[68:69]
	v_mul_f32_e32 v68, 0xbfb8aa3b, v70
	v_mul_f32_e32 v69, 0xbfb8aa3b, v71
	v_exp_f32_e32 v68, v68
	v_exp_f32_e32 v69, v69
	v_cvt_pk_bf16_f32 v64, v64, v65
	v_pk_add_f32 v[68:69], v[68:69], 1.0 op_sel_hi:[1,0]
	s_nop 0
	v_rcp_f32_e32 v73, v69
	s_nop 0
	v_mul_f32_e32 v69, v71, v73
	v_rcp_f32_e32 v72, v68
	s_nop 0
	v_mul_f32_e32 v68, v70, v72
	v_pk_mul_f32 v[66:67], v[66:67], v[68:69]
	s_nop 0
	v_cvt_pk_bf16_f32 v65, v66, v67
	v_lshl_add_u64 v[66:67], v[74:75], 0, v[112:113]
	global_store_dwordx2 v[66:67], v[64:65], off offset:128
	v_mul_f32_e32 v64, 0xbfb8aa3b, v60
	v_mul_f32_e32 v65, 0xbfb8aa3b, v61
	v_exp_f32_e32 v64, v64
	v_exp_f32_e32 v65, v65
	v_add_u32_e32 v66, 0x80, v143
	v_pk_add_f32 v[64:65], v[64:65], 1.0 op_sel_hi:[1,0]
	s_nop 0
	v_rcp_f32_e32 v68, v65
	s_nop 0
	v_mul_f32_e32 v61, v61, v68
	v_rcp_f32_e32 v67, v64
	s_nop 0
	v_mul_f32_e32 v60, v60, v67
	v_pk_mul_f32 v[56:57], v[56:57], v[60:61]
	v_mul_f32_e32 v60, 0xbfb8aa3b, v62
	v_mul_f32_e32 v61, 0xbfb8aa3b, v63
	v_exp_f32_e32 v60, v60
	v_exp_f32_e32 v61, v61
	v_cvt_pk_bf16_f32 v56, v56, v57
	v_pk_add_f32 v[60:61], v[60:61], 1.0 op_sel_hi:[1,0]
	s_nop 0
	v_rcp_f32_e32 v65, v61
	s_nop 0
	v_mul_f32_e32 v61, v63, v65
	v_rcp_f32_e32 v64, v60
	s_nop 0
	v_mul_f32_e32 v60, v62, v64
	v_pk_mul_f32 v[58:59], v[58:59], v[60:61]
	s_nop 0
	v_cvt_pk_bf16_f32 v57, v58, v59
	v_mad_i64_i32 v[58:59], s[18:19], v66, s47, v[120:121]
	v_lshl_add_u64 v[60:61], v[58:59], 0, v[122:123]
	global_store_dwordx2 v[60:61], v[56:57], off
	v_mul_f32_e32 v56, 0xbfb8aa3b, v52
	v_mul_f32_e32 v57, 0xbfb8aa3b, v53
	v_exp_f32_e32 v56, v56
	v_exp_f32_e32 v57, v57
	s_nop 0
	v_pk_add_f32 v[56:57], v[56:57], 1.0 op_sel_hi:[1,0]
	s_nop 0
	v_rcp_f32_e32 v61, v57
	s_nop 0
	v_mul_f32_e32 v53, v53, v61
	v_rcp_f32_e32 v60, v56
	s_nop 0
	v_mul_f32_e32 v52, v52, v60
	v_pk_mul_f32 v[48:49], v[48:49], v[52:53]
	v_mul_f32_e32 v52, 0xbfb8aa3b, v54
	v_mul_f32_e32 v53, 0xbfb8aa3b, v55
	v_exp_f32_e32 v52, v52
	v_exp_f32_e32 v53, v53
	v_cvt_pk_bf16_f32 v48, v48, v49
	v_pk_add_f32 v[52:53], v[52:53], 1.0 op_sel_hi:[1,0]
	s_nop 0
	v_rcp_f32_e32 v57, v53
	s_nop 0
	v_mul_f32_e32 v53, v55, v57
	v_rcp_f32_e32 v56, v52
	s_nop 0
	v_mul_f32_e32 v52, v54, v56
	v_pk_mul_f32 v[50:51], v[50:51], v[52:53]
	s_nop 0
	v_cvt_pk_bf16_f32 v49, v50, v51
	v_lshl_add_u64 v[50:51], v[58:59], 0, v[112:113]
	global_store_dwordx2 v[50:51], v[48:49], off offset:128
	v_mul_f32_e32 v48, 0xbfb8aa3b, v44
	v_mul_f32_e32 v49, 0xbfb8aa3b, v45
	v_exp_f32_e32 v48, v48
	v_exp_f32_e32 v49, v49
	v_add_u32_e32 v50, 0x90, v143
	v_pk_add_f32 v[48:49], v[48:49], 1.0 op_sel_hi:[1,0]
	s_nop 0
	v_rcp_f32_e32 v52, v49
	s_nop 0
	v_mul_f32_e32 v45, v45, v52
	v_rcp_f32_e32 v51, v48
	s_nop 0
	v_mul_f32_e32 v44, v44, v51
	v_pk_mul_f32 v[40:41], v[40:41], v[44:45]
	v_mul_f32_e32 v44, 0xbfb8aa3b, v46
	v_mul_f32_e32 v45, 0xbfb8aa3b, v47
	v_exp_f32_e32 v44, v44
	v_exp_f32_e32 v45, v45
	v_cvt_pk_bf16_f32 v40, v40, v41
	v_pk_add_f32 v[44:45], v[44:45], 1.0 op_sel_hi:[1,0]
	s_nop 0
	v_rcp_f32_e32 v49, v45
	s_nop 0
	v_mul_f32_e32 v45, v47, v49
	v_rcp_f32_e32 v48, v44
	s_nop 0
	v_mul_f32_e32 v44, v46, v48
	v_pk_mul_f32 v[42:43], v[42:43], v[44:45]
	s_nop 0
	v_cvt_pk_bf16_f32 v41, v42, v43
	v_mad_i64_i32 v[42:43], s[18:19], v50, s47, v[120:121]
	v_lshl_add_u64 v[44:45], v[42:43], 0, v[122:123]
	global_store_dwordx2 v[44:45], v[40:41], off
	v_mul_f32_e32 v40, 0xbfb8aa3b, v36
	v_mul_f32_e32 v41, 0xbfb8aa3b, v37
	v_exp_f32_e32 v40, v40
	v_exp_f32_e32 v41, v41
	s_nop 0
	v_pk_add_f32 v[40:41], v[40:41], 1.0 op_sel_hi:[1,0]
	s_nop 0
	v_rcp_f32_e32 v45, v41
	s_nop 0
	v_mul_f32_e32 v37, v37, v45
	v_rcp_f32_e32 v44, v40
	s_nop 0
	v_mul_f32_e32 v36, v36, v44
	v_pk_mul_f32 v[32:33], v[32:33], v[36:37]
	v_mul_f32_e32 v36, 0xbfb8aa3b, v38
	v_mul_f32_e32 v37, 0xbfb8aa3b, v39
	v_exp_f32_e32 v36, v36
	v_exp_f32_e32 v37, v37
	v_cvt_pk_bf16_f32 v32, v32, v33
	v_pk_add_f32 v[36:37], v[36:37], 1.0 op_sel_hi:[1,0]
	s_nop 0
	v_rcp_f32_e32 v41, v37
	s_nop 0
	v_mul_f32_e32 v37, v39, v41
	v_rcp_f32_e32 v40, v36
	s_nop 0
	v_mul_f32_e32 v36, v38, v40
	v_pk_mul_f32 v[34:35], v[34:35], v[36:37]
	s_nop 0
	v_cvt_pk_bf16_f32 v33, v34, v35
	v_lshl_add_u64 v[34:35], v[42:43], 0, v[112:113]
	global_store_dwordx2 v[34:35], v[32:33], off offset:128
	v_mul_f32_e32 v32, 0xbfb8aa3b, v28
	v_mul_f32_e32 v33, 0xbfb8aa3b, v29
	v_exp_f32_e32 v32, v32
	v_exp_f32_e32 v33, v33
	v_add_u32_e32 v34, 0xa0, v143
	v_pk_add_f32 v[32:33], v[32:33], 1.0 op_sel_hi:[1,0]
	s_nop 0
	v_rcp_f32_e32 v36, v33
	s_nop 0
	v_mul_f32_e32 v29, v29, v36
	v_rcp_f32_e32 v35, v32
	s_nop 0
	v_mul_f32_e32 v28, v28, v35
	v_pk_mul_f32 v[24:25], v[24:25], v[28:29]
	v_mul_f32_e32 v28, 0xbfb8aa3b, v30
	v_mul_f32_e32 v29, 0xbfb8aa3b, v31
	v_exp_f32_e32 v28, v28
	v_exp_f32_e32 v29, v29
	v_cvt_pk_bf16_f32 v24, v24, v25
	v_pk_add_f32 v[28:29], v[28:29], 1.0 op_sel_hi:[1,0]
	s_nop 0
	v_rcp_f32_e32 v33, v29
	s_nop 0
	v_mul_f32_e32 v29, v31, v33
	v_rcp_f32_e32 v32, v28
	s_nop 0
	v_mul_f32_e32 v28, v30, v32
	v_pk_mul_f32 v[26:27], v[26:27], v[28:29]
	s_nop 0
	v_cvt_pk_bf16_f32 v25, v26, v27
	v_mad_i64_i32 v[26:27], s[18:19], v34, s47, v[120:121]
	v_lshl_add_u64 v[28:29], v[26:27], 0, v[122:123]
	global_store_dwordx2 v[28:29], v[24:25], off
	v_mul_f32_e32 v24, 0xbfb8aa3b, v20
	v_mul_f32_e32 v25, 0xbfb8aa3b, v21
	v_exp_f32_e32 v24, v24
	v_exp_f32_e32 v25, v25
	s_nop 0
	v_pk_add_f32 v[24:25], v[24:25], 1.0 op_sel_hi:[1,0]
	s_nop 0
	v_rcp_f32_e32 v29, v25
	s_nop 0
	v_mul_f32_e32 v21, v21, v29
	v_rcp_f32_e32 v28, v24
	s_nop 0
	v_mul_f32_e32 v20, v20, v28
	v_pk_mul_f32 v[16:17], v[16:17], v[20:21]
	v_mul_f32_e32 v20, 0xbfb8aa3b, v22
	v_mul_f32_e32 v21, 0xbfb8aa3b, v23
	v_exp_f32_e32 v20, v20
	v_exp_f32_e32 v21, v21
	v_cvt_pk_bf16_f32 v16, v16, v17
	v_pk_add_f32 v[20:21], v[20:21], 1.0 op_sel_hi:[1,0]
	s_nop 0
	v_rcp_f32_e32 v25, v21
	s_nop 0
	v_mul_f32_e32 v21, v23, v25
	v_rcp_f32_e32 v24, v20
	s_nop 0
	v_mul_f32_e32 v20, v22, v24
	v_pk_mul_f32 v[18:19], v[18:19], v[20:21]
	s_nop 0
	v_cvt_pk_bf16_f32 v17, v18, v19
	v_lshl_add_u64 v[18:19], v[26:27], 0, v[112:113]
	global_store_dwordx2 v[18:19], v[16:17], off offset:128
	v_mul_f32_e32 v16, 0xbfb8aa3b, v12
	v_mul_f32_e32 v17, 0xbfb8aa3b, v13
	v_exp_f32_e32 v16, v16
	v_exp_f32_e32 v17, v17
	v_add_u32_e32 v18, 0xb0, v143
	v_pk_add_f32 v[16:17], v[16:17], 1.0 op_sel_hi:[1,0]
	s_nop 0
	v_rcp_f32_e32 v20, v17
	s_nop 0
	v_mul_f32_e32 v13, v13, v20
	v_rcp_f32_e32 v19, v16
	s_nop 0
	v_mul_f32_e32 v12, v12, v19
	v_pk_mul_f32 v[8:9], v[8:9], v[12:13]
	v_mul_f32_e32 v12, 0xbfb8aa3b, v14
	v_mul_f32_e32 v13, 0xbfb8aa3b, v15
	v_exp_f32_e32 v12, v12
	v_exp_f32_e32 v13, v13
	v_cvt_pk_bf16_f32 v8, v8, v9
	v_pk_add_f32 v[12:13], v[12:13], 1.0 op_sel_hi:[1,0]
	s_nop 0
	v_rcp_f32_e32 v17, v13
	s_nop 0
	v_mul_f32_e32 v13, v15, v17
	v_rcp_f32_e32 v16, v12
	s_nop 0
	v_mul_f32_e32 v12, v14, v16
	v_pk_mul_f32 v[10:11], v[10:11], v[12:13]
	s_nop 0
	v_cvt_pk_bf16_f32 v9, v10, v11
	v_mad_i64_i32 v[10:11], s[18:19], v18, s47, v[120:121]
	v_lshl_add_u64 v[12:13], v[10:11], 0, v[122:123]
	global_store_dwordx2 v[12:13], v[8:9], off
	v_mul_f32_e32 v8, 0xbfb8aa3b, v4
	v_mul_f32_e32 v9, 0xbfb8aa3b, v5
	v_exp_f32_e32 v8, v8
	v_exp_f32_e32 v9, v9
	s_nop 0
	v_pk_add_f32 v[8:9], v[8:9], 1.0 op_sel_hi:[1,0]
	s_nop 0
	v_rcp_f32_e32 v13, v9
	s_nop 0
	v_mul_f32_e32 v5, v5, v13
	v_rcp_f32_e32 v12, v8
	s_nop 0
	v_mul_f32_e32 v4, v4, v12
	v_pk_mul_f32 v[0:1], v[0:1], v[4:5]
	v_mul_f32_e32 v4, 0xbfb8aa3b, v6
	v_mul_f32_e32 v5, 0xbfb8aa3b, v7
	v_exp_f32_e32 v4, v4
	v_exp_f32_e32 v5, v5
	v_cvt_pk_bf16_f32 v0, v0, v1
	v_pk_add_f32 v[4:5], v[4:5], 1.0 op_sel_hi:[1,0]
	s_nop 0
	v_rcp_f32_e32 v9, v5
	s_nop 0
	v_mul_f32_e32 v5, v7, v9
	s_nop 0
	v_rcp_f32_e32 v8, v4
	s_mov_b64 s[18:19], s[50:51]
	s_nop 7
	v_mul_f32_e32 v4, v6, v8
	v_pk_mul_f32 v[2:3], v[2:3], v[4:5]
	s_and_b64 vcc, exec, s[42:43]
	v_cvt_pk_bf16_f32 v1, v2, v3
	v_lshl_add_u64 v[2:3], v[10:11], 0, v[112:113]
	global_store_dwordx2 v[2:3], v[0:1], off offset:128
	s_cbranch_vccnz .LBB0_2391
